# speedup vs baseline: 1.0126x; 1.0078x over previous
; __device__ __forceinline__ int tidx() { int t = threadIdx.x; asm volatile("" : "+v"(t)); return t; }
; __device__ __forceinline__ void gemm_mainloop256(const bh* __restrict__ A, long lda, const bh* __restrict__ B, long ldb, int K,
;                                                  char* lds, f32x4 (&acc)[8][4]) {
;   constexpr int T_BYTES = 256 * 128, STAGE = 2 * T_BYTES;
;   const int tid = tidx(), lane = tid & 63, wid = tid >> 6, wr = wid >> 2, wc = wid & 3, fr = lane & 15, fq = lane >> 4;
;   const int srow = tid >> 3, sch = tid & 7;
;   const bh* Ap = A + (long)srow * lda + sch * 8;
;   const bh* Bp = B + (long)srow * ldb + sch * 8;
;   const int swo = srow * 128 + ((sch ^ (srow & 7)) << 4);
;   bf16x8 ra[4], rb[4];
;   const int nk = K >> 6;
; #pragma unroll
;   for (int i = 0; i < 4; ++i) { ra[i] = *reinterpret_cast<const bf16x8*>(Ap + (long)(64 * i) * lda); rb[i] = *reinterpret_cast<const bf16x8*>(Bp + (long)(64 * i) * ldb); }
; #pragma unroll
;   for (int i = 0; i < 4; ++i) { *reinterpret_cast<bf16x8*>(lds + swo + i * 8192) = ra[i]; *reinterpret_cast<bf16x8*>(lds + T_BYTES + swo + i * 8192) = rb[i]; }
;   __syncthreads();
; template <int OMODE>
; __device__ __forceinline__ void gemm_phase256(const bh* __restrict__ A, long lda, const bh* __restrict__ Bt, long ldb, int M, int ncols, int K,
;                                               void* Cp, long ldc, char* lds) {
;   const int tm_n = M >> 8, tn_n = ncols >> 8;
;   const int tid = tidx(), lane = tid & 63, wid = tid >> 6, wr = wid >> 2, wc = wid & 3, fr = lane & 15, fq = lane >> 4;
;   for (int tile = blockIdx.x; tile < tm_n * tn_n; tile += gridDim.x) {
;     const int tn = tile / tm_n, tm = tile - tn * tm_n;
;     f32x4 acc[8][4];
; #pragma unroll
;     for (int m = 0; m < 8; ++m)
; #pragma unroll
;       for (int n = 0; n < 4; ++n) acc[m][n] = f32x4{0.f, 0.f, 0.f, 0.f};
;     gemm_mainloop256(A + (long)tm * 256 * lda, lda, Bt + (long)tn * 256 * ldb, ldb, K, lds, acc);
.LBB0_196:
	s_ashr_i32 s1, s0, 31
	s_lshl_b64 s[8:9], s[0:1], 19
	s_lshr_b32 s1, s1, 26
	s_add_i32 s1, s0, s1
	s_and_b32 s6, s1, 0xffffffc0
	s_sub_i32 s4, s0, s6
	s_ashr_i32 s5, s4, 31
	s_ashr_i32 s2, s1, 6
	s_lshl_b64 s[10:11], s[4:5], 19
	s_add_u32 s10, s38, s10
	v_mov_b32_e32 v10, v188
	s_addc_u32 s11, s39, s11
	s_ashr_i32 s3, s2, 31
	s_lshl_b64 s[12:13], s[2:3], 19
	v_ashrrev_i32_e32 v0, 3, v10
	v_readlane_b32 s14, v253, 55
	v_ashrrev_i32_e32 v1, 31, v0
	v_readlane_b32 s15, v253, 56
	s_add_u32 s12, s14, s12
	v_lshlrev_b64 v[2:3], 11, v[0:1]
	v_lshlrev_b32_e32 v1, 4, v10
	s_addc_u32 s13, s15, s13
	v_lshl_add_u64 v[4:5], s[10:11], 0, v[2:3]
	v_and_b32_e32 v176, 0x70, v1
	v_lshl_add_u64 v[4:5], v[4:5], 0, v[176:177]
	v_lshl_add_u64 v[6:7], s[12:13], 0, v[2:3]
	s_mov_b32 s1, 0x20000
	v_lshl_add_u64 v[160:161], v[6:7], 0, v[176:177]
	v_add_co_u32_e32 v6, vcc, s1, v4
	global_load_dwordx4 v[64:67], v[4:5], off
	global_load_dwordx4 v[68:71], v[160:161], off
	v_addc_co_u32_e32 v7, vcc, 0, v5, vcc
	v_add_co_u32_e32 v8, vcc, s1, v160
	s_mov_b32 s1, 0x40000
	s_nop 0
	v_addc_co_u32_e32 v9, vcc, 0, v161, vcc
	global_load_dwordx4 v[76:79], v[6:7], off
	global_load_dwordx4 v[80:83], v[8:9], off
	v_add_co_u32_e32 v6, vcc, s1, v4
	v_lshrrev_b32_e32 v1, 4, v10
	s_nop 0
	v_addc_co_u32_e32 v7, vcc, 0, v5, vcc
	v_add_co_u32_e32 v8, vcc, s1, v160
	s_mov_b32 s1, 0x60000
	s_nop 0
	v_addc_co_u32_e32 v9, vcc, 0, v161, vcc
	v_add_co_u32_e32 v4, vcc, s1, v4
	global_load_dwordx4 v[92:95], v[6:7], off
	global_load_dwordx4 v[96:99], v[8:9], off
	v_addc_co_u32_e32 v5, vcc, 0, v5, vcc
	global_load_dwordx4 v[104:107], v[4:5], off
	v_add_co_u32_e32 v4, vcc, s1, v160
	v_lshrrev_b32_e32 v6, 1, v10
	s_nop 0
	v_addc_co_u32_e32 v5, vcc, 0, v161, vcc
	global_load_dwordx4 v[108:111], v[4:5], off
	v_and_b32_e32 v4, 15, v10
	v_and_b32_e32 v8, 7, v10
	v_xor_b32_e32 v9, v0, v10
	s_mov_b32 s1, 0x1ffff80
	v_lshlrev_b32_e32 v0, 7, v0
	v_and_or_b32 v4, v6, s1, v4
	v_bitop3_b32 v1, v1, v8, 3 bitop3:0x6c
	v_lshlrev_b32_e32 v6, 4, v9
	s_movk_i32 s1, 0x70
	v_lshlrev_b32_e32 v167, 7, v4
	v_lshlrev_b32_e32 v168, 4, v1
	v_and_or_b32 v4, v6, s1, v0
	v_lshl_add_u64 v[0:1], s[8:9], 0, v[2:3]
	s_ashr_i32 s7, s6, 31
	v_lshl_or_b32 v0, v8, 4, v0
	s_lshl_b64 s[6:7], s[6:7], 19
	v_mov_b32_e32 v2, s7
	v_subrev_co_u32_e32 v0, vcc, s6, v0
	v_bfe_u32 v5, v10, 4, 2
	s_nop 0
	v_subb_co_u32_e32 v1, vcc, v1, v2, vcc
	v_lshlrev_b32_e32 v7, 7, v10
	v_bitop3_b32 v5, v5, v8, 4 bitop3:0x36
	v_lshl_add_u64 v[162:163], s[28:29], 0, v[0:1]
	v_mov_b32_e32 v0, 0
	s_mov_b32 s3, 0
	v_and_b32_e32 v166, 0x6780, v7
	v_lshlrev_b32_e32 v169, 4, v5
	v_add_u32_e32 v170, 32, v4
	s_mov_b64 s[6:7], 0
	s_mov_b32 s1, 0
	v_mov_b32_e32 v1, v0
	v_mov_b32_e32 v2, v0
	v_mov_b32_e32 v3, v0
	v_mov_b32_e32 v4, v0
	v_mov_b32_e32 v5, v0
	v_mov_b32_e32 v6, v0
	v_mov_b32_e32 v7, v0
	v_mov_b32_e32 v8, v0
	v_mov_b32_e32 v9, v0
	v_mov_b32_e32 v10, v0
	v_mov_b32_e32 v11, v0
	v_mov_b32_e32 v12, v0
	v_mov_b32_e32 v13, v0
	v_mov_b32_e32 v14, v0
	v_mov_b32_e32 v15, v0
	s_waitcnt vmcnt(18)
	v_mov_b32_e32 v16, v0
	v_mov_b32_e32 v17, v0
	v_mov_b32_e32 v18, v0
	v_mov_b32_e32 v19, v0
	v_mov_b32_e32 v20, v0
	v_mov_b32_e32 v21, v0
	v_mov_b32_e32 v22, v0
	v_mov_b32_e32 v23, v0
	s_waitcnt vmcnt(17)
	v_mov_b32_e32 v24, v0
	v_mov_b32_e32 v25, v0
	v_mov_b32_e32 v26, v0
	v_mov_b32_e32 v27, v0
	v_mov_b32_e32 v28, v0
	v_mov_b32_e32 v29, v0
	v_mov_b32_e32 v30, v0
	v_mov_b32_e32 v31, v0
	s_waitcnt vmcnt(16)
; __device__ __forceinline__ void gemm_mainloop256(const bh* __restrict__ A, long lda, const bh* __restrict__ B, long ldb, int K,
;                                                  char* lds, f32x4 (&acc)[8][4]) {
;     ...
; #pragma unroll
;   for (int i = 0; i < 4; ++i) { ra[i] = *reinterpret_cast<const bf16x8*>(Ap + (long)(64 * i) * lda); rb[i] = *reinterpret_cast<const bf16x8*>(Bp + (long)(64 * i) * ldb); }
; #pragma unroll
;   for (int i = 0; i < 4; ++i) { *reinterpret_cast<bf16x8*>(lds + swo + i * 8192) = ra[i]; *reinterpret_cast<bf16x8*>(lds + T_BYTES + swo + i * 8192) = rb[i]; }
;   __syncthreads();
;   const int a_row = (wr * 128 + fr) * 128, b_row = (wc * 64 + fr) * 128;
;   const int c0 = ((0 + fq) ^ (fr & 7)) << 4, c1 = ((4 + fq) ^ (fr & 7)) << 4;
; #pragma unroll 1
;   for (int kt = 0; kt < nk; ++kt) {
;     const bool more = kt + 1 < nk;
;     if (more) {
; #pragma unroll
;       for (int i = 0; i < 4; ++i) { ra[i] = *reinterpret_cast<const bf16x8*>(Ap + (long)(64 * i) * lda + (kt + 1) * 64); rb[i] = *reinterpret_cast<const bf16x8*>(Bp + (long)(64 * i) * ldb + (kt + 1) * 64); }
;     }
	v_mov_b32_e32 v32, v0
	v_mov_b32_e32 v33, v0
	v_mov_b32_e32 v34, v0
	v_mov_b32_e32 v35, v0
	v_mov_b32_e32 v36, v0
	v_mov_b32_e32 v37, v0
	v_mov_b32_e32 v38, v0
	v_mov_b32_e32 v39, v0
	v_mov_b32_e32 v40, v0
	v_mov_b32_e32 v41, v0
	v_mov_b32_e32 v42, v0
	v_mov_b32_e32 v43, v0
	v_mov_b32_e32 v44, v0
	v_mov_b32_e32 v45, v0
	v_mov_b32_e32 v46, v0
	v_mov_b32_e32 v47, v0
	v_mov_b32_e32 v48, v0
	v_mov_b32_e32 v49, v0
	v_mov_b32_e32 v50, v0
	v_mov_b32_e32 v51, v0
	v_mov_b32_e32 v52, v0
	v_mov_b32_e32 v53, v0
	v_mov_b32_e32 v54, v0
	v_mov_b32_e32 v55, v0
	v_mov_b32_e32 v56, v0
	v_mov_b32_e32 v57, v0
	v_mov_b32_e32 v58, v0
	v_mov_b32_e32 v59, v0
	v_mov_b32_e32 v60, v0
	v_mov_b32_e32 v61, v0
	v_mov_b32_e32 v62, v0
	v_mov_b32_e32 v63, v0
	v_mov_b32_e32 v72, v0
	v_mov_b32_e32 v73, v0
	v_mov_b32_e32 v74, v0
	v_mov_b32_e32 v75, v0
	v_mov_b32_e32 v84, v0
	v_mov_b32_e32 v85, v0
	v_mov_b32_e32 v86, v0
	v_mov_b32_e32 v87, v0
	v_mov_b32_e32 v88, v0
	v_mov_b32_e32 v89, v0
	v_mov_b32_e32 v90, v0
	v_mov_b32_e32 v91, v0
	v_mov_b32_e32 v100, v0
	v_mov_b32_e32 v101, v0
	v_mov_b32_e32 v102, v0
	v_mov_b32_e32 v103, v0
	v_mov_b32_e32 v112, v0
	v_mov_b32_e32 v113, v0
	v_mov_b32_e32 v114, v0
	v_mov_b32_e32 v115, v0
	v_mov_b32_e32 v116, v0
	v_mov_b32_e32 v117, v0
	v_mov_b32_e32 v118, v0
	v_mov_b32_e32 v119, v0
	v_mov_b32_e32 v120, v0
	v_mov_b32_e32 v121, v0
	v_mov_b32_e32 v122, v0
	v_mov_b32_e32 v123, v0
	v_mov_b32_e32 v124, v0
	v_mov_b32_e32 v125, v0
	v_mov_b32_e32 v126, v0
	v_mov_b32_e32 v127, v0
	v_mov_b32_e32 v128, v0
	v_mov_b32_e32 v129, v0
	v_mov_b32_e32 v130, v0
	v_mov_b32_e32 v131, v0
	v_mov_b32_e32 v132, v0
	v_mov_b32_e32 v133, v0
	v_mov_b32_e32 v134, v0
	v_mov_b32_e32 v135, v0
	v_mov_b32_e32 v136, v0
	v_mov_b32_e32 v137, v0
	v_mov_b32_e32 v138, v0
	v_mov_b32_e32 v139, v0
	v_mov_b32_e32 v140, v0
	v_mov_b32_e32 v141, v0
	v_mov_b32_e32 v142, v0
	v_mov_b32_e32 v143, v0
	v_mov_b32_e32 v144, v0
	v_mov_b32_e32 v145, v0
	v_mov_b32_e32 v146, v0
	v_mov_b32_e32 v147, v0
	v_mov_b32_e32 v148, v0
	v_mov_b32_e32 v149, v0
	v_mov_b32_e32 v150, v0
	v_mov_b32_e32 v151, v0
	v_mov_b32_e32 v152, v0
	v_mov_b32_e32 v153, v0
	v_mov_b32_e32 v154, v0
	v_mov_b32_e32 v155, v0
	v_mov_b32_e32 v156, v0
	v_mov_b32_e32 v157, v0
	v_mov_b32_e32 v158, v0
	v_mov_b32_e32 v159, v0
	s_waitcnt vmcnt(7)
	ds_write_b128 v170, v[64:67]
	s_waitcnt vmcnt(5)
	ds_write_b128 v170, v[76:79] offset:8192
	s_waitcnt vmcnt(3)
	ds_write_b128 v170, v[92:95] offset:16384
	s_waitcnt vmcnt(1)
	ds_write_b128 v170, v[104:107] offset:24576
	ds_write_b128 v170, v[68:71] offset:32768
	ds_write_b128 v170, v[80:83] offset:40960
	ds_write_b128 v170, v[96:99] offset:49152
	s_waitcnt vmcnt(0)
	ds_write_b128 v170, v[108:111] offset:57344
	s_waitcnt lgkmcnt(0)
	s_waitcnt vmcnt(1)
	v_lshl_add_u64 v[104:105], v[162:163], 0, s[6:7]
	v_add_co_u32_e32 v64, vcc, 0x5770000, v104
	v_lshl_add_u64 v[106:107], v[160:161], 0, s[6:7]
	s_nop 0
	v_addc_co_u32_e32 v65, vcc, 0, v105, vcc
	v_add_co_u32_e32 v76, vcc, 0x5790000, v104
	global_load_dwordx4 v[64:67], v[64:65], off offset:128
	s_nop 0
	global_load_dwordx4 v[68:71], v[106:107], off offset:128
	v_addc_co_u32_e32 v77, vcc, 0, v105, vcc
	v_add_co_u32_e32 v80, vcc, 0x20000, v106
	s_nop 1
	v_addc_co_u32_e32 v81, vcc, 0, v107, vcc
	v_add_co_u32_e32 v92, vcc, 0x57b0000, v104
	global_load_dwordx4 v[76:79], v[76:77], off offset:128
	s_nop 0
	global_load_dwordx4 v[80:83], v[80:81], off offset:128
	v_addc_co_u32_e32 v93, vcc, 0, v105, vcc
	v_add_co_u32_e32 v96, vcc, 0x40000, v106
	s_nop 1
	v_addc_co_u32_e32 v97, vcc, 0, v107, vcc
	v_add_co_u32_e32 v104, vcc, 0x57d0000, v104
	global_load_dwordx4 v[92:95], v[92:93], off offset:128
	s_nop 0
	global_load_dwordx4 v[96:99], v[96:97], off offset:128
	v_addc_co_u32_e32 v105, vcc, 0, v105, vcc
	s_waitcnt vmcnt(6)
	v_add_co_u32_e32 v108, vcc, 0x60000, v106
	s_nop 1
	v_addc_co_u32_e32 v109, vcc, 0, v107, vcc
	global_load_dwordx4 v[104:107], v[104:105], off offset:128
	s_nop 0
	global_load_dwordx4 v[108:111], v[108:109], off offset:128
	s_barrier
	s_branch .LBB0_198

; #define LDF_A(dst, mh, co) _Pragma("unroll") for (int m = 0; m < 4; ++m) dst[m] = *reinterpret_cast<const bf16x8*>(sa + ((mh) * 4 + m) * 2048 + (co))
; #define LDF_B(dst, co) _Pragma("unroll") for (int n = 0; n < 4; ++n) dst[n] = *reinterpret_cast<const bf16x8*>(sb + n * 2048 + (co))
; #define MMA16(av, bv, mh) do { __builtin_amdgcn_s_setprio(1); _Pragma("unroll") for (int m = 0; m < 4; ++m) _Pragma("unroll") for (int n = 0; n < 4; ++n) \
;       acc[(mh) * 4 + m][n] = mfma16(av[m], bv[n], acc[(mh) * 4 + m][n]); __builtin_amdgcn_s_setprio(0); } while (0)
; __device__ __forceinline__ void gemm_mainloop256(const bh* __restrict__ A, long lda, const bh* __restrict__ B, long ldb, int K,
;                                                  char* lds, f32x4 (&acc)[8][4]) {
;     ...
;     const char* sa = lds + (kt & 1) * STAGE + a_row;
;     const char* sb = lds + (kt & 1) * STAGE + T_BYTES + b_row;
;     bf16x8 b0[4], a0[4], a1[4];
;     ...
;     LDF_B(b0, c0); LDF_A(a0, 0, c0);
;     LDF_A(a1, 1, c0);
;     MMA16(a0, b0, 0);
;     LDF_A(a0, 0, c1);
;     MMA16(a1, b0, 1);
;     LDF_B(b0, c1); LDF_A(a1, 1, c1);
;     MMA16(a0, b0, 0);
;     MMA16(a1, b0, 1);
.LBB0_198:
	s_cmp_gt_u32 s1, 14
	s_cselect_b64 s[8:9], -1, 0
	s_and_b32 s5, s3, 0x10000
	s_add_i32 s5, s5, 32
	v_add_u32_e32 v171, s5, v166
	v_add_u32_e32 v176, v171, v168
	ds_read_b128 v[172:175], v176 offset:32768
	ds_read_b128 v[182:185], v176 offset:34816
	ds_read_b128 v[206:209], v176 offset:36864
	ds_read_b128 v[210:213], v176 offset:38912
	v_add_u32_e32 v176, s5, v167
	v_add_u32_e32 v179, v176, v168
	ds_read_b128 v[214:217], v179
	ds_read_b128 v[218:221], v179 offset:2048
	ds_read_b128 v[222:225], v179 offset:4096
	ds_read_b128 v[226:229], v179 offset:6144
	ds_read_b128 v[230:233], v179 offset:8192
	ds_read_b128 v[234:237], v179 offset:10240
	ds_read_b128 v[238:241], v179 offset:12288
	ds_read_b128 v[242:245], v179 offset:14336
.LBB0_200:
	s_setprio 1
	s_waitcnt lgkmcnt(7)
	v_mfma_f32_16x16x32_bf16 v[156:159], v[214:217], v[172:175], v[156:159]
	v_mfma_f32_16x16x32_bf16 v[152:155], v[214:217], v[182:185], v[152:155]
	v_mfma_f32_16x16x32_bf16 v[148:151], v[214:217], v[206:209], v[148:151]
	v_mfma_f32_16x16x32_bf16 v[144:147], v[214:217], v[210:213], v[144:147]
	s_waitcnt lgkmcnt(6)
	v_mfma_f32_16x16x32_bf16 v[140:143], v[218:221], v[172:175], v[140:143]
	v_mfma_f32_16x16x32_bf16 v[136:139], v[218:221], v[182:185], v[136:139]
	v_mfma_f32_16x16x32_bf16 v[132:135], v[218:221], v[206:209], v[132:135]
	v_mfma_f32_16x16x32_bf16 v[128:131], v[218:221], v[210:213], v[128:131]
	s_waitcnt lgkmcnt(5)
	v_mfma_f32_16x16x32_bf16 v[124:127], v[222:225], v[172:175], v[124:127]
	v_mfma_f32_16x16x32_bf16 v[120:123], v[222:225], v[182:185], v[120:123]
	v_mfma_f32_16x16x32_bf16 v[116:119], v[222:225], v[206:209], v[116:119]
	v_mfma_f32_16x16x32_bf16 v[112:115], v[222:225], v[210:213], v[112:115]
	s_waitcnt lgkmcnt(4)
	v_mfma_f32_16x16x32_bf16 v[100:103], v[226:229], v[172:175], v[100:103]
	v_mfma_f32_16x16x32_bf16 v[88:91], v[226:229], v[182:185], v[88:91]
	v_mfma_f32_16x16x32_bf16 v[84:87], v[226:229], v[206:209], v[84:87]
	v_mfma_f32_16x16x32_bf16 v[72:75], v[226:229], v[210:213], v[72:75]
	s_setprio 0
	v_add_u32_e32 v176, v176, v169
	ds_read_b128 v[214:217], v176
	ds_read_b128 v[218:221], v176 offset:2048
	ds_read_b128 v[222:225], v176 offset:4096
	ds_read_b128 v[226:229], v176 offset:6144
	s_setprio 1
	s_waitcnt lgkmcnt(7)
	v_mfma_f32_16x16x32_bf16 v[60:63], v[230:233], v[172:175], v[60:63]
	v_mfma_f32_16x16x32_bf16 v[56:59], v[230:233], v[182:185], v[56:59]
	v_mfma_f32_16x16x32_bf16 v[52:55], v[230:233], v[206:209], v[52:55]
	v_mfma_f32_16x16x32_bf16 v[48:51], v[230:233], v[210:213], v[48:51]
	s_waitcnt lgkmcnt(6)
	v_mfma_f32_16x16x32_bf16 v[44:47], v[234:237], v[172:175], v[44:47]
	v_mfma_f32_16x16x32_bf16 v[40:43], v[234:237], v[182:185], v[40:43]
	v_mfma_f32_16x16x32_bf16 v[36:39], v[234:237], v[206:209], v[36:39]
	v_mfma_f32_16x16x32_bf16 v[32:35], v[234:237], v[210:213], v[32:35]
	s_waitcnt lgkmcnt(5)
	v_mfma_f32_16x16x32_bf16 v[28:31], v[238:241], v[172:175], v[28:31]
	v_mfma_f32_16x16x32_bf16 v[24:27], v[238:241], v[182:185], v[24:27]
	v_mfma_f32_16x16x32_bf16 v[20:23], v[238:241], v[206:209], v[20:23]
	v_mfma_f32_16x16x32_bf16 v[16:19], v[238:241], v[210:213], v[16:19]
	s_waitcnt lgkmcnt(4)
	v_mfma_f32_16x16x32_bf16 v[12:15], v[242:245], v[172:175], v[12:15]
	v_mfma_f32_16x16x32_bf16 v[8:11], v[242:245], v[182:185], v[8:11]
	v_mfma_f32_16x16x32_bf16 v[4:7], v[242:245], v[206:209], v[4:7]
	v_mfma_f32_16x16x32_bf16 v[0:3], v[242:245], v[210:213], v[0:3]
	s_setprio 0
	v_add_u32_e32 v171, v171, v169
	ds_read_b128 v[172:175], v171 offset:32768
	ds_read_b128 v[182:185], v171 offset:34816
	ds_read_b128 v[206:209], v171 offset:36864
	ds_read_b128 v[210:213], v171 offset:38912
	ds_read_b128 v[230:233], v176 offset:8192
	ds_read_b128 v[234:237], v176 offset:10240
	ds_read_b128 v[238:241], v176 offset:12288
	ds_read_b128 v[242:245], v176 offset:14336
	s_and_b64 vcc, exec, s[8:9]
	s_cbranch_vccnz .Lmy_g256_last_6
; #define LDF_A(dst, mh, co) _Pragma("unroll") for (int m = 0; m < 4; ++m) dst[m] = *reinterpret_cast<const bf16x8*>(sa + ((mh) * 4 + m) * 2048 + (co))
; #define LDF_B(dst, co) _Pragma("unroll") for (int n = 0; n < 4; ++n) dst[n] = *reinterpret_cast<const bf16x8*>(sb + n * 2048 + (co))
; #define MMA16(av, bv, mh) do { __builtin_amdgcn_s_setprio(1); _Pragma("unroll") for (int m = 0; m < 4; ++m) _Pragma("unroll") for (int n = 0; n < 4; ++n) \
;       acc[(mh) * 4 + m][n] = mfma16(av[m], bv[n], acc[(mh) * 4 + m][n]); __builtin_amdgcn_s_setprio(0); } while (0)
; __device__ __forceinline__ void gemm_mainloop256(const bh* __restrict__ A, long lda, const bh* __restrict__ B, long ldb, int K,
;                                                  char* lds, f32x4 (&acc)[8][4]) {
;     ...
;     MMA16(a1, b0, 1);
;     LDF_B(b0, c1); LDF_A(a1, 1, c1);
;     MMA16(a0, b0, 0);
;     MMA16(a1, b0, 1);
;     ...
;     if (more) {
;       char* wb = lds + ((kt + 1) & 1) * STAGE;
; #pragma unroll
;       for (int i = 0; i < 4; ++i) { *reinterpret_cast<bf16x8*>(wb + swo + i * 8192) = ra[i]; *reinterpret_cast<bf16x8*>(wb + T_BYTES + swo + i * 8192) = rb[i]; }
;     }
;     __syncthreads();
	s_add_i32 s5, s3, 0x10000
	s_and_b32 s3, s5, 0x10000
	v_add_u32_e32 v171, s3, v170
	s_setprio 1
	s_waitcnt lgkmcnt(7)
	v_mfma_f32_16x16x32_bf16 v[156:159], v[214:217], v[172:175], v[156:159]
	s_waitcnt lgkmcnt(6)
	v_mfma_f32_16x16x32_bf16 v[152:155], v[214:217], v[182:185], v[152:155]
	s_waitcnt lgkmcnt(5)
	v_mfma_f32_16x16x32_bf16 v[148:151], v[214:217], v[206:209], v[148:151]
	s_waitcnt lgkmcnt(4)
	v_mfma_f32_16x16x32_bf16 v[144:147], v[214:217], v[210:213], v[144:147]
	s_waitcnt vmcnt(7)
	ds_write_b128 v171, v[64:67]
	v_mfma_f32_16x16x32_bf16 v[140:143], v[218:221], v[172:175], v[140:143]
	v_mfma_f32_16x16x32_bf16 v[136:139], v[218:221], v[182:185], v[136:139]
	v_mfma_f32_16x16x32_bf16 v[132:135], v[218:221], v[206:209], v[132:135]
	v_mfma_f32_16x16x32_bf16 v[128:131], v[218:221], v[210:213], v[128:131]
	s_waitcnt vmcnt(6)
	ds_write_b128 v171, v[68:71] offset:32768
	v_mfma_f32_16x16x32_bf16 v[124:127], v[222:225], v[172:175], v[124:127]
	v_mfma_f32_16x16x32_bf16 v[120:123], v[222:225], v[182:185], v[120:123]
	v_mfma_f32_16x16x32_bf16 v[116:119], v[222:225], v[206:209], v[116:119]
	v_mfma_f32_16x16x32_bf16 v[112:115], v[222:225], v[210:213], v[112:115]
	s_waitcnt vmcnt(5)
	ds_write_b128 v171, v[76:79] offset:8192
	v_mfma_f32_16x16x32_bf16 v[100:103], v[226:229], v[172:175], v[100:103]
	v_mfma_f32_16x16x32_bf16 v[88:91], v[226:229], v[182:185], v[88:91]
	v_mfma_f32_16x16x32_bf16 v[84:87], v[226:229], v[206:209], v[84:87]
	v_mfma_f32_16x16x32_bf16 v[72:75], v[226:229], v[210:213], v[72:75]
	s_waitcnt vmcnt(4)
	ds_write_b128 v171, v[80:83] offset:40960
	s_waitcnt lgkmcnt(7)
	v_mfma_f32_16x16x32_bf16 v[60:63], v[230:233], v[172:175], v[60:63]
	v_mfma_f32_16x16x32_bf16 v[56:59], v[230:233], v[182:185], v[56:59]
	v_mfma_f32_16x16x32_bf16 v[52:55], v[230:233], v[206:209], v[52:55]
	v_mfma_f32_16x16x32_bf16 v[48:51], v[230:233], v[210:213], v[48:51]
	s_waitcnt vmcnt(3)
	ds_write_b128 v171, v[92:95] offset:16384
	s_waitcnt lgkmcnt(7)
	v_mfma_f32_16x16x32_bf16 v[44:47], v[234:237], v[172:175], v[44:47]
	v_mfma_f32_16x16x32_bf16 v[40:43], v[234:237], v[182:185], v[40:43]
	v_mfma_f32_16x16x32_bf16 v[36:39], v[234:237], v[206:209], v[36:39]
	v_mfma_f32_16x16x32_bf16 v[32:35], v[234:237], v[210:213], v[32:35]
	s_waitcnt vmcnt(2)
	ds_write_b128 v171, v[96:99] offset:49152
	s_waitcnt lgkmcnt(7)
	v_mfma_f32_16x16x32_bf16 v[28:31], v[238:241], v[172:175], v[28:31]
	v_mfma_f32_16x16x32_bf16 v[24:27], v[238:241], v[182:185], v[24:27]
	v_mfma_f32_16x16x32_bf16 v[20:23], v[238:241], v[206:209], v[20:23]
	v_mfma_f32_16x16x32_bf16 v[16:19], v[238:241], v[210:213], v[16:19]
	s_waitcnt vmcnt(1)
	ds_write_b128 v171, v[104:107] offset:24576
	s_waitcnt lgkmcnt(7)
	v_mfma_f32_16x16x32_bf16 v[12:15], v[242:245], v[172:175], v[12:15]
	v_mfma_f32_16x16x32_bf16 v[8:11], v[242:245], v[182:185], v[8:11]
	v_mfma_f32_16x16x32_bf16 v[4:7], v[242:245], v[206:209], v[4:7]
	v_mfma_f32_16x16x32_bf16 v[0:3], v[242:245], v[210:213], v[0:3]
	s_waitcnt vmcnt(0)
	ds_write_b128 v171, v[108:111] offset:57344
	s_setprio 0
	s_cmp_gt_u32 s1, 13
	s_cbranch_scc1 .Lmy_t14_skip_1
	s_waitcnt vmcnt(1)
	v_lshl_add_u64 v[104:105], v[162:163], 0, s[6:7]
	v_add_co_u32_e32 v64, vcc, 0x5770000, v104
	v_lshl_add_u64 v[106:107], v[160:161], 0, s[6:7]
	s_nop 0
	v_addc_co_u32_e32 v65, vcc, 0, v105, vcc
	v_add_co_u32_e32 v76, vcc, 0x5790000, v104
	global_load_dwordx4 v[64:67], v[64:65], off offset:256
	s_nop 0
	global_load_dwordx4 v[68:71], v[106:107], off offset:256
	v_addc_co_u32_e32 v77, vcc, 0, v105, vcc
	v_add_co_u32_e32 v80, vcc, 0x20000, v106
	s_nop 1
	v_addc_co_u32_e32 v81, vcc, 0, v107, vcc
	v_add_co_u32_e32 v92, vcc, 0x57b0000, v104
	global_load_dwordx4 v[76:79], v[76:77], off offset:256
	s_nop 0
	global_load_dwordx4 v[80:83], v[80:81], off offset:256
	v_addc_co_u32_e32 v93, vcc, 0, v105, vcc
	v_add_co_u32_e32 v96, vcc, 0x40000, v106
	s_nop 1
	v_addc_co_u32_e32 v97, vcc, 0, v107, vcc
	v_add_co_u32_e32 v104, vcc, 0x57d0000, v104
	global_load_dwordx4 v[92:95], v[92:93], off offset:256
	s_nop 0
	global_load_dwordx4 v[96:99], v[96:97], off offset:256
	v_addc_co_u32_e32 v105, vcc, 0, v105, vcc
	s_waitcnt vmcnt(6)
	v_add_co_u32_e32 v108, vcc, 0x60000, v106
	s_nop 1
	v_addc_co_u32_e32 v109, vcc, 0, v107, vcc
	global_load_dwordx4 v[104:107], v[104:105], off offset:256
	s_nop 0
	global_load_dwordx4 v[108:111], v[108:109], off offset:256
.Lmy_t14_skip_1:
	s_branch .LBB0_197

; __device__ __forceinline__ int tidx() { int t = threadIdx.x; asm volatile("" : "+v"(t)); return t; }
; __device__ __forceinline__ void gemm_mainloop256(const bh* __restrict__ A, long lda, const bh* __restrict__ B, long ldb, int K,
;                                                  char* lds, f32x4 (&acc)[8][4]) {
;   constexpr int T_BYTES = 256 * 128, STAGE = 2 * T_BYTES;
;   const int tid = tidx(), lane = tid & 63, wid = tid >> 6, wr = wid >> 2, wc = wid & 3, fr = lane & 15, fq = lane >> 4;
;   const int srow = tid >> 3, sch = tid & 7;
;   const bh* Ap = A + (long)srow * lda + sch * 8;
;   const bh* Bp = B + (long)srow * ldb + sch * 8;
;   const int swo = srow * 128 + ((sch ^ (srow & 7)) << 4);
;   bf16x8 ra[4], rb[4];
;   const int nk = K >> 6;
; #pragma unroll
;   for (int i = 0; i < 4; ++i) { ra[i] = *reinterpret_cast<const bf16x8*>(Ap + (long)(64 * i) * lda); rb[i] = *reinterpret_cast<const bf16x8*>(Bp + (long)(64 * i) * ldb); }
; #pragma unroll
;   for (int i = 0; i < 4; ++i) { *reinterpret_cast<bf16x8*>(lds + swo + i * 8192) = ra[i]; *reinterpret_cast<bf16x8*>(lds + T_BYTES + swo + i * 8192) = rb[i]; }
;   __syncthreads();
; template <int OMODE>
; __device__ __forceinline__ void gemm_phase256(const bh* __restrict__ A, long lda, const bh* __restrict__ Bt, long ldb, int M, int ncols, int K,
;                                               void* Cp, long ldc, char* lds) {
;   const int tm_n = M >> 8, tn_n = ncols >> 8;
;   const int tid = tidx(), lane = tid & 63, wid = tid >> 6, wr = wid >> 2, wc = wid & 3, fr = lane & 15, fq = lane >> 4;
;   for (int tile = blockIdx.x; tile < tm_n * tn_n; tile += gridDim.x) {
;     const int tn = tile / tm_n, tm = tile - tn * tm_n;
;     f32x4 acc[8][4];
; #pragma unroll
;     for (int m = 0; m < 8; ++m)
; #pragma unroll
;       for (int n = 0; n < 4; ++n) acc[m][n] = f32x4{0.f, 0.f, 0.f, 0.f};
;     gemm_mainloop256(A + (long)tm * 256 * lda, lda, Bt + (long)tn * 256 * ldb, ldb, K, lds, acc);
.LBB0_743:
	s_ashr_i32 s1, s0, 31
	s_lshl_b64 s[10:11], s[0:1], 19
	s_lshr_b32 s1, s1, 26
	s_add_i32 s1, s0, s1
	s_and_b32 s8, s1, 0xffffffc0
	s_sub_i32 s4, s0, s8
	s_ashr_i32 s5, s4, 31
	s_ashr_i32 s2, s1, 6
	s_lshl_b64 s[6:7], s[4:5], 19
	v_mov_b32_e32 v12, v188
	s_add_u32 s14, s38, s6
	s_addc_u32 s15, s39, s7
	v_ashrrev_i32_e32 v0, 3, v12
	s_ashr_i32 s3, s2, 31
	v_ashrrev_i32_e32 v1, 31, v0
	s_lshl_b64 s[6:7], s[2:3], 19
	v_lshlrev_b64 v[2:3], 11, v[0:1]
	v_lshlrev_b32_e32 v1, 4, v12
	s_add_u32 s16, s12, s6
	v_lshl_add_u64 v[4:5], s[14:15], 0, v[2:3]
	v_and_b32_e32 v176, 0x70, v1
	s_addc_u32 s17, s13, s7
	v_lshl_add_u64 v[4:5], v[4:5], 0, v[176:177]
	s_mov_b32 s1, 0x20000
	v_lshl_add_u64 v[6:7], s[16:17], 0, v[2:3]
	v_add_co_u32_e32 v8, vcc, s1, v4
	v_lshl_add_u64 v[6:7], v[6:7], 0, v[176:177]
	s_nop 0
	v_addc_co_u32_e32 v9, vcc, 0, v5, vcc
	v_add_co_u32_e32 v10, vcc, s1, v6
	s_mov_b32 s1, 0x40000
	s_nop 0
	v_addc_co_u32_e32 v11, vcc, 0, v7, vcc
	global_load_dwordx4 v[120:123], v[4:5], off
	global_load_dwordx4 v[124:127], v[6:7], off
	global_load_dwordx4 v[128:131], v[8:9], off
	global_load_dwordx4 v[132:135], v[10:11], off
	v_add_co_u32_e32 v8, vcc, s1, v4
	v_lshrrev_b32_e32 v1, 4, v12
	s_nop 0
	v_addc_co_u32_e32 v9, vcc, 0, v5, vcc
	v_add_co_u32_e32 v10, vcc, s1, v6
	s_mov_b32 s1, 0x60000
	s_nop 0
	v_addc_co_u32_e32 v11, vcc, 0, v7, vcc
	v_add_co_u32_e32 v4, vcc, s1, v4
	global_load_dwordx4 v[136:139], v[8:9], off
	global_load_dwordx4 v[140:143], v[10:11], off
	v_addc_co_u32_e32 v5, vcc, 0, v5, vcc
	global_load_dwordx4 v[144:147], v[4:5], off
	v_add_co_u32_e32 v4, vcc, s1, v6
	v_lshrrev_b32_e32 v6, 1, v12
	s_nop 0
	v_addc_co_u32_e32 v5, vcc, 0, v7, vcc
	global_load_dwordx4 v[148:151], v[4:5], off
	v_and_b32_e32 v4, 15, v12
	v_lshlrev_b32_e32 v7, 7, v12
	v_and_b32_e32 v8, 7, v12
	v_xor_b32_e32 v9, v0, v12
	s_mov_b32 s1, 0x1ffff80
	v_lshlrev_b32_e32 v0, 7, v0
	v_and_or_b32 v4, v6, s1, v4
	v_and_b32_e32 v166, 0x6780, v7
	v_bitop3_b32 v1, v1, v8, 3 bitop3:0x6c
	v_lshlrev_b32_e32 v7, 4, v9
	s_movk_i32 s1, 0x70
	v_lshlrev_b32_e32 v6, 4, v8
	v_lshlrev_b32_e32 v167, 7, v4
	v_lshlrev_b32_e32 v168, 4, v1
	v_and_or_b32 v4, v7, s1, v0
	v_lshl_add_u64 v[0:1], s[10:11], 0, v[2:3]
	s_ashr_i32 s9, s8, 31
	v_or_b32_e32 v0, v0, v6
	s_lshl_b64 s[8:9], s[8:9], 19
	v_add_u32_e32 v170, 32, v4
	v_mov_b32_e32 v4, s9
	v_subrev_co_u32_e32 v0, vcc, s8, v0
	v_bfe_u32 v5, v12, 4, 2
	s_nop 0
	v_subb_co_u32_e32 v1, vcc, v1, v4, vcc
	v_lshl_add_u64 v[160:161], s[28:29], 0, v[0:1]
	v_lshl_add_u64 v[0:1], s[6:7], 0, v[2:3]
	v_readlane_b32 s6, v253, 55
	v_or_b32_e32 v0, v0, v6
	v_readlane_b32 s7, v253, 56
	v_bitop3_b32 v5, v5, v8, 4 bitop3:0x36
	s_mov_b32 s3, 0
	v_lshl_add_u64 v[162:163], s[6:7], 0, v[0:1]
	v_mov_b32_e32 v0, 0
	v_lshlrev_b32_e32 v169, 4, v5
	s_mov_b64 s[6:7], 0
	s_mov_b32 s1, 0
	v_mov_b32_e32 v1, v0
	v_mov_b32_e32 v2, v0
	v_mov_b32_e32 v3, v0
	v_mov_b32_e32 v4, v0
	v_mov_b32_e32 v5, v0
	v_mov_b32_e32 v6, v0
	v_mov_b32_e32 v7, v0
	v_mov_b32_e32 v8, v0
	v_mov_b32_e32 v9, v0
	v_mov_b32_e32 v10, v0
	v_mov_b32_e32 v11, v0
	v_mov_b32_e32 v12, v0
	v_mov_b32_e32 v13, v0
	v_mov_b32_e32 v14, v0
	v_mov_b32_e32 v15, v0
	v_mov_b32_e32 v16, v0
	v_mov_b32_e32 v17, v0
	v_mov_b32_e32 v18, v0
	v_mov_b32_e32 v19, v0
	v_mov_b32_e32 v20, v0
	v_mov_b32_e32 v21, v0
	v_mov_b32_e32 v22, v0
	v_mov_b32_e32 v23, v0
	v_mov_b32_e32 v24, v0
	v_mov_b32_e32 v25, v0
	v_mov_b32_e32 v26, v0
	v_mov_b32_e32 v27, v0
	v_mov_b32_e32 v28, v0
	v_mov_b32_e32 v29, v0
	v_mov_b32_e32 v30, v0
	v_mov_b32_e32 v31, v0
	v_mov_b32_e32 v32, v0
	v_mov_b32_e32 v33, v0
	v_mov_b32_e32 v34, v0
	v_mov_b32_e32 v35, v0
	v_mov_b32_e32 v36, v0
	v_mov_b32_e32 v37, v0
	v_mov_b32_e32 v38, v0
	v_mov_b32_e32 v39, v0
	v_mov_b32_e32 v40, v0
	v_mov_b32_e32 v41, v0
	v_mov_b32_e32 v42, v0
	v_mov_b32_e32 v43, v0
	v_mov_b32_e32 v44, v0
	v_mov_b32_e32 v45, v0
	v_mov_b32_e32 v46, v0
	v_mov_b32_e32 v47, v0
	v_mov_b32_e32 v48, v0
	v_mov_b32_e32 v49, v0
	v_mov_b32_e32 v50, v0
	v_mov_b32_e32 v51, v0
	v_mov_b32_e32 v52, v0
	v_mov_b32_e32 v53, v0
	v_mov_b32_e32 v54, v0
	v_mov_b32_e32 v55, v0
	v_mov_b32_e32 v56, v0
	v_mov_b32_e32 v57, v0
	v_mov_b32_e32 v58, v0
	v_mov_b32_e32 v59, v0
	v_mov_b32_e32 v60, v0
	v_mov_b32_e32 v61, v0
	v_mov_b32_e32 v62, v0
	v_mov_b32_e32 v63, v0
	v_mov_b32_e32 v64, v0
	v_mov_b32_e32 v65, v0
	v_mov_b32_e32 v66, v0
	v_mov_b32_e32 v67, v0
	v_mov_b32_e32 v68, v0
	v_mov_b32_e32 v69, v0
	v_mov_b32_e32 v70, v0
	v_mov_b32_e32 v71, v0
	v_mov_b32_e32 v72, v0
	v_mov_b32_e32 v73, v0
	v_mov_b32_e32 v74, v0
	v_mov_b32_e32 v75, v0
	v_mov_b32_e32 v76, v0
	v_mov_b32_e32 v77, v0
	v_mov_b32_e32 v78, v0
	v_mov_b32_e32 v79, v0
	v_mov_b32_e32 v80, v0
	v_mov_b32_e32 v81, v0
	v_mov_b32_e32 v82, v0
	v_mov_b32_e32 v83, v0
	v_mov_b32_e32 v84, v0
	v_mov_b32_e32 v85, v0
	v_mov_b32_e32 v86, v0
	v_mov_b32_e32 v87, v0
	v_mov_b32_e32 v88, v0
	v_mov_b32_e32 v89, v0
	v_mov_b32_e32 v90, v0
	v_mov_b32_e32 v91, v0
	v_mov_b32_e32 v92, v0
	v_mov_b32_e32 v93, v0
	v_mov_b32_e32 v94, v0
	v_mov_b32_e32 v95, v0
	v_mov_b32_e32 v96, v0
	v_mov_b32_e32 v97, v0
	v_mov_b32_e32 v98, v0
	v_mov_b32_e32 v99, v0
	v_mov_b32_e32 v100, v0
	v_mov_b32_e32 v101, v0
	v_mov_b32_e32 v102, v0
	v_mov_b32_e32 v103, v0
	v_mov_b32_e32 v104, v0
	v_mov_b32_e32 v105, v0
	v_mov_b32_e32 v106, v0
	v_mov_b32_e32 v107, v0
	v_mov_b32_e32 v108, v0
	v_mov_b32_e32 v109, v0
	v_mov_b32_e32 v110, v0
	v_mov_b32_e32 v111, v0
	v_mov_b32_e32 v112, v0
	v_mov_b32_e32 v113, v0
	v_mov_b32_e32 v114, v0
	v_mov_b32_e32 v115, v0
	v_mov_b32_e32 v116, v0
	v_mov_b32_e32 v117, v0
	v_mov_b32_e32 v118, v0
	v_mov_b32_e32 v119, v0
	v_mov_b32_e32 v152, v0
	v_mov_b32_e32 v153, v0
	v_mov_b32_e32 v154, v0
	v_mov_b32_e32 v155, v0
	v_mov_b32_e32 v156, v0
	v_mov_b32_e32 v157, v0
	v_mov_b32_e32 v158, v0
	v_mov_b32_e32 v159, v0
	s_waitcnt vmcnt(7)
; __device__ __forceinline__ void gemm_mainloop256(const bh* __restrict__ A, long lda, const bh* __restrict__ B, long ldb, int K,
;                                                  char* lds, f32x4 (&acc)[8][4]) {
;     ...
; #pragma unroll
;   for (int i = 0; i < 4; ++i) { ra[i] = *reinterpret_cast<const bf16x8*>(Ap + (long)(64 * i) * lda); rb[i] = *reinterpret_cast<const bf16x8*>(Bp + (long)(64 * i) * ldb); }
; #pragma unroll
;   for (int i = 0; i < 4; ++i) { *reinterpret_cast<bf16x8*>(lds + swo + i * 8192) = ra[i]; *reinterpret_cast<bf16x8*>(lds + T_BYTES + swo + i * 8192) = rb[i]; }
;   __syncthreads();
;   const int a_row = (wr * 128 + fr) * 128, b_row = (wc * 64 + fr) * 128;
;   const int c0 = ((0 + fq) ^ (fr & 7)) << 4, c1 = ((4 + fq) ^ (fr & 7)) << 4;
; #pragma unroll 1
;   for (int kt = 0; kt < nk; ++kt) {
;     const bool more = kt + 1 < nk;
;     if (more) {
; #pragma unroll
;       for (int i = 0; i < 4; ++i) { ra[i] = *reinterpret_cast<const bf16x8*>(Ap + (long)(64 * i) * lda + (kt + 1) * 64); rb[i] = *reinterpret_cast<const bf16x8*>(Bp + (long)(64 * i) * ldb + (kt + 1) * 64); }
;     }
	ds_write_b128 v170, v[120:123]
	s_waitcnt vmcnt(5)
	ds_write_b128 v170, v[128:131] offset:8192
	s_waitcnt vmcnt(3)
	ds_write_b128 v170, v[136:139] offset:16384
	s_waitcnt vmcnt(1)
	ds_write_b128 v170, v[144:147] offset:24576
	ds_write_b128 v170, v[124:127] offset:32768
	ds_write_b128 v170, v[132:135] offset:40960
	ds_write_b128 v170, v[140:143] offset:49152
	s_waitcnt vmcnt(0)
	ds_write_b128 v170, v[148:151] offset:57344
	s_waitcnt lgkmcnt(0)
	s_waitcnt vmcnt(1)
	v_lshl_add_u64 v[144:145], v[160:161], 0, s[6:7]
	v_add_co_u32_e32 v120, vcc, 0x5770000, v144
	v_lshl_add_u64 v[146:147], v[162:163], 0, s[6:7]
	s_nop 0
	v_addc_co_u32_e32 v121, vcc, 0, v145, vcc
	v_add_co_u32_e32 v124, vcc, 0x858000, v146
	s_nop 1
	v_addc_co_u32_e32 v125, vcc, 0, v147, vcc
	v_add_co_u32_e32 v128, vcc, 0x5790000, v144
	global_load_dwordx4 v[120:123], v[120:121], off offset:128
	s_nop 0
	global_load_dwordx4 v[124:127], v[124:125], off offset:128
	v_addc_co_u32_e32 v129, vcc, 0, v145, vcc
	v_add_co_u32_e32 v132, vcc, 0x878000, v146
	s_nop 1
	v_addc_co_u32_e32 v133, vcc, 0, v147, vcc
	v_add_co_u32_e32 v136, vcc, 0x57b0000, v144
	global_load_dwordx4 v[128:131], v[128:129], off offset:128
	s_nop 0
	global_load_dwordx4 v[132:135], v[132:133], off offset:128
	v_addc_co_u32_e32 v137, vcc, 0, v145, vcc
	v_add_co_u32_e32 v140, vcc, 0x898000, v146
	s_nop 1
	v_addc_co_u32_e32 v141, vcc, 0, v147, vcc
	v_add_co_u32_e32 v144, vcc, 0x57d0000, v144
	global_load_dwordx4 v[136:139], v[136:137], off offset:128
	s_nop 0
	global_load_dwordx4 v[140:143], v[140:141], off offset:128
	v_addc_co_u32_e32 v145, vcc, 0, v145, vcc
	s_waitcnt vmcnt(6)
	v_add_co_u32_e32 v148, vcc, 0x8b8000, v146
	s_nop 1
	v_addc_co_u32_e32 v149, vcc, 0, v147, vcc
	global_load_dwordx4 v[144:147], v[144:145], off offset:128
	s_nop 0
	global_load_dwordx4 v[148:151], v[148:149], off offset:128
	s_barrier
	s_branch .LBB0_745

; #define LDF_A(dst, mh, co) _Pragma("unroll") for (int m = 0; m < 4; ++m) dst[m] = *reinterpret_cast<const bf16x8*>(sa + ((mh) * 4 + m) * 2048 + (co))
; #define LDF_B(dst, co) _Pragma("unroll") for (int n = 0; n < 4; ++n) dst[n] = *reinterpret_cast<const bf16x8*>(sb + n * 2048 + (co))
; #define MMA16(av, bv, mh) do { __builtin_amdgcn_s_setprio(1); _Pragma("unroll") for (int m = 0; m < 4; ++m) _Pragma("unroll") for (int n = 0; n < 4; ++n) \
;       acc[(mh) * 4 + m][n] = mfma16(av[m], bv[n], acc[(mh) * 4 + m][n]); __builtin_amdgcn_s_setprio(0); } while (0)
; __device__ __forceinline__ void gemm_mainloop256(const bh* __restrict__ A, long lda, const bh* __restrict__ B, long ldb, int K,
;                                                  char* lds, f32x4 (&acc)[8][4]) {
;     ...
;     const char* sa = lds + (kt & 1) * STAGE + a_row;
;     const char* sb = lds + (kt & 1) * STAGE + T_BYTES + b_row;
;     bf16x8 b0[4], a0[4], a1[4];
;     ...
;     LDF_B(b0, c0); LDF_A(a0, 0, c0);
;     LDF_A(a1, 1, c0);
;     MMA16(a0, b0, 0);
;     LDF_A(a0, 0, c1);
;     MMA16(a1, b0, 1);
;     LDF_B(b0, c1); LDF_A(a1, 1, c1);
;     MMA16(a0, b0, 0);
;     MMA16(a1, b0, 1);
.LBB0_745:
	s_cmp_gt_u32 s1, 14
	s_cselect_b64 s[8:9], -1, 0
	s_and_b32 s5, s3, 0x10000
	s_add_i32 s5, s5, 32
	v_add_u32_e32 v171, s5, v166
	v_add_u32_e32 v176, v171, v168
	ds_read_b128 v[172:175], v176 offset:32768
	ds_read_b128 v[182:185], v176 offset:34816
	ds_read_b128 v[198:201], v176 offset:36864
	ds_read_b128 v[206:209], v176 offset:38912
	v_add_u32_e32 v176, s5, v167
	v_add_u32_e32 v179, v176, v168
	ds_read_b128 v[210:213], v179
	ds_read_b128 v[214:217], v179 offset:2048
	ds_read_b128 v[218:221], v179 offset:4096
	ds_read_b128 v[222:225], v179 offset:6144
	ds_read_b128 v[226:229], v179 offset:8192
	ds_read_b128 v[230:233], v179 offset:10240
	ds_read_b128 v[234:237], v179 offset:12288
	ds_read_b128 v[238:241], v179 offset:14336
.LBB0_747:
	s_setprio 1
	s_waitcnt lgkmcnt(7)
	v_mfma_f32_16x16x32_bf16 v[156:159], v[210:213], v[172:175], v[156:159]
	v_mfma_f32_16x16x32_bf16 v[152:155], v[210:213], v[182:185], v[152:155]
	v_mfma_f32_16x16x32_bf16 v[116:119], v[210:213], v[198:201], v[116:119]
	v_mfma_f32_16x16x32_bf16 v[112:115], v[210:213], v[206:209], v[112:115]
	s_waitcnt lgkmcnt(6)
	v_mfma_f32_16x16x32_bf16 v[108:111], v[214:217], v[172:175], v[108:111]
	v_mfma_f32_16x16x32_bf16 v[104:107], v[214:217], v[182:185], v[104:107]
	v_mfma_f32_16x16x32_bf16 v[100:103], v[214:217], v[198:201], v[100:103]
	v_mfma_f32_16x16x32_bf16 v[96:99], v[214:217], v[206:209], v[96:99]
	s_waitcnt lgkmcnt(5)
	v_mfma_f32_16x16x32_bf16 v[92:95], v[218:221], v[172:175], v[92:95]
	v_mfma_f32_16x16x32_bf16 v[88:91], v[218:221], v[182:185], v[88:91]
	v_mfma_f32_16x16x32_bf16 v[84:87], v[218:221], v[198:201], v[84:87]
	v_mfma_f32_16x16x32_bf16 v[80:83], v[218:221], v[206:209], v[80:83]
	s_waitcnt lgkmcnt(4)
	v_mfma_f32_16x16x32_bf16 v[76:79], v[222:225], v[172:175], v[76:79]
	v_mfma_f32_16x16x32_bf16 v[72:75], v[222:225], v[182:185], v[72:75]
	v_mfma_f32_16x16x32_bf16 v[68:71], v[222:225], v[198:201], v[68:71]
	v_mfma_f32_16x16x32_bf16 v[64:67], v[222:225], v[206:209], v[64:67]
	s_setprio 0
	v_add_u32_e32 v176, v176, v169
	ds_read_b128 v[210:213], v176
	ds_read_b128 v[214:217], v176 offset:2048
	ds_read_b128 v[218:221], v176 offset:4096
	ds_read_b128 v[222:225], v176 offset:6144
	s_setprio 1
	s_waitcnt lgkmcnt(7)
	v_mfma_f32_16x16x32_bf16 v[60:63], v[226:229], v[172:175], v[60:63]
	v_mfma_f32_16x16x32_bf16 v[56:59], v[226:229], v[182:185], v[56:59]
	v_mfma_f32_16x16x32_bf16 v[52:55], v[226:229], v[198:201], v[52:55]
	v_mfma_f32_16x16x32_bf16 v[48:51], v[226:229], v[206:209], v[48:51]
	s_waitcnt lgkmcnt(6)
	v_mfma_f32_16x16x32_bf16 v[44:47], v[230:233], v[172:175], v[44:47]
	v_mfma_f32_16x16x32_bf16 v[40:43], v[230:233], v[182:185], v[40:43]
	v_mfma_f32_16x16x32_bf16 v[36:39], v[230:233], v[198:201], v[36:39]
	v_mfma_f32_16x16x32_bf16 v[32:35], v[230:233], v[206:209], v[32:35]
	s_waitcnt lgkmcnt(5)
	v_mfma_f32_16x16x32_bf16 v[28:31], v[234:237], v[172:175], v[28:31]
	v_mfma_f32_16x16x32_bf16 v[24:27], v[234:237], v[182:185], v[24:27]
	v_mfma_f32_16x16x32_bf16 v[20:23], v[234:237], v[198:201], v[20:23]
	v_mfma_f32_16x16x32_bf16 v[16:19], v[234:237], v[206:209], v[16:19]
	s_waitcnt lgkmcnt(4)
	v_mfma_f32_16x16x32_bf16 v[12:15], v[238:241], v[172:175], v[12:15]
	v_mfma_f32_16x16x32_bf16 v[8:11], v[238:241], v[182:185], v[8:11]
	v_mfma_f32_16x16x32_bf16 v[4:7], v[238:241], v[198:201], v[4:7]
	v_mfma_f32_16x16x32_bf16 v[0:3], v[238:241], v[206:209], v[0:3]
	s_setprio 0
	v_add_u32_e32 v171, v171, v169
	ds_read_b128 v[172:175], v171 offset:32768
	ds_read_b128 v[182:185], v171 offset:34816
	ds_read_b128 v[198:201], v171 offset:36864
	ds_read_b128 v[206:209], v171 offset:38912
	ds_read_b128 v[226:229], v176 offset:8192
	ds_read_b128 v[230:233], v176 offset:10240
	ds_read_b128 v[234:237], v176 offset:12288
	ds_read_b128 v[238:241], v176 offset:14336
	s_and_b64 vcc, exec, s[8:9]
	s_cbranch_vccnz .Lmy_g256_last_5
; #define LDF_A(dst, mh, co) _Pragma("unroll") for (int m = 0; m < 4; ++m) dst[m] = *reinterpret_cast<const bf16x8*>(sa + ((mh) * 4 + m) * 2048 + (co))
; #define LDF_B(dst, co) _Pragma("unroll") for (int n = 0; n < 4; ++n) dst[n] = *reinterpret_cast<const bf16x8*>(sb + n * 2048 + (co))
; #define MMA16(av, bv, mh) do { __builtin_amdgcn_s_setprio(1); _Pragma("unroll") for (int m = 0; m < 4; ++m) _Pragma("unroll") for (int n = 0; n < 4; ++n) \
;       acc[(mh) * 4 + m][n] = mfma16(av[m], bv[n], acc[(mh) * 4 + m][n]); __builtin_amdgcn_s_setprio(0); } while (0)
; __device__ __forceinline__ void gemm_mainloop256(const bh* __restrict__ A, long lda, const bh* __restrict__ B, long ldb, int K,
;                                                  char* lds, f32x4 (&acc)[8][4]) {
;     ...
;     if (more) {
; #pragma unroll
;       for (int i = 0; i < 4; ++i) { ra[i] = *reinterpret_cast<const bf16x8*>(Ap + (long)(64 * i) * lda + (kt + 1) * 64); rb[i] = *reinterpret_cast<const bf16x8*>(Bp + (long)(64 * i) * ldb + (kt + 1) * 64); }
;     }
;     ...
;     MMA16(a1, b0, 1);
;     LDF_B(b0, c1); LDF_A(a1, 1, c1);
;     MMA16(a0, b0, 0);
;     MMA16(a1, b0, 1);
;     ...
;     if (more) {
;       char* wb = lds + ((kt + 1) & 1) * STAGE;
; #pragma unroll
;       for (int i = 0; i < 4; ++i) { *reinterpret_cast<bf16x8*>(wb + swo + i * 8192) = ra[i]; *reinterpret_cast<bf16x8*>(wb + T_BYTES + swo + i * 8192) = rb[i]; }
;     }
;     __syncthreads();
	s_add_i32 s5, s3, 0x10000
	s_and_b32 s3, s5, 0x10000
	v_add_u32_e32 v171, s3, v170
	s_setprio 1
	s_waitcnt lgkmcnt(7)
	v_mfma_f32_16x16x32_bf16 v[156:159], v[210:213], v[172:175], v[156:159]
	s_waitcnt lgkmcnt(6)
	v_mfma_f32_16x16x32_bf16 v[152:155], v[210:213], v[182:185], v[152:155]
	s_waitcnt lgkmcnt(5)
	v_mfma_f32_16x16x32_bf16 v[116:119], v[210:213], v[198:201], v[116:119]
	s_waitcnt lgkmcnt(4)
	v_mfma_f32_16x16x32_bf16 v[112:115], v[210:213], v[206:209], v[112:115]
	s_waitcnt vmcnt(7)
	ds_write_b128 v171, v[120:123]
	v_mfma_f32_16x16x32_bf16 v[108:111], v[214:217], v[172:175], v[108:111]
	v_mfma_f32_16x16x32_bf16 v[104:107], v[214:217], v[182:185], v[104:107]
	v_mfma_f32_16x16x32_bf16 v[100:103], v[214:217], v[198:201], v[100:103]
	v_mfma_f32_16x16x32_bf16 v[96:99], v[214:217], v[206:209], v[96:99]
	s_waitcnt vmcnt(6)
	ds_write_b128 v171, v[124:127] offset:32768
	v_mfma_f32_16x16x32_bf16 v[92:95], v[218:221], v[172:175], v[92:95]
	v_mfma_f32_16x16x32_bf16 v[88:91], v[218:221], v[182:185], v[88:91]
	v_mfma_f32_16x16x32_bf16 v[84:87], v[218:221], v[198:201], v[84:87]
	v_mfma_f32_16x16x32_bf16 v[80:83], v[218:221], v[206:209], v[80:83]
	s_waitcnt vmcnt(5)
	ds_write_b128 v171, v[128:131] offset:8192
	v_mfma_f32_16x16x32_bf16 v[76:79], v[222:225], v[172:175], v[76:79]
	v_mfma_f32_16x16x32_bf16 v[72:75], v[222:225], v[182:185], v[72:75]
	v_mfma_f32_16x16x32_bf16 v[68:71], v[222:225], v[198:201], v[68:71]
	v_mfma_f32_16x16x32_bf16 v[64:67], v[222:225], v[206:209], v[64:67]
	s_waitcnt vmcnt(4)
	ds_write_b128 v171, v[132:135] offset:40960
	s_waitcnt lgkmcnt(7)
	v_mfma_f32_16x16x32_bf16 v[60:63], v[226:229], v[172:175], v[60:63]
	v_mfma_f32_16x16x32_bf16 v[56:59], v[226:229], v[182:185], v[56:59]
	v_mfma_f32_16x16x32_bf16 v[52:55], v[226:229], v[198:201], v[52:55]
	v_mfma_f32_16x16x32_bf16 v[48:51], v[226:229], v[206:209], v[48:51]
	s_waitcnt vmcnt(3)
	ds_write_b128 v171, v[136:139] offset:16384
	s_waitcnt lgkmcnt(7)
	v_mfma_f32_16x16x32_bf16 v[44:47], v[230:233], v[172:175], v[44:47]
	v_mfma_f32_16x16x32_bf16 v[40:43], v[230:233], v[182:185], v[40:43]
	v_mfma_f32_16x16x32_bf16 v[36:39], v[230:233], v[198:201], v[36:39]
	v_mfma_f32_16x16x32_bf16 v[32:35], v[230:233], v[206:209], v[32:35]
	s_waitcnt vmcnt(2)
	ds_write_b128 v171, v[140:143] offset:49152
	s_waitcnt lgkmcnt(7)
	v_mfma_f32_16x16x32_bf16 v[28:31], v[234:237], v[172:175], v[28:31]
	v_mfma_f32_16x16x32_bf16 v[24:27], v[234:237], v[182:185], v[24:27]
	v_mfma_f32_16x16x32_bf16 v[20:23], v[234:237], v[198:201], v[20:23]
	v_mfma_f32_16x16x32_bf16 v[16:19], v[234:237], v[206:209], v[16:19]
	s_waitcnt vmcnt(1)
	ds_write_b128 v171, v[144:147] offset:24576
	s_waitcnt lgkmcnt(7)
	v_mfma_f32_16x16x32_bf16 v[12:15], v[238:241], v[172:175], v[12:15]
	v_mfma_f32_16x16x32_bf16 v[8:11], v[238:241], v[182:185], v[8:11]
	v_mfma_f32_16x16x32_bf16 v[4:7], v[238:241], v[198:201], v[4:7]
	v_mfma_f32_16x16x32_bf16 v[0:3], v[238:241], v[206:209], v[0:3]
	s_waitcnt vmcnt(0)
	ds_write_b128 v171, v[148:151] offset:57344
	s_setprio 0
	s_cmp_gt_u32 s1, 13
	s_cbranch_scc1 .Lmy_t14_skip_2
	s_waitcnt vmcnt(1)
	v_lshl_add_u64 v[144:145], v[160:161], 0, s[6:7]
	v_add_co_u32_e32 v120, vcc, 0x5770000, v144
	v_lshl_add_u64 v[146:147], v[162:163], 0, s[6:7]
	s_nop 0
	v_addc_co_u32_e32 v121, vcc, 0, v145, vcc
	v_add_co_u32_e32 v124, vcc, 0x858000, v146
	s_nop 1
	v_addc_co_u32_e32 v125, vcc, 0, v147, vcc
	v_add_co_u32_e32 v128, vcc, 0x5790000, v144
	global_load_dwordx4 v[120:123], v[120:121], off offset:256
	s_nop 0
	global_load_dwordx4 v[124:127], v[124:125], off offset:256
	v_addc_co_u32_e32 v129, vcc, 0, v145, vcc
	v_add_co_u32_e32 v132, vcc, 0x878000, v146
	s_nop 1
	v_addc_co_u32_e32 v133, vcc, 0, v147, vcc
	v_add_co_u32_e32 v136, vcc, 0x57b0000, v144
	global_load_dwordx4 v[128:131], v[128:129], off offset:256
	s_nop 0
	global_load_dwordx4 v[132:135], v[132:133], off offset:256
	v_addc_co_u32_e32 v137, vcc, 0, v145, vcc
	v_add_co_u32_e32 v140, vcc, 0x898000, v146
	s_nop 1
	v_addc_co_u32_e32 v141, vcc, 0, v147, vcc
	v_add_co_u32_e32 v144, vcc, 0x57d0000, v144
	global_load_dwordx4 v[136:139], v[136:137], off offset:256
	s_nop 0
	global_load_dwordx4 v[140:143], v[140:141], off offset:256
	v_addc_co_u32_e32 v145, vcc, 0, v145, vcc
	s_waitcnt vmcnt(6)
	v_add_co_u32_e32 v148, vcc, 0x8b8000, v146
	s_nop 1
	v_addc_co_u32_e32 v149, vcc, 0, v147, vcc
	global_load_dwordx4 v[144:147], v[144:145], off offset:256
	s_nop 0
	global_load_dwordx4 v[148:151], v[148:149], off offset:256

; __device__ __forceinline__ int tidx() { int t = threadIdx.x; asm volatile("" : "+v"(t)); return t; }
; __device__ __forceinline__ void gemm_mainloop256(const bh* __restrict__ A, long lda, const bh* __restrict__ B, long ldb, int K,
;                                                  char* lds, f32x4 (&acc)[8][4]) {
;     ...
;   const int tid = tidx(), lane = tid & 63, wid = tid >> 6, wr = wid >> 2, wc = wid & 3, fr = lane & 15, fq = lane >> 4;
;   const int srow = tid >> 3, sch = tid & 7;
;   const bh* Ap = A + (long)srow * lda + sch * 8;
;   const bh* Bp = B + (long)srow * ldb + sch * 8;
;   const int swo = srow * 128 + ((sch ^ (srow & 7)) << 4);
;   bf16x8 ra[4], rb[4];
;   const int nk = K >> 6;
; #pragma unroll
;   for (int i = 0; i < 4; ++i) { ra[i] = *reinterpret_cast<const bf16x8*>(Ap + (long)(64 * i) * lda); rb[i] = *reinterpret_cast<const bf16x8*>(Bp + (long)(64 * i) * ldb); }
; #pragma unroll
;   for (int i = 0; i < 4; ++i) { *reinterpret_cast<bf16x8*>(lds + swo + i * 8192) = ra[i]; *reinterpret_cast<bf16x8*>(lds + T_BYTES + swo + i * 8192) = rb[i]; }
;   __syncthreads();
; template <int OMODE>
; __device__ __forceinline__ void gemm_phase256(const bh* __restrict__ A, long lda, const bh* __restrict__ Bt, long ldb, int M, int ncols, int K,
;                                               void* Cp, long ldc, char* lds) {
;     ...
;   for (int tile = blockIdx.x; tile < tm_n * tn_n; tile += gridDim.x) {
;     const int tn = tile / tm_n, tm = tile - tn * tm_n;
;     f32x4 acc[8][4];
; #pragma unroll
;     for (int m = 0; m < 8; ++m)
; #pragma unroll
;       for (int n = 0; n < 4; ++n) acc[m][n] = f32x4{0.f, 0.f, 0.f, 0.f};
;     gemm_mainloop256(A + (long)tm * 256 * lda, lda, Bt + (long)tn * 256 * ldb, ldb, K, lds, acc);
.LBB0_843:
	s_ashr_i32 s1, s0, 31
	s_lshl_b64 s[10:11], s[0:1], 19
	s_lshr_b32 s1, s1, 26
	s_add_i32 s1, s0, s1
	s_and_b32 s8, s1, 0xffffffc0
	s_sub_i32 s4, s0, s8
	s_ashr_i32 s5, s4, 31
	s_ashr_i32 s2, s1, 6
	s_lshl_b64 s[6:7], s[4:5], 19
	v_mov_b32_e32 v12, v188
	s_add_u32 s14, s40, s6
	s_addc_u32 s15, s41, s7
	v_ashrrev_i32_e32 v0, 3, v12
	s_ashr_i32 s3, s2, 31
	v_ashrrev_i32_e32 v1, 31, v0
	s_lshl_b64 s[6:7], s[2:3], 19
	v_lshlrev_b64 v[2:3], 11, v[0:1]
	v_lshlrev_b32_e32 v1, 4, v12
	s_add_u32 s16, s12, s6
	v_lshl_add_u64 v[4:5], s[14:15], 0, v[2:3]
	v_and_b32_e32 v176, 0x70, v1
	s_addc_u32 s17, s13, s7
	v_lshl_add_u64 v[4:5], v[4:5], 0, v[176:177]
	s_mov_b32 s1, 0x20000
	v_lshl_add_u64 v[6:7], s[16:17], 0, v[2:3]
	v_add_co_u32_e32 v8, vcc, s1, v4
	v_lshl_add_u64 v[6:7], v[6:7], 0, v[176:177]
	s_nop 0
	v_addc_co_u32_e32 v9, vcc, 0, v5, vcc
	v_add_co_u32_e32 v10, vcc, s1, v6
	s_mov_b32 s1, 0x40000
	s_nop 0
	v_addc_co_u32_e32 v11, vcc, 0, v7, vcc
	global_load_dwordx4 v[76:79], v[4:5], off
	global_load_dwordx4 v[80:83], v[6:7], off
	global_load_dwordx4 v[88:91], v[8:9], off
	global_load_dwordx4 v[92:95], v[10:11], off
	v_add_co_u32_e32 v8, vcc, s1, v4
	v_lshrrev_b32_e32 v1, 4, v12
	s_nop 0
	v_addc_co_u32_e32 v9, vcc, 0, v5, vcc
	v_add_co_u32_e32 v10, vcc, s1, v6
	s_mov_b32 s1, 0x60000
	s_nop 0
	v_addc_co_u32_e32 v11, vcc, 0, v7, vcc
	v_add_co_u32_e32 v4, vcc, s1, v4
	global_load_dwordx4 v[100:103], v[8:9], off
	global_load_dwordx4 v[108:111], v[10:11], off
	v_addc_co_u32_e32 v5, vcc, 0, v5, vcc
	global_load_dwordx4 v[116:119], v[4:5], off
	v_add_co_u32_e32 v4, vcc, s1, v6
	v_lshrrev_b32_e32 v6, 1, v12
	s_nop 0
	v_addc_co_u32_e32 v5, vcc, 0, v7, vcc
	global_load_dwordx4 v[120:123], v[4:5], off
	v_and_b32_e32 v4, 15, v12
	v_lshlrev_b32_e32 v7, 7, v12
	v_and_b32_e32 v8, 7, v12
	v_xor_b32_e32 v9, v0, v12
	s_mov_b32 s1, 0x1ffff80
	v_lshlrev_b32_e32 v0, 7, v0
	v_and_or_b32 v4, v6, s1, v4
	v_and_b32_e32 v166, 0x6780, v7
	v_bitop3_b32 v1, v1, v8, 3 bitop3:0x6c
	v_lshlrev_b32_e32 v7, 4, v9
	s_movk_i32 s1, 0x70
	v_lshlrev_b32_e32 v6, 4, v8
	v_lshlrev_b32_e32 v167, 7, v4
	v_lshlrev_b32_e32 v168, 4, v1
	v_and_or_b32 v4, v7, s1, v0
	v_lshl_add_u64 v[0:1], s[10:11], 0, v[2:3]
	s_ashr_i32 s9, s8, 31
	v_or_b32_e32 v0, v0, v6
	s_lshl_b64 s[8:9], s[8:9], 19
	v_add_u32_e32 v170, 32, v4
	v_mov_b32_e32 v4, s9
	v_subrev_co_u32_e32 v0, vcc, s8, v0
	v_bfe_u32 v5, v12, 4, 2
	s_nop 0
	v_subb_co_u32_e32 v1, vcc, v1, v4, vcc
	v_lshl_add_u64 v[160:161], s[28:29], 0, v[0:1]
	v_lshl_add_u64 v[0:1], s[6:7], 0, v[2:3]
	v_readlane_b32 s6, v253, 55
	v_or_b32_e32 v0, v0, v6
	v_readlane_b32 s7, v253, 56
	v_bitop3_b32 v5, v5, v8, 4 bitop3:0x36
	s_mov_b32 s3, 0
	v_lshl_add_u64 v[162:163], s[6:7], 0, v[0:1]
	v_mov_b32_e32 v0, 0
	v_lshlrev_b32_e32 v169, 4, v5
	s_mov_b64 s[6:7], 0
	s_mov_b32 s1, 0
	v_mov_b32_e32 v1, v0
	v_mov_b32_e32 v2, v0
	v_mov_b32_e32 v3, v0
	v_mov_b32_e32 v4, v0
	v_mov_b32_e32 v5, v0
	v_mov_b32_e32 v6, v0
	v_mov_b32_e32 v7, v0
	v_mov_b32_e32 v8, v0
	v_mov_b32_e32 v9, v0
	v_mov_b32_e32 v10, v0
	v_mov_b32_e32 v11, v0
	v_mov_b32_e32 v12, v0
	v_mov_b32_e32 v13, v0
	v_mov_b32_e32 v14, v0
	v_mov_b32_e32 v15, v0
	v_mov_b32_e32 v16, v0
	v_mov_b32_e32 v17, v0
	v_mov_b32_e32 v18, v0
	v_mov_b32_e32 v19, v0
	v_mov_b32_e32 v20, v0
	v_mov_b32_e32 v21, v0
	v_mov_b32_e32 v22, v0
	v_mov_b32_e32 v23, v0
	v_mov_b32_e32 v24, v0
	v_mov_b32_e32 v25, v0
	v_mov_b32_e32 v26, v0
	v_mov_b32_e32 v27, v0
	v_mov_b32_e32 v28, v0
	v_mov_b32_e32 v29, v0
	v_mov_b32_e32 v30, v0
	v_mov_b32_e32 v31, v0
	v_mov_b32_e32 v32, v0
	v_mov_b32_e32 v33, v0
	v_mov_b32_e32 v34, v0
	v_mov_b32_e32 v35, v0
	v_mov_b32_e32 v36, v0
	v_mov_b32_e32 v37, v0
	v_mov_b32_e32 v38, v0
	v_mov_b32_e32 v39, v0
	v_mov_b32_e32 v40, v0
	v_mov_b32_e32 v41, v0
	v_mov_b32_e32 v42, v0
	v_mov_b32_e32 v43, v0
	v_mov_b32_e32 v44, v0
	v_mov_b32_e32 v45, v0
	v_mov_b32_e32 v46, v0
	v_mov_b32_e32 v47, v0
	v_mov_b32_e32 v48, v0
	v_mov_b32_e32 v49, v0
	v_mov_b32_e32 v50, v0
	v_mov_b32_e32 v51, v0
	v_mov_b32_e32 v52, v0
	v_mov_b32_e32 v53, v0
	v_mov_b32_e32 v54, v0
	v_mov_b32_e32 v55, v0
	v_mov_b32_e32 v56, v0
	v_mov_b32_e32 v57, v0
	v_mov_b32_e32 v58, v0
	v_mov_b32_e32 v59, v0
	v_mov_b32_e32 v60, v0
	v_mov_b32_e32 v61, v0
	v_mov_b32_e32 v62, v0
	v_mov_b32_e32 v63, v0
	v_mov_b32_e32 v64, v0
	v_mov_b32_e32 v65, v0
	v_mov_b32_e32 v66, v0
	v_mov_b32_e32 v67, v0
	v_mov_b32_e32 v68, v0
	v_mov_b32_e32 v69, v0
	v_mov_b32_e32 v70, v0
	v_mov_b32_e32 v71, v0
	v_mov_b32_e32 v72, v0
	v_mov_b32_e32 v73, v0
	v_mov_b32_e32 v74, v0
	v_mov_b32_e32 v75, v0
	v_mov_b32_e32 v84, v0
	v_mov_b32_e32 v85, v0
	v_mov_b32_e32 v86, v0
	v_mov_b32_e32 v87, v0
	v_mov_b32_e32 v96, v0
	v_mov_b32_e32 v97, v0
	v_mov_b32_e32 v98, v0
	v_mov_b32_e32 v99, v0
	v_mov_b32_e32 v104, v0
	v_mov_b32_e32 v105, v0
	v_mov_b32_e32 v106, v0
	v_mov_b32_e32 v107, v0
	v_mov_b32_e32 v112, v0
	v_mov_b32_e32 v113, v0
	v_mov_b32_e32 v114, v0
	v_mov_b32_e32 v115, v0
	v_mov_b32_e32 v124, v0
	v_mov_b32_e32 v125, v0
	v_mov_b32_e32 v126, v0
	v_mov_b32_e32 v127, v0
	v_mov_b32_e32 v128, v0
	v_mov_b32_e32 v129, v0
	v_mov_b32_e32 v130, v0
	v_mov_b32_e32 v131, v0
	v_mov_b32_e32 v132, v0
	v_mov_b32_e32 v133, v0
	v_mov_b32_e32 v134, v0
	v_mov_b32_e32 v135, v0
	v_mov_b32_e32 v136, v0
	v_mov_b32_e32 v137, v0
	v_mov_b32_e32 v138, v0
	v_mov_b32_e32 v139, v0
	v_mov_b32_e32 v140, v0
	v_mov_b32_e32 v141, v0
	v_mov_b32_e32 v142, v0
	v_mov_b32_e32 v143, v0
	v_mov_b32_e32 v144, v0
	v_mov_b32_e32 v145, v0
	v_mov_b32_e32 v146, v0
	v_mov_b32_e32 v147, v0
	v_mov_b32_e32 v148, v0
	v_mov_b32_e32 v149, v0
	v_mov_b32_e32 v150, v0
	v_mov_b32_e32 v151, v0
	v_mov_b32_e32 v152, v0
	v_mov_b32_e32 v153, v0
	v_mov_b32_e32 v154, v0
	v_mov_b32_e32 v155, v0
	v_mov_b32_e32 v156, v0
	v_mov_b32_e32 v157, v0
	v_mov_b32_e32 v158, v0
	v_mov_b32_e32 v159, v0
	s_waitcnt vmcnt(7)
; __device__ __forceinline__ void gemm_mainloop256(const bh* __restrict__ A, long lda, const bh* __restrict__ B, long ldb, int K,
;                                                  char* lds, f32x4 (&acc)[8][4]) {
;     ...
; #pragma unroll
;   for (int i = 0; i < 4; ++i) { *reinterpret_cast<bf16x8*>(lds + swo + i * 8192) = ra[i]; *reinterpret_cast<bf16x8*>(lds + T_BYTES + swo + i * 8192) = rb[i]; }
;   __syncthreads();
;   const int a_row = (wr * 128 + fr) * 128, b_row = (wc * 64 + fr) * 128;
;   const int c0 = ((0 + fq) ^ (fr & 7)) << 4, c1 = ((4 + fq) ^ (fr & 7)) << 4;
; #pragma unroll 1
;   for (int kt = 0; kt < nk; ++kt) {
;     const bool more = kt + 1 < nk;
;     if (more) {
; #pragma unroll
;       for (int i = 0; i < 4; ++i) { ra[i] = *reinterpret_cast<const bf16x8*>(Ap + (long)(64 * i) * lda + (kt + 1) * 64); rb[i] = *reinterpret_cast<const bf16x8*>(Bp + (long)(64 * i) * ldb + (kt + 1) * 64); }
;     }
	ds_write_b128 v170, v[76:79]
	s_waitcnt vmcnt(5)
	ds_write_b128 v170, v[88:91] offset:8192
	s_waitcnt vmcnt(3)
	ds_write_b128 v170, v[100:103] offset:16384
	s_waitcnt vmcnt(1)
	ds_write_b128 v170, v[116:119] offset:24576
	ds_write_b128 v170, v[80:83] offset:32768
	ds_write_b128 v170, v[92:95] offset:40960
	ds_write_b128 v170, v[108:111] offset:49152
	s_waitcnt vmcnt(0)
	ds_write_b128 v170, v[120:123] offset:57344
	s_waitcnt lgkmcnt(0)
	s_waitcnt vmcnt(1)
	v_lshl_add_u64 v[116:117], v[160:161], 0, s[6:7]
	v_add_co_u32_e32 v76, vcc, 0x13f70000, v116
	v_lshl_add_u64 v[118:119], v[162:163], 0, s[6:7]
	s_nop 0
	v_addc_co_u32_e32 v77, vcc, 0, v117, vcc
	v_add_co_u32_e32 v80, vcc, 0x1458000, v118
	s_nop 1
	v_addc_co_u32_e32 v81, vcc, 0, v119, vcc
	v_add_co_u32_e32 v88, vcc, 0x13f90000, v116
	global_load_dwordx4 v[76:79], v[76:77], off offset:128
	s_nop 0
	global_load_dwordx4 v[80:83], v[80:81], off offset:128
	v_addc_co_u32_e32 v89, vcc, 0, v117, vcc
	v_add_co_u32_e32 v92, vcc, 0x1478000, v118
	s_nop 1
	v_addc_co_u32_e32 v93, vcc, 0, v119, vcc
	v_add_co_u32_e32 v100, vcc, 0x13fb0000, v116
	global_load_dwordx4 v[88:91], v[88:89], off offset:128
	s_nop 0
	global_load_dwordx4 v[92:95], v[92:93], off offset:128
	v_addc_co_u32_e32 v101, vcc, 0, v117, vcc
	v_add_co_u32_e32 v108, vcc, 0x1498000, v118
	s_nop 1
	v_addc_co_u32_e32 v109, vcc, 0, v119, vcc
	v_add_co_u32_e32 v116, vcc, 0x13fd0000, v116
	global_load_dwordx4 v[100:103], v[100:101], off offset:128
	s_nop 0
	global_load_dwordx4 v[108:111], v[108:109], off offset:128
	v_addc_co_u32_e32 v117, vcc, 0, v117, vcc
	s_waitcnt vmcnt(6)
	v_add_co_u32_e32 v120, vcc, 0x14b8000, v118
	s_nop 1
	v_addc_co_u32_e32 v121, vcc, 0, v119, vcc
	global_load_dwordx4 v[116:119], v[116:117], off offset:128
	s_nop 0
	global_load_dwordx4 v[120:123], v[120:121], off offset:128
	s_barrier
	s_branch .LBB0_845

; #define LDF_A(dst, mh, co) _Pragma("unroll") for (int m = 0; m < 4; ++m) dst[m] = *reinterpret_cast<const bf16x8*>(sa + ((mh) * 4 + m) * 2048 + (co))
; #define LDF_B(dst, co) _Pragma("unroll") for (int n = 0; n < 4; ++n) dst[n] = *reinterpret_cast<const bf16x8*>(sb + n * 2048 + (co))
; #define MMA16(av, bv, mh) do { __builtin_amdgcn_s_setprio(1); _Pragma("unroll") for (int m = 0; m < 4; ++m) _Pragma("unroll") for (int n = 0; n < 4; ++n) \
;       acc[(mh) * 4 + m][n] = mfma16(av[m], bv[n], acc[(mh) * 4 + m][n]); __builtin_amdgcn_s_setprio(0); } while (0)
; __device__ __forceinline__ void gemm_mainloop256(const bh* __restrict__ A, long lda, const bh* __restrict__ B, long ldb, int K,
;                                                  char* lds, f32x4 (&acc)[8][4]) {
;     ...
;     const char* sa = lds + (kt & 1) * STAGE + a_row;
;     const char* sb = lds + (kt & 1) * STAGE + T_BYTES + b_row;
;     bf16x8 b0[4], a0[4], a1[4];
;     ...
;     LDF_B(b0, c0); LDF_A(a0, 0, c0);
;     LDF_A(a1, 1, c0);
;     MMA16(a0, b0, 0);
;     LDF_A(a0, 0, c1);
;     MMA16(a1, b0, 1);
;     LDF_B(b0, c1); LDF_A(a1, 1, c1);
;     MMA16(a0, b0, 0);
;     MMA16(a1, b0, 1);
.LBB0_847:
	s_setprio 1
	s_waitcnt lgkmcnt(7)
	v_mfma_f32_16x16x32_bf16 v[156:159], v[210:213], v[172:175], v[156:159]
	v_mfma_f32_16x16x32_bf16 v[152:155], v[210:213], v[182:185], v[152:155]
	v_mfma_f32_16x16x32_bf16 v[148:151], v[210:213], v[198:201], v[148:151]
	v_mfma_f32_16x16x32_bf16 v[144:147], v[210:213], v[206:209], v[144:147]
	s_waitcnt lgkmcnt(6)
	v_mfma_f32_16x16x32_bf16 v[140:143], v[214:217], v[172:175], v[140:143]
	v_mfma_f32_16x16x32_bf16 v[136:139], v[214:217], v[182:185], v[136:139]
	v_mfma_f32_16x16x32_bf16 v[132:135], v[214:217], v[198:201], v[132:135]
	v_mfma_f32_16x16x32_bf16 v[128:131], v[214:217], v[206:209], v[128:131]
	s_waitcnt lgkmcnt(5)
	v_mfma_f32_16x16x32_bf16 v[124:127], v[218:221], v[172:175], v[124:127]
	v_mfma_f32_16x16x32_bf16 v[112:115], v[218:221], v[182:185], v[112:115]
	v_mfma_f32_16x16x32_bf16 v[104:107], v[218:221], v[198:201], v[104:107]
	v_mfma_f32_16x16x32_bf16 v[96:99], v[218:221], v[206:209], v[96:99]
	s_waitcnt lgkmcnt(4)
	v_mfma_f32_16x16x32_bf16 v[84:87], v[222:225], v[172:175], v[84:87]
	v_mfma_f32_16x16x32_bf16 v[72:75], v[222:225], v[182:185], v[72:75]
	v_mfma_f32_16x16x32_bf16 v[68:71], v[222:225], v[198:201], v[68:71]
	v_mfma_f32_16x16x32_bf16 v[64:67], v[222:225], v[206:209], v[64:67]
	s_setprio 0
	v_add_u32_e32 v176, v176, v169
	ds_read_b128 v[210:213], v176
	ds_read_b128 v[214:217], v176 offset:2048
	ds_read_b128 v[218:221], v176 offset:4096
	ds_read_b128 v[222:225], v176 offset:6144
	s_setprio 1
	s_waitcnt lgkmcnt(7)
	v_mfma_f32_16x16x32_bf16 v[60:63], v[226:229], v[172:175], v[60:63]
	v_mfma_f32_16x16x32_bf16 v[56:59], v[226:229], v[182:185], v[56:59]
	v_mfma_f32_16x16x32_bf16 v[52:55], v[226:229], v[198:201], v[52:55]
	v_mfma_f32_16x16x32_bf16 v[48:51], v[226:229], v[206:209], v[48:51]
	s_waitcnt lgkmcnt(6)
	v_mfma_f32_16x16x32_bf16 v[44:47], v[230:233], v[172:175], v[44:47]
	v_mfma_f32_16x16x32_bf16 v[40:43], v[230:233], v[182:185], v[40:43]
	v_mfma_f32_16x16x32_bf16 v[36:39], v[230:233], v[198:201], v[36:39]
	v_mfma_f32_16x16x32_bf16 v[32:35], v[230:233], v[206:209], v[32:35]
	s_waitcnt lgkmcnt(5)
	v_mfma_f32_16x16x32_bf16 v[28:31], v[234:237], v[172:175], v[28:31]
	v_mfma_f32_16x16x32_bf16 v[24:27], v[234:237], v[182:185], v[24:27]
	v_mfma_f32_16x16x32_bf16 v[20:23], v[234:237], v[198:201], v[20:23]
	v_mfma_f32_16x16x32_bf16 v[16:19], v[234:237], v[206:209], v[16:19]
	s_waitcnt lgkmcnt(4)
	v_mfma_f32_16x16x32_bf16 v[12:15], v[238:241], v[172:175], v[12:15]
	v_mfma_f32_16x16x32_bf16 v[8:11], v[238:241], v[182:185], v[8:11]
	v_mfma_f32_16x16x32_bf16 v[4:7], v[238:241], v[198:201], v[4:7]
	v_mfma_f32_16x16x32_bf16 v[0:3], v[238:241], v[206:209], v[0:3]
	s_setprio 0
	v_add_u32_e32 v171, v171, v169
	ds_read_b128 v[172:175], v171 offset:32768
	ds_read_b128 v[182:185], v171 offset:34816
	ds_read_b128 v[198:201], v171 offset:36864
	ds_read_b128 v[206:209], v171 offset:38912
	ds_read_b128 v[226:229], v176 offset:8192
	ds_read_b128 v[230:233], v176 offset:10240
	ds_read_b128 v[234:237], v176 offset:12288
	ds_read_b128 v[238:241], v176 offset:14336
	s_and_b64 vcc, exec, s[8:9]
	s_cbranch_vccnz .Lmy_g256_last_4
; #define LDF_A(dst, mh, co) _Pragma("unroll") for (int m = 0; m < 4; ++m) dst[m] = *reinterpret_cast<const bf16x8*>(sa + ((mh) * 4 + m) * 2048 + (co))
; #define LDF_B(dst, co) _Pragma("unroll") for (int n = 0; n < 4; ++n) dst[n] = *reinterpret_cast<const bf16x8*>(sb + n * 2048 + (co))
; #define MMA16(av, bv, mh) do { __builtin_amdgcn_s_setprio(1); _Pragma("unroll") for (int m = 0; m < 4; ++m) _Pragma("unroll") for (int n = 0; n < 4; ++n) \
;       acc[(mh) * 4 + m][n] = mfma16(av[m], bv[n], acc[(mh) * 4 + m][n]); __builtin_amdgcn_s_setprio(0); } while (0)
; __device__ __forceinline__ void gemm_mainloop256(const bh* __restrict__ A, long lda, const bh* __restrict__ B, long ldb, int K,
;                                                  char* lds, f32x4 (&acc)[8][4]) {
;     ...
;     if (more) {
; #pragma unroll
;       for (int i = 0; i < 4; ++i) { ra[i] = *reinterpret_cast<const bf16x8*>(Ap + (long)(64 * i) * lda + (kt + 1) * 64); rb[i] = *reinterpret_cast<const bf16x8*>(Bp + (long)(64 * i) * ldb + (kt + 1) * 64); }
;     }
;     ...
;     MMA16(a1, b0, 1);
;     LDF_B(b0, c1); LDF_A(a1, 1, c1);
;     MMA16(a0, b0, 0);
;     MMA16(a1, b0, 1);
;     ...
;     if (more) {
;       char* wb = lds + ((kt + 1) & 1) * STAGE;
; #pragma unroll
;       for (int i = 0; i < 4; ++i) { *reinterpret_cast<bf16x8*>(wb + swo + i * 8192) = ra[i]; *reinterpret_cast<bf16x8*>(wb + T_BYTES + swo + i * 8192) = rb[i]; }
;     }
;     __syncthreads();
	s_add_i32 s5, s3, 0x10000
	s_and_b32 s3, s5, 0x10000
	v_add_u32_e32 v171, s3, v170
	s_setprio 1
	s_waitcnt lgkmcnt(7)
	v_mfma_f32_16x16x32_bf16 v[156:159], v[210:213], v[172:175], v[156:159]
	s_waitcnt lgkmcnt(6)
	v_mfma_f32_16x16x32_bf16 v[152:155], v[210:213], v[182:185], v[152:155]
	s_waitcnt lgkmcnt(5)
	v_mfma_f32_16x16x32_bf16 v[148:151], v[210:213], v[198:201], v[148:151]
	s_waitcnt lgkmcnt(4)
	v_mfma_f32_16x16x32_bf16 v[144:147], v[210:213], v[206:209], v[144:147]
	s_waitcnt vmcnt(7)
	ds_write_b128 v171, v[76:79]
	v_mfma_f32_16x16x32_bf16 v[140:143], v[214:217], v[172:175], v[140:143]
	v_mfma_f32_16x16x32_bf16 v[136:139], v[214:217], v[182:185], v[136:139]
	v_mfma_f32_16x16x32_bf16 v[132:135], v[214:217], v[198:201], v[132:135]
	v_mfma_f32_16x16x32_bf16 v[128:131], v[214:217], v[206:209], v[128:131]
	s_waitcnt vmcnt(6)
	ds_write_b128 v171, v[80:83] offset:32768
	v_mfma_f32_16x16x32_bf16 v[124:127], v[218:221], v[172:175], v[124:127]
	v_mfma_f32_16x16x32_bf16 v[112:115], v[218:221], v[182:185], v[112:115]
	v_mfma_f32_16x16x32_bf16 v[104:107], v[218:221], v[198:201], v[104:107]
	v_mfma_f32_16x16x32_bf16 v[96:99], v[218:221], v[206:209], v[96:99]
	s_waitcnt vmcnt(5)
	ds_write_b128 v171, v[88:91] offset:8192
	v_mfma_f32_16x16x32_bf16 v[84:87], v[222:225], v[172:175], v[84:87]
	v_mfma_f32_16x16x32_bf16 v[72:75], v[222:225], v[182:185], v[72:75]
	v_mfma_f32_16x16x32_bf16 v[68:71], v[222:225], v[198:201], v[68:71]
	v_mfma_f32_16x16x32_bf16 v[64:67], v[222:225], v[206:209], v[64:67]
	s_waitcnt vmcnt(4)
	ds_write_b128 v171, v[92:95] offset:40960
	s_waitcnt lgkmcnt(7)
	v_mfma_f32_16x16x32_bf16 v[60:63], v[226:229], v[172:175], v[60:63]
	v_mfma_f32_16x16x32_bf16 v[56:59], v[226:229], v[182:185], v[56:59]
	v_mfma_f32_16x16x32_bf16 v[52:55], v[226:229], v[198:201], v[52:55]
	v_mfma_f32_16x16x32_bf16 v[48:51], v[226:229], v[206:209], v[48:51]
	s_waitcnt vmcnt(3)
	ds_write_b128 v171, v[100:103] offset:16384
	s_waitcnt lgkmcnt(7)
	v_mfma_f32_16x16x32_bf16 v[44:47], v[230:233], v[172:175], v[44:47]
	v_mfma_f32_16x16x32_bf16 v[40:43], v[230:233], v[182:185], v[40:43]
	v_mfma_f32_16x16x32_bf16 v[36:39], v[230:233], v[198:201], v[36:39]
	v_mfma_f32_16x16x32_bf16 v[32:35], v[230:233], v[206:209], v[32:35]
	s_waitcnt vmcnt(2)
	ds_write_b128 v171, v[108:111] offset:49152
	s_waitcnt lgkmcnt(7)
	v_mfma_f32_16x16x32_bf16 v[28:31], v[234:237], v[172:175], v[28:31]
	v_mfma_f32_16x16x32_bf16 v[24:27], v[234:237], v[182:185], v[24:27]
	v_mfma_f32_16x16x32_bf16 v[20:23], v[234:237], v[198:201], v[20:23]
	v_mfma_f32_16x16x32_bf16 v[16:19], v[234:237], v[206:209], v[16:19]
	s_waitcnt vmcnt(1)
	ds_write_b128 v171, v[116:119] offset:24576
	s_waitcnt lgkmcnt(7)
	v_mfma_f32_16x16x32_bf16 v[12:15], v[238:241], v[172:175], v[12:15]
	v_mfma_f32_16x16x32_bf16 v[8:11], v[238:241], v[182:185], v[8:11]
	v_mfma_f32_16x16x32_bf16 v[4:7], v[238:241], v[198:201], v[4:7]
	v_mfma_f32_16x16x32_bf16 v[0:3], v[238:241], v[206:209], v[0:3]
	s_waitcnt vmcnt(0)
	ds_write_b128 v171, v[120:123] offset:57344
	s_setprio 0
	s_cmp_gt_u32 s1, 13
	s_cbranch_scc1 .Lmy_t14_skip_3
	s_waitcnt vmcnt(1)
	v_lshl_add_u64 v[116:117], v[160:161], 0, s[6:7]
	v_add_co_u32_e32 v76, vcc, 0x13f70000, v116
	v_lshl_add_u64 v[118:119], v[162:163], 0, s[6:7]
	s_nop 0
	v_addc_co_u32_e32 v77, vcc, 0, v117, vcc
	v_add_co_u32_e32 v80, vcc, 0x1458000, v118
	s_nop 1
	v_addc_co_u32_e32 v81, vcc, 0, v119, vcc
	v_add_co_u32_e32 v88, vcc, 0x13f90000, v116
	global_load_dwordx4 v[76:79], v[76:77], off offset:256
	s_nop 0
	global_load_dwordx4 v[80:83], v[80:81], off offset:256
	v_addc_co_u32_e32 v89, vcc, 0, v117, vcc
	v_add_co_u32_e32 v92, vcc, 0x1478000, v118
	s_nop 1
	v_addc_co_u32_e32 v93, vcc, 0, v119, vcc
	v_add_co_u32_e32 v100, vcc, 0x13fb0000, v116
	global_load_dwordx4 v[88:91], v[88:89], off offset:256
	s_nop 0
	global_load_dwordx4 v[92:95], v[92:93], off offset:256
	v_addc_co_u32_e32 v101, vcc, 0, v117, vcc
	v_add_co_u32_e32 v108, vcc, 0x1498000, v118
	s_nop 1
	v_addc_co_u32_e32 v109, vcc, 0, v119, vcc
	v_add_co_u32_e32 v116, vcc, 0x13fd0000, v116
	global_load_dwordx4 v[100:103], v[100:101], off offset:256
	s_nop 0
	global_load_dwordx4 v[108:111], v[108:109], off offset:256
	v_addc_co_u32_e32 v117, vcc, 0, v117, vcc
	s_waitcnt vmcnt(6)
	v_add_co_u32_e32 v120, vcc, 0x14b8000, v118
	s_nop 1
	v_addc_co_u32_e32 v121, vcc, 0, v119, vcc
	global_load_dwordx4 v[116:119], v[116:117], off offset:256
	s_nop 0
	global_load_dwordx4 v[120:123], v[120:121], off offset:256

; __device__ __forceinline__ int tidx() { int t = threadIdx.x; asm volatile("" : "+v"(t)); return t; }
; __device__ __forceinline__ void gemm_mainloop256(const bh* __restrict__ A, long lda, const bh* __restrict__ B, long ldb, int K,
;                                                  char* lds, f32x4 (&acc)[8][4]) {
;     ...
;   const int tid = tidx(), lane = tid & 63, wid = tid >> 6, wr = wid >> 2, wc = wid & 3, fr = lane & 15, fq = lane >> 4;
;   const int srow = tid >> 3, sch = tid & 7;
;   const bh* Ap = A + (long)srow * lda + sch * 8;
;   const bh* Bp = B + (long)srow * ldb + sch * 8;
;   const int swo = srow * 128 + ((sch ^ (srow & 7)) << 4);
;   bf16x8 ra[4], rb[4];
;   const int nk = K >> 6;
; #pragma unroll
;   for (int i = 0; i < 4; ++i) { ra[i] = *reinterpret_cast<const bf16x8*>(Ap + (long)(64 * i) * lda); rb[i] = *reinterpret_cast<const bf16x8*>(Bp + (long)(64 * i) * ldb); }
; #pragma unroll
;   for (int i = 0; i < 4; ++i) { *reinterpret_cast<bf16x8*>(lds + swo + i * 8192) = ra[i]; *reinterpret_cast<bf16x8*>(lds + T_BYTES + swo + i * 8192) = rb[i]; }
;   __syncthreads();
; template <int OMODE>
; __device__ __forceinline__ void gemm_phase256(const bh* __restrict__ A, long lda, const bh* __restrict__ Bt, long ldb, int M, int ncols, int K,
;                                               void* Cp, long ldc, char* lds) {
;     ...
;   for (int tile = blockIdx.x; tile < tm_n * tn_n; tile += gridDim.x) {
;     const int tn = tile / tm_n, tm = tile - tn * tm_n;
;     f32x4 acc[8][4];
; #pragma unroll
;     for (int m = 0; m < 8; ++m)
; #pragma unroll
;       for (int n = 0; n < 4; ++n) acc[m][n] = f32x4{0.f, 0.f, 0.f, 0.f};
;     gemm_mainloop256(A + (long)tm * 256 * lda, lda, Bt + (long)tn * 256 * ldb, ldb, K, lds, acc);
.LBB0_1031:
	s_ashr_i32 s1, s0, 31
	s_lshl_b64 s[14:15], s[0:1], 18
	s_lshr_b32 s1, s1, 26
	s_add_i32 s1, s0, s1
	s_and_b32 s12, s1, 0xffffffc0
	s_sub_i32 s4, s0, s12
	s_ashr_i32 s5, s4, 31
	s_ashr_i32 s2, s1, 6
	s_lshl_b64 s[10:11], s[4:5], 18
	v_mov_b32_e32 v12, v188
	s_add_u32 s18, s44, s10
	s_addc_u32 s19, s45, s11
	v_ashrrev_i32_e32 v0, 3, v12
	s_ashr_i32 s3, s2, 31
	v_ashrrev_i32_e32 v1, 31, v0
	s_lshl_b64 s[10:11], s[2:3], 18
	v_lshlrev_b64 v[2:3], 10, v[0:1]
	v_lshlrev_b32_e32 v1, 4, v12
	s_add_u32 s20, s16, s10
	v_lshl_add_u64 v[4:5], s[18:19], 0, v[2:3]
	v_and_b32_e32 v176, 0x70, v1
	s_addc_u32 s21, s17, s11
	v_lshl_add_u64 v[4:5], v[4:5], 0, v[176:177]
	s_mov_b32 s1, 0x10000
	v_lshl_add_u64 v[6:7], s[20:21], 0, v[2:3]
	v_add_co_u32_e32 v8, vcc, s1, v4
	v_lshl_add_u64 v[6:7], v[6:7], 0, v[176:177]
	s_nop 0
	v_addc_co_u32_e32 v9, vcc, 0, v5, vcc
	v_add_co_u32_e32 v10, vcc, s1, v6
	s_mov_b32 s1, 0x20000
	s_nop 0
	v_addc_co_u32_e32 v11, vcc, 0, v7, vcc
	global_load_dwordx4 v[76:79], v[4:5], off
	global_load_dwordx4 v[80:83], v[6:7], off
	global_load_dwordx4 v[88:91], v[8:9], off
	global_load_dwordx4 v[92:95], v[10:11], off
	v_add_co_u32_e32 v8, vcc, s1, v4
	v_lshrrev_b32_e32 v1, 4, v12
	s_nop 0
	v_addc_co_u32_e32 v9, vcc, 0, v5, vcc
	v_add_co_u32_e32 v10, vcc, s1, v6
	s_mov_b32 s1, 0x30000
	s_nop 0
	v_addc_co_u32_e32 v11, vcc, 0, v7, vcc
	v_add_co_u32_e32 v4, vcc, s1, v4
	global_load_dwordx4 v[100:103], v[8:9], off
	global_load_dwordx4 v[108:111], v[10:11], off
	v_addc_co_u32_e32 v5, vcc, 0, v5, vcc
	global_load_dwordx4 v[116:119], v[4:5], off
	v_add_co_u32_e32 v4, vcc, s1, v6
	v_lshrrev_b32_e32 v6, 1, v12
	s_nop 0
	v_addc_co_u32_e32 v5, vcc, 0, v7, vcc
	global_load_dwordx4 v[120:123], v[4:5], off
	v_and_b32_e32 v4, 15, v12
	v_lshlrev_b32_e32 v7, 7, v12
	v_and_b32_e32 v8, 7, v12
	v_xor_b32_e32 v9, v0, v12
	s_mov_b32 s1, 0x1ffff80
	v_lshlrev_b32_e32 v0, 7, v0
	v_and_or_b32 v4, v6, s1, v4
	v_and_b32_e32 v166, 0x6780, v7
	v_bitop3_b32 v1, v1, v8, 3 bitop3:0x6c
	v_lshlrev_b32_e32 v7, 4, v9
	s_movk_i32 s1, 0x70
	v_lshlrev_b32_e32 v6, 4, v8
	v_lshlrev_b32_e32 v167, 7, v4
	v_lshlrev_b32_e32 v168, 4, v1
	v_and_or_b32 v4, v7, s1, v0
	v_lshl_add_u64 v[0:1], s[14:15], 0, v[2:3]
	s_ashr_i32 s13, s12, 31
	v_or_b32_e32 v0, v0, v6
	s_lshl_b64 s[12:13], s[12:13], 18
	v_add_u32_e32 v170, 32, v4
	v_mov_b32_e32 v4, s13
	v_subrev_co_u32_e32 v0, vcc, s12, v0
	v_bfe_u32 v5, v12, 4, 2
	s_nop 0
	v_subb_co_u32_e32 v1, vcc, v1, v4, vcc
	v_lshl_add_u64 v[160:161], s[28:29], 0, v[0:1]
	v_lshl_add_u64 v[0:1], s[10:11], 0, v[2:3]
	v_readlane_b32 s10, v253, 55
	v_or_b32_e32 v0, v0, v6
	v_readlane_b32 s11, v253, 56
	v_bitop3_b32 v5, v5, v8, 4 bitop3:0x36
	s_mov_b32 s3, 0
	v_lshl_add_u64 v[162:163], s[10:11], 0, v[0:1]
	v_mov_b32_e32 v0, 0
	v_lshlrev_b32_e32 v169, 4, v5
	s_mov_b64 s[10:11], 0
	s_mov_b32 s1, 0
	v_mov_b32_e32 v1, v0
	v_mov_b32_e32 v2, v0
	v_mov_b32_e32 v3, v0
	v_mov_b32_e32 v4, v0
	v_mov_b32_e32 v5, v0
	v_mov_b32_e32 v6, v0
	v_mov_b32_e32 v7, v0
	v_mov_b32_e32 v8, v0
	v_mov_b32_e32 v9, v0
	v_mov_b32_e32 v10, v0
	v_mov_b32_e32 v11, v0
	v_mov_b32_e32 v12, v0
	v_mov_b32_e32 v13, v0
	v_mov_b32_e32 v14, v0
	v_mov_b32_e32 v15, v0
	v_mov_b32_e32 v16, v0
	v_mov_b32_e32 v17, v0
	v_mov_b32_e32 v18, v0
	v_mov_b32_e32 v19, v0
	v_mov_b32_e32 v20, v0
	v_mov_b32_e32 v21, v0
	v_mov_b32_e32 v22, v0
	v_mov_b32_e32 v23, v0
	v_mov_b32_e32 v24, v0
	v_mov_b32_e32 v25, v0
	v_mov_b32_e32 v26, v0
	v_mov_b32_e32 v27, v0
	v_mov_b32_e32 v28, v0
	v_mov_b32_e32 v29, v0
	v_mov_b32_e32 v30, v0
	v_mov_b32_e32 v31, v0
	v_mov_b32_e32 v32, v0
	v_mov_b32_e32 v33, v0
	v_mov_b32_e32 v34, v0
	v_mov_b32_e32 v35, v0
	s_waitcnt vmcnt(41)
	v_mov_b32_e32 v36, v0
	v_mov_b32_e32 v37, v0
	v_mov_b32_e32 v38, v0
	v_mov_b32_e32 v39, v0
	s_waitcnt vmcnt(40)
; __device__ __forceinline__ void gemm_mainloop256(const bh* __restrict__ A, long lda, const bh* __restrict__ B, long ldb, int K,
;                                                  char* lds, f32x4 (&acc)[8][4]) {
;     ...
; #pragma unroll
;   for (int i = 0; i < 4; ++i) { *reinterpret_cast<bf16x8*>(lds + swo + i * 8192) = ra[i]; *reinterpret_cast<bf16x8*>(lds + T_BYTES + swo + i * 8192) = rb[i]; }
;   __syncthreads();
;   const int a_row = (wr * 128 + fr) * 128, b_row = (wc * 64 + fr) * 128;
;   const int c0 = ((0 + fq) ^ (fr & 7)) << 4, c1 = ((4 + fq) ^ (fr & 7)) << 4;
; #pragma unroll 1
;   for (int kt = 0; kt < nk; ++kt) {
;     const bool more = kt + 1 < nk;
;     if (more) {
; #pragma unroll
;       for (int i = 0; i < 4; ++i) { ra[i] = *reinterpret_cast<const bf16x8*>(Ap + (long)(64 * i) * lda + (kt + 1) * 64); rb[i] = *reinterpret_cast<const bf16x8*>(Bp + (long)(64 * i) * ldb + (kt + 1) * 64); }
;     }
; template <int OMODE>
; __device__ __forceinline__ void gemm_phase256(const bh* __restrict__ A, long lda, const bh* __restrict__ Bt, long ldb, int M, int ncols, int K,
;                                               void* Cp, long ldc, char* lds) {
;     ...
; #pragma unroll
;     for (int m = 0; m < 8; ++m)
; #pragma unroll
;       for (int n = 0; n < 4; ++n) acc[m][n] = f32x4{0.f, 0.f, 0.f, 0.f};
	v_mov_b32_e32 v40, v0
	v_mov_b32_e32 v41, v0
	v_mov_b32_e32 v42, v0
	v_mov_b32_e32 v43, v0
	v_mov_b32_e32 v44, v0
	v_mov_b32_e32 v45, v0
	v_mov_b32_e32 v46, v0
	v_mov_b32_e32 v47, v0
	v_mov_b32_e32 v48, v0
	v_mov_b32_e32 v49, v0
	v_mov_b32_e32 v50, v0
	v_mov_b32_e32 v51, v0
	v_mov_b32_e32 v52, v0
	v_mov_b32_e32 v53, v0
	v_mov_b32_e32 v54, v0
	v_mov_b32_e32 v55, v0
	v_mov_b32_e32 v56, v0
	v_mov_b32_e32 v57, v0
	v_mov_b32_e32 v58, v0
	v_mov_b32_e32 v59, v0
	v_mov_b32_e32 v60, v0
	v_mov_b32_e32 v61, v0
	v_mov_b32_e32 v62, v0
	v_mov_b32_e32 v63, v0
	v_mov_b32_e32 v64, v0
	v_mov_b32_e32 v65, v0
	v_mov_b32_e32 v66, v0
	v_mov_b32_e32 v67, v0
	v_mov_b32_e32 v68, v0
	v_mov_b32_e32 v69, v0
	v_mov_b32_e32 v70, v0
	v_mov_b32_e32 v71, v0
	v_mov_b32_e32 v72, v0
	v_mov_b32_e32 v73, v0
	v_mov_b32_e32 v74, v0
	v_mov_b32_e32 v75, v0
	v_mov_b32_e32 v84, v0
	v_mov_b32_e32 v85, v0
	v_mov_b32_e32 v86, v0
	v_mov_b32_e32 v87, v0
	v_mov_b32_e32 v96, v0
	v_mov_b32_e32 v97, v0
	v_mov_b32_e32 v98, v0
	v_mov_b32_e32 v99, v0
	v_mov_b32_e32 v104, v0
	v_mov_b32_e32 v105, v0
	v_mov_b32_e32 v106, v0
	v_mov_b32_e32 v107, v0
	v_mov_b32_e32 v112, v0
	v_mov_b32_e32 v113, v0
	v_mov_b32_e32 v114, v0
	v_mov_b32_e32 v115, v0
	v_mov_b32_e32 v124, v0
	v_mov_b32_e32 v125, v0
	v_mov_b32_e32 v126, v0
	v_mov_b32_e32 v127, v0
	v_mov_b32_e32 v128, v0
	v_mov_b32_e32 v129, v0
	v_mov_b32_e32 v130, v0
	v_mov_b32_e32 v131, v0
	v_mov_b32_e32 v132, v0
	v_mov_b32_e32 v133, v0
	v_mov_b32_e32 v134, v0
	v_mov_b32_e32 v135, v0
	v_mov_b32_e32 v136, v0
	v_mov_b32_e32 v137, v0
	v_mov_b32_e32 v138, v0
	v_mov_b32_e32 v139, v0
	v_mov_b32_e32 v140, v0
	v_mov_b32_e32 v141, v0
	v_mov_b32_e32 v142, v0
	v_mov_b32_e32 v143, v0
	v_mov_b32_e32 v144, v0
	v_mov_b32_e32 v145, v0
	v_mov_b32_e32 v146, v0
	v_mov_b32_e32 v147, v0
	v_mov_b32_e32 v148, v0
	v_mov_b32_e32 v149, v0
	v_mov_b32_e32 v150, v0
	v_mov_b32_e32 v151, v0
	v_mov_b32_e32 v152, v0
	v_mov_b32_e32 v153, v0
	v_mov_b32_e32 v154, v0
	v_mov_b32_e32 v155, v0
	v_mov_b32_e32 v156, v0
	v_mov_b32_e32 v157, v0
	v_mov_b32_e32 v158, v0
	v_mov_b32_e32 v159, v0
	s_waitcnt vmcnt(7)
	ds_write_b128 v170, v[76:79]
	s_waitcnt vmcnt(5)
	ds_write_b128 v170, v[88:91] offset:8192
	s_waitcnt vmcnt(3)
	ds_write_b128 v170, v[100:103] offset:16384
	s_waitcnt vmcnt(1)
	ds_write_b128 v170, v[116:119] offset:24576
	ds_write_b128 v170, v[80:83] offset:32768
	ds_write_b128 v170, v[92:95] offset:40960
	ds_write_b128 v170, v[108:111] offset:49152
	s_waitcnt vmcnt(0)
	ds_write_b128 v170, v[120:123] offset:57344
	s_waitcnt lgkmcnt(0)
	s_waitcnt vmcnt(1)
	v_lshl_add_u64 v[116:117], v[160:161], 0, s[10:11]
	v_add_co_u32_e32 v76, vcc, 0x16f70000, v116
	v_lshl_add_u64 v[118:119], v[162:163], 0, s[10:11]
	s_nop 0
	v_addc_co_u32_e32 v77, vcc, 0, v117, vcc
	v_add_co_u32_e32 v80, vcc, 0x1a38000, v118
	s_nop 1
	v_addc_co_u32_e32 v81, vcc, 0, v119, vcc
	v_add_co_u32_e32 v88, vcc, 0x16f80000, v116
	global_load_dwordx4 v[76:79], v[76:77], off offset:128
	s_nop 0
	global_load_dwordx4 v[80:83], v[80:81], off offset:128
	v_addc_co_u32_e32 v89, vcc, 0, v117, vcc
	v_add_co_u32_e32 v92, vcc, 0x1a48000, v118
	s_nop 1
	v_addc_co_u32_e32 v93, vcc, 0, v119, vcc
	v_add_co_u32_e32 v100, vcc, 0x16f90000, v116
	global_load_dwordx4 v[88:91], v[88:89], off offset:128
	s_nop 0
	global_load_dwordx4 v[92:95], v[92:93], off offset:128
	v_addc_co_u32_e32 v101, vcc, 0, v117, vcc
	v_add_co_u32_e32 v108, vcc, 0x1a58000, v118
	s_nop 1
	v_addc_co_u32_e32 v109, vcc, 0, v119, vcc
	v_add_co_u32_e32 v116, vcc, 0x16fa0000, v116
	global_load_dwordx4 v[100:103], v[100:101], off offset:128
	s_nop 0
	global_load_dwordx4 v[108:111], v[108:109], off offset:128
	v_addc_co_u32_e32 v117, vcc, 0, v117, vcc
	s_waitcnt vmcnt(6)
	v_add_co_u32_e32 v120, vcc, 0x1a68000, v118
	s_nop 1
	v_addc_co_u32_e32 v121, vcc, 0, v119, vcc
	global_load_dwordx4 v[116:119], v[116:117], off offset:128
	s_nop 0
	global_load_dwordx4 v[120:123], v[120:121], off offset:128
	s_barrier
	s_branch .LBB0_1033

; #define LDF_A(dst, mh, co) _Pragma("unroll") for (int m = 0; m < 4; ++m) dst[m] = *reinterpret_cast<const bf16x8*>(sa + ((mh) * 4 + m) * 2048 + (co))
; #define LDF_B(dst, co) _Pragma("unroll") for (int n = 0; n < 4; ++n) dst[n] = *reinterpret_cast<const bf16x8*>(sb + n * 2048 + (co))
; #define MMA16(av, bv, mh) do { __builtin_amdgcn_s_setprio(1); _Pragma("unroll") for (int m = 0; m < 4; ++m) _Pragma("unroll") for (int n = 0; n < 4; ++n) \
;       acc[(mh) * 4 + m][n] = mfma16(av[m], bv[n], acc[(mh) * 4 + m][n]); __builtin_amdgcn_s_setprio(0); } while (0)
; __device__ __forceinline__ void gemm_mainloop256(const bh* __restrict__ A, long lda, const bh* __restrict__ B, long ldb, int K,
;                                                  char* lds, f32x4 (&acc)[8][4]) {
;     ...
;   for (int kt = 0; kt < nk; ++kt) {
;     const bool more = kt + 1 < nk;
;     if (more) {
; #pragma unroll
;       for (int i = 0; i < 4; ++i) { ra[i] = *reinterpret_cast<const bf16x8*>(Ap + (long)(64 * i) * lda + (kt + 1) * 64); rb[i] = *reinterpret_cast<const bf16x8*>(Bp + (long)(64 * i) * ldb + (kt + 1) * 64); }
;     }
;     const char* sa = lds + (kt & 1) * STAGE + a_row;
;     const char* sb = lds + (kt & 1) * STAGE + T_BYTES + b_row;
;     bf16x8 b0[4], a0[4], a1[4];
;     ...
;     LDF_B(b0, c0); LDF_A(a0, 0, c0);
;     LDF_A(a1, 1, c0);
;     MMA16(a0, b0, 0);
;     LDF_A(a0, 0, c1);
;     MMA16(a1, b0, 1);
;     LDF_B(b0, c1); LDF_A(a1, 1, c1);
;     MMA16(a0, b0, 0);
;     MMA16(a1, b0, 1);
.LBB0_1033:
	s_cmp_gt_u32 s1, 6
	s_cselect_b64 s[12:13], -1, 0
	s_and_b32 s5, s3, 0x10000
	s_add_i32 s5, s5, 32
	v_add_u32_e32 v171, s5, v166
	v_add_u32_e32 v176, v171, v168
	ds_read_b128 v[172:175], v176 offset:32768
	ds_read_b128 v[182:185], v176 offset:34816
	ds_read_b128 v[198:201], v176 offset:36864
	ds_read_b128 v[206:209], v176 offset:38912
	v_add_u32_e32 v176, s5, v167
	v_add_u32_e32 v179, v176, v168
	ds_read_b128 v[210:213], v179
	ds_read_b128 v[214:217], v179 offset:2048
	ds_read_b128 v[218:221], v179 offset:4096
	ds_read_b128 v[222:225], v179 offset:6144
	ds_read_b128 v[226:229], v179 offset:8192
	ds_read_b128 v[230:233], v179 offset:10240
	ds_read_b128 v[234:237], v179 offset:12288
	ds_read_b128 v[238:241], v179 offset:14336
.LBB0_1035:
	s_setprio 1
	s_waitcnt lgkmcnt(7)
	v_mfma_f32_16x16x32_bf16 v[156:159], v[210:213], v[172:175], v[156:159]
	v_mfma_f32_16x16x32_bf16 v[152:155], v[210:213], v[182:185], v[152:155]
	v_mfma_f32_16x16x32_bf16 v[148:151], v[210:213], v[198:201], v[148:151]
	v_mfma_f32_16x16x32_bf16 v[144:147], v[210:213], v[206:209], v[144:147]
	s_waitcnt lgkmcnt(6)
	v_mfma_f32_16x16x32_bf16 v[140:143], v[214:217], v[172:175], v[140:143]
	v_mfma_f32_16x16x32_bf16 v[136:139], v[214:217], v[182:185], v[136:139]
	v_mfma_f32_16x16x32_bf16 v[132:135], v[214:217], v[198:201], v[132:135]
	v_mfma_f32_16x16x32_bf16 v[128:131], v[214:217], v[206:209], v[128:131]
	s_waitcnt lgkmcnt(5)
	v_mfma_f32_16x16x32_bf16 v[124:127], v[218:221], v[172:175], v[124:127]
	v_mfma_f32_16x16x32_bf16 v[112:115], v[218:221], v[182:185], v[112:115]
	v_mfma_f32_16x16x32_bf16 v[104:107], v[218:221], v[198:201], v[104:107]
	v_mfma_f32_16x16x32_bf16 v[96:99], v[218:221], v[206:209], v[96:99]
	s_waitcnt lgkmcnt(4)
	v_mfma_f32_16x16x32_bf16 v[84:87], v[222:225], v[172:175], v[84:87]
	v_mfma_f32_16x16x32_bf16 v[72:75], v[222:225], v[182:185], v[72:75]
	v_mfma_f32_16x16x32_bf16 v[68:71], v[222:225], v[198:201], v[68:71]
	v_mfma_f32_16x16x32_bf16 v[64:67], v[222:225], v[206:209], v[64:67]
	s_setprio 0
	v_add_u32_e32 v176, v176, v169
	ds_read_b128 v[210:213], v176
	ds_read_b128 v[214:217], v176 offset:2048
	ds_read_b128 v[218:221], v176 offset:4096
	ds_read_b128 v[222:225], v176 offset:6144
	s_setprio 1
	s_waitcnt lgkmcnt(7)
	v_mfma_f32_16x16x32_bf16 v[60:63], v[226:229], v[172:175], v[60:63]
	v_mfma_f32_16x16x32_bf16 v[56:59], v[226:229], v[182:185], v[56:59]
	v_mfma_f32_16x16x32_bf16 v[52:55], v[226:229], v[198:201], v[52:55]
	v_mfma_f32_16x16x32_bf16 v[48:51], v[226:229], v[206:209], v[48:51]
	s_waitcnt lgkmcnt(6)
	v_mfma_f32_16x16x32_bf16 v[44:47], v[230:233], v[172:175], v[44:47]
	v_mfma_f32_16x16x32_bf16 v[40:43], v[230:233], v[182:185], v[40:43]
	v_mfma_f32_16x16x32_bf16 v[36:39], v[230:233], v[198:201], v[36:39]
	v_mfma_f32_16x16x32_bf16 v[32:35], v[230:233], v[206:209], v[32:35]
	s_waitcnt lgkmcnt(5)
	v_mfma_f32_16x16x32_bf16 v[28:31], v[234:237], v[172:175], v[28:31]
	v_mfma_f32_16x16x32_bf16 v[24:27], v[234:237], v[182:185], v[24:27]
	v_mfma_f32_16x16x32_bf16 v[20:23], v[234:237], v[198:201], v[20:23]
	v_mfma_f32_16x16x32_bf16 v[16:19], v[234:237], v[206:209], v[16:19]
	s_waitcnt lgkmcnt(4)
	v_mfma_f32_16x16x32_bf16 v[12:15], v[238:241], v[172:175], v[12:15]
	v_mfma_f32_16x16x32_bf16 v[8:11], v[238:241], v[182:185], v[8:11]
	v_mfma_f32_16x16x32_bf16 v[4:7], v[238:241], v[198:201], v[4:7]
	v_mfma_f32_16x16x32_bf16 v[0:3], v[238:241], v[206:209], v[0:3]
	s_setprio 0
	v_add_u32_e32 v171, v171, v169
	ds_read_b128 v[172:175], v171 offset:32768
	ds_read_b128 v[182:185], v171 offset:34816
	ds_read_b128 v[198:201], v171 offset:36864
	ds_read_b128 v[206:209], v171 offset:38912
	ds_read_b128 v[226:229], v176 offset:8192
	ds_read_b128 v[230:233], v176 offset:10240
	ds_read_b128 v[234:237], v176 offset:12288
	ds_read_b128 v[238:241], v176 offset:14336
	s_and_b64 vcc, exec, s[12:13]
	s_cbranch_vccnz .Lmy_g256_last_3
; #define LDF_A(dst, mh, co) _Pragma("unroll") for (int m = 0; m < 4; ++m) dst[m] = *reinterpret_cast<const bf16x8*>(sa + ((mh) * 4 + m) * 2048 + (co))
; #define LDF_B(dst, co) _Pragma("unroll") for (int n = 0; n < 4; ++n) dst[n] = *reinterpret_cast<const bf16x8*>(sb + n * 2048 + (co))
; #define MMA16(av, bv, mh) do { __builtin_amdgcn_s_setprio(1); _Pragma("unroll") for (int m = 0; m < 4; ++m) _Pragma("unroll") for (int n = 0; n < 4; ++n) \
;       acc[(mh) * 4 + m][n] = mfma16(av[m], bv[n], acc[(mh) * 4 + m][n]); __builtin_amdgcn_s_setprio(0); } while (0)
; __device__ __forceinline__ void gemm_mainloop256(const bh* __restrict__ A, long lda, const bh* __restrict__ B, long ldb, int K,
;                                                  char* lds, f32x4 (&acc)[8][4]) {
;     ...
;     if (more) {
; #pragma unroll
;       for (int i = 0; i < 4; ++i) { ra[i] = *reinterpret_cast<const bf16x8*>(Ap + (long)(64 * i) * lda + (kt + 1) * 64); rb[i] = *reinterpret_cast<const bf16x8*>(Bp + (long)(64 * i) * ldb + (kt + 1) * 64); }
;     }
;     ...
;     MMA16(a1, b0, 1);
;     LDF_B(b0, c1); LDF_A(a1, 1, c1);
;     MMA16(a0, b0, 0);
;     MMA16(a1, b0, 1);
;     ...
;     if (more) {
;       char* wb = lds + ((kt + 1) & 1) * STAGE;
; #pragma unroll
;       for (int i = 0; i < 4; ++i) { *reinterpret_cast<bf16x8*>(wb + swo + i * 8192) = ra[i]; *reinterpret_cast<bf16x8*>(wb + T_BYTES + swo + i * 8192) = rb[i]; }
;     }
;     __syncthreads();
	s_add_i32 s5, s3, 0x10000
	s_and_b32 s3, s5, 0x10000
	v_add_u32_e32 v171, s3, v170
	s_setprio 1
	s_waitcnt lgkmcnt(7)
	v_mfma_f32_16x16x32_bf16 v[156:159], v[210:213], v[172:175], v[156:159]
	s_waitcnt lgkmcnt(6)
	v_mfma_f32_16x16x32_bf16 v[152:155], v[210:213], v[182:185], v[152:155]
	s_waitcnt lgkmcnt(5)
	v_mfma_f32_16x16x32_bf16 v[148:151], v[210:213], v[198:201], v[148:151]
	s_waitcnt lgkmcnt(4)
	v_mfma_f32_16x16x32_bf16 v[144:147], v[210:213], v[206:209], v[144:147]
	s_waitcnt vmcnt(7)
	ds_write_b128 v171, v[76:79]
	v_mfma_f32_16x16x32_bf16 v[140:143], v[214:217], v[172:175], v[140:143]
	v_mfma_f32_16x16x32_bf16 v[136:139], v[214:217], v[182:185], v[136:139]
	v_mfma_f32_16x16x32_bf16 v[132:135], v[214:217], v[198:201], v[132:135]
	v_mfma_f32_16x16x32_bf16 v[128:131], v[214:217], v[206:209], v[128:131]
	s_waitcnt vmcnt(6)
	ds_write_b128 v171, v[80:83] offset:32768
	v_mfma_f32_16x16x32_bf16 v[124:127], v[218:221], v[172:175], v[124:127]
	v_mfma_f32_16x16x32_bf16 v[112:115], v[218:221], v[182:185], v[112:115]
	v_mfma_f32_16x16x32_bf16 v[104:107], v[218:221], v[198:201], v[104:107]
	v_mfma_f32_16x16x32_bf16 v[96:99], v[218:221], v[206:209], v[96:99]
	s_waitcnt vmcnt(5)
	ds_write_b128 v171, v[88:91] offset:8192
	v_mfma_f32_16x16x32_bf16 v[84:87], v[222:225], v[172:175], v[84:87]
	v_mfma_f32_16x16x32_bf16 v[72:75], v[222:225], v[182:185], v[72:75]
	v_mfma_f32_16x16x32_bf16 v[68:71], v[222:225], v[198:201], v[68:71]
	v_mfma_f32_16x16x32_bf16 v[64:67], v[222:225], v[206:209], v[64:67]
	s_waitcnt vmcnt(4)
	ds_write_b128 v171, v[92:95] offset:40960
	s_waitcnt lgkmcnt(7)
	v_mfma_f32_16x16x32_bf16 v[60:63], v[226:229], v[172:175], v[60:63]
	v_mfma_f32_16x16x32_bf16 v[56:59], v[226:229], v[182:185], v[56:59]
	v_mfma_f32_16x16x32_bf16 v[52:55], v[226:229], v[198:201], v[52:55]
	v_mfma_f32_16x16x32_bf16 v[48:51], v[226:229], v[206:209], v[48:51]
	s_waitcnt vmcnt(3)
	ds_write_b128 v171, v[100:103] offset:16384
	s_waitcnt lgkmcnt(7)
	v_mfma_f32_16x16x32_bf16 v[44:47], v[230:233], v[172:175], v[44:47]
	v_mfma_f32_16x16x32_bf16 v[40:43], v[230:233], v[182:185], v[40:43]
	v_mfma_f32_16x16x32_bf16 v[36:39], v[230:233], v[198:201], v[36:39]
	v_mfma_f32_16x16x32_bf16 v[32:35], v[230:233], v[206:209], v[32:35]
	s_waitcnt vmcnt(2)
	ds_write_b128 v171, v[108:111] offset:49152
	s_waitcnt lgkmcnt(7)
	v_mfma_f32_16x16x32_bf16 v[28:31], v[234:237], v[172:175], v[28:31]
	v_mfma_f32_16x16x32_bf16 v[24:27], v[234:237], v[182:185], v[24:27]
	v_mfma_f32_16x16x32_bf16 v[20:23], v[234:237], v[198:201], v[20:23]
	v_mfma_f32_16x16x32_bf16 v[16:19], v[234:237], v[206:209], v[16:19]
	s_waitcnt vmcnt(1)
	ds_write_b128 v171, v[116:119] offset:24576
	s_waitcnt lgkmcnt(7)
	v_mfma_f32_16x16x32_bf16 v[12:15], v[238:241], v[172:175], v[12:15]
	v_mfma_f32_16x16x32_bf16 v[8:11], v[238:241], v[182:185], v[8:11]
	v_mfma_f32_16x16x32_bf16 v[4:7], v[238:241], v[198:201], v[4:7]
	v_mfma_f32_16x16x32_bf16 v[0:3], v[238:241], v[206:209], v[0:3]
	s_waitcnt vmcnt(0)
	ds_write_b128 v171, v[120:123] offset:57344
	s_setprio 0
	s_cmp_gt_u32 s1, 5
	s_cbranch_scc1 .Lmy_t14_skip_4
	s_waitcnt vmcnt(1)
	v_lshl_add_u64 v[116:117], v[160:161], 0, s[10:11]
	v_add_co_u32_e32 v76, vcc, 0x16f70000, v116
	v_lshl_add_u64 v[118:119], v[162:163], 0, s[10:11]
	s_nop 0
	v_addc_co_u32_e32 v77, vcc, 0, v117, vcc
	v_add_co_u32_e32 v80, vcc, 0x1a38000, v118
	s_nop 1
	v_addc_co_u32_e32 v81, vcc, 0, v119, vcc
	v_add_co_u32_e32 v88, vcc, 0x16f80000, v116
	global_load_dwordx4 v[76:79], v[76:77], off offset:256
	s_nop 0
	global_load_dwordx4 v[80:83], v[80:81], off offset:256
	v_addc_co_u32_e32 v89, vcc, 0, v117, vcc
	v_add_co_u32_e32 v92, vcc, 0x1a48000, v118
	s_nop 1
	v_addc_co_u32_e32 v93, vcc, 0, v119, vcc
	v_add_co_u32_e32 v100, vcc, 0x16f90000, v116
	global_load_dwordx4 v[88:91], v[88:89], off offset:256
	s_nop 0
	global_load_dwordx4 v[92:95], v[92:93], off offset:256
	v_addc_co_u32_e32 v101, vcc, 0, v117, vcc
	v_add_co_u32_e32 v108, vcc, 0x1a58000, v118
	s_nop 1
	v_addc_co_u32_e32 v109, vcc, 0, v119, vcc
	v_add_co_u32_e32 v116, vcc, 0x16fa0000, v116
	global_load_dwordx4 v[100:103], v[100:101], off offset:256
	s_nop 0
	global_load_dwordx4 v[108:111], v[108:109], off offset:256
	v_addc_co_u32_e32 v117, vcc, 0, v117, vcc
	s_waitcnt vmcnt(6)
	v_add_co_u32_e32 v120, vcc, 0x1a68000, v118
	s_nop 1
	v_addc_co_u32_e32 v121, vcc, 0, v119, vcc
	global_load_dwordx4 v[116:119], v[116:117], off offset:256
	s_nop 0
	global_load_dwordx4 v[120:123], v[120:121], off offset:256

; __device__ __forceinline__ int tidx() { int t = threadIdx.x; asm volatile("" : "+v"(t)); return t; }
; __device__ __forceinline__ void gemm_mainloop256(const bh* __restrict__ A, long lda, const bh* __restrict__ B, long ldb, int K,
;                                                  char* lds, f32x4 (&acc)[8][4]) {
;     ...
;   const int tid = tidx(), lane = tid & 63, wid = tid >> 6, wr = wid >> 2, wc = wid & 3, fr = lane & 15, fq = lane >> 4;
;   const int srow = tid >> 3, sch = tid & 7;
;   const bh* Ap = A + (long)srow * lda + sch * 8;
;   const bh* Bp = B + (long)srow * ldb + sch * 8;
;   const int swo = srow * 128 + ((sch ^ (srow & 7)) << 4);
;   bf16x8 ra[4], rb[4];
;   const int nk = K >> 6;
; #pragma unroll
;   for (int i = 0; i < 4; ++i) { ra[i] = *reinterpret_cast<const bf16x8*>(Ap + (long)(64 * i) * lda); rb[i] = *reinterpret_cast<const bf16x8*>(Bp + (long)(64 * i) * ldb); }
; #pragma unroll
;   for (int i = 0; i < 4; ++i) { *reinterpret_cast<bf16x8*>(lds + swo + i * 8192) = ra[i]; *reinterpret_cast<bf16x8*>(lds + T_BYTES + swo + i * 8192) = rb[i]; }
;   __syncthreads();
; template <int OMODE>
; __device__ __forceinline__ void gemm_phase256(const bh* __restrict__ A, long lda, const bh* __restrict__ Bt, long ldb, int M, int ncols, int K,
;                                               void* Cp, long ldc, char* lds) {
;     ...
;   for (int tile = blockIdx.x; tile < tm_n * tn_n; tile += gridDim.x) {
;     const int tn = tile / tm_n, tm = tile - tn * tm_n;
;     f32x4 acc[8][4];
; #pragma unroll
;     for (int m = 0; m < 8; ++m)
; #pragma unroll
;       for (int n = 0; n < 4; ++n) acc[m][n] = f32x4{0.f, 0.f, 0.f, 0.f};
;     gemm_mainloop256(A + (long)tm * 256 * lda, lda, Bt + (long)tn * 256 * ldb, ldb, K, lds, acc);
.LBB0_1119:
	s_ashr_i32 s1, s0, 31
	s_lshl_b64 s[12:13], s[0:1], 19
	s_lshr_b32 s1, s1, 26
	s_add_i32 s1, s0, s1
	s_and_b32 s10, s1, 0xffffffc0
	s_sub_i32 s4, s0, s10
	s_ashr_i32 s5, s4, 31
	s_ashr_i32 s2, s1, 6
	s_lshl_b64 s[8:9], s[4:5], 19
	v_mov_b32_e32 v12, v188
	s_add_u32 s16, s38, s8
	s_addc_u32 s17, s39, s9
	v_ashrrev_i32_e32 v0, 3, v12
	s_ashr_i32 s3, s2, 31
	v_ashrrev_i32_e32 v1, 31, v0
	s_lshl_b64 s[8:9], s[2:3], 19
	v_lshlrev_b64 v[2:3], 11, v[0:1]
	v_lshlrev_b32_e32 v1, 4, v12
	s_add_u32 s18, s14, s8
	v_lshl_add_u64 v[4:5], s[16:17], 0, v[2:3]
	v_and_b32_e32 v176, 0x70, v1
	s_addc_u32 s19, s15, s9
	v_lshl_add_u64 v[4:5], v[4:5], 0, v[176:177]
	s_mov_b32 s1, 0x20000
	v_lshl_add_u64 v[6:7], s[18:19], 0, v[2:3]
	v_add_co_u32_e32 v8, vcc, s1, v4
	v_lshl_add_u64 v[6:7], v[6:7], 0, v[176:177]
	s_nop 0
	v_addc_co_u32_e32 v9, vcc, 0, v5, vcc
	v_add_co_u32_e32 v10, vcc, s1, v6
	s_mov_b32 s1, 0x40000
	s_nop 0
	v_addc_co_u32_e32 v11, vcc, 0, v7, vcc
	global_load_dwordx4 v[64:67], v[4:5], off
	global_load_dwordx4 v[68:71], v[6:7], off
	global_load_dwordx4 v[76:79], v[8:9], off
	global_load_dwordx4 v[80:83], v[10:11], off
	v_add_co_u32_e32 v8, vcc, s1, v4
	v_lshrrev_b32_e32 v1, 4, v12
	s_nop 0
	v_addc_co_u32_e32 v9, vcc, 0, v5, vcc
	v_add_co_u32_e32 v10, vcc, s1, v6
	s_mov_b32 s1, 0x60000
	s_nop 0
	v_addc_co_u32_e32 v11, vcc, 0, v7, vcc
	v_add_co_u32_e32 v4, vcc, s1, v4
	global_load_dwordx4 v[92:95], v[8:9], off
	global_load_dwordx4 v[96:99], v[10:11], off
	v_addc_co_u32_e32 v5, vcc, 0, v5, vcc
	global_load_dwordx4 v[104:107], v[4:5], off
	v_add_co_u32_e32 v4, vcc, s1, v6
	v_lshrrev_b32_e32 v6, 1, v12
	s_nop 0
	v_addc_co_u32_e32 v5, vcc, 0, v7, vcc
	global_load_dwordx4 v[108:111], v[4:5], off
	v_and_b32_e32 v4, 15, v12
	v_lshlrev_b32_e32 v7, 7, v12
	v_and_b32_e32 v8, 7, v12
	v_xor_b32_e32 v9, v0, v12
	s_mov_b32 s1, 0x1ffff80
	v_lshlrev_b32_e32 v0, 7, v0
	v_and_or_b32 v4, v6, s1, v4
	v_and_b32_e32 v166, 0x6780, v7
	v_bitop3_b32 v1, v1, v8, 3 bitop3:0x6c
	v_lshlrev_b32_e32 v7, 4, v9
	s_movk_i32 s1, 0x70
	v_lshlrev_b32_e32 v6, 4, v8
	v_lshlrev_b32_e32 v167, 7, v4
	v_lshlrev_b32_e32 v168, 4, v1
	v_and_or_b32 v4, v7, s1, v0
	v_lshl_add_u64 v[0:1], s[12:13], 0, v[2:3]
	s_ashr_i32 s11, s10, 31
	v_or_b32_e32 v0, v0, v6
	s_lshl_b64 s[10:11], s[10:11], 19
	v_add_u32_e32 v170, 32, v4
	v_mov_b32_e32 v4, s11
	v_subrev_co_u32_e32 v0, vcc, s10, v0
	v_bfe_u32 v5, v12, 4, 2
	s_nop 0
	v_subb_co_u32_e32 v1, vcc, v1, v4, vcc
	v_lshl_add_u64 v[160:161], s[28:29], 0, v[0:1]
	v_lshl_add_u64 v[0:1], s[8:9], 0, v[2:3]
	v_readlane_b32 s8, v253, 55
	v_or_b32_e32 v0, v0, v6
	v_readlane_b32 s9, v253, 56
	v_bitop3_b32 v5, v5, v8, 4 bitop3:0x36
	s_mov_b32 s3, 0
	v_lshl_add_u64 v[162:163], s[8:9], 0, v[0:1]
	v_mov_b32_e32 v0, 0
	v_lshlrev_b32_e32 v169, 4, v5
	s_mov_b64 s[8:9], 0
	s_mov_b32 s1, 0
	v_mov_b32_e32 v1, v0
	v_mov_b32_e32 v2, v0
	v_mov_b32_e32 v3, v0
	v_mov_b32_e32 v4, v0
	v_mov_b32_e32 v5, v0
	v_mov_b32_e32 v6, v0
	v_mov_b32_e32 v7, v0
	v_mov_b32_e32 v8, v0
	v_mov_b32_e32 v9, v0
	v_mov_b32_e32 v10, v0
	v_mov_b32_e32 v11, v0
	v_mov_b32_e32 v12, v0
	v_mov_b32_e32 v13, v0
	v_mov_b32_e32 v14, v0
	v_mov_b32_e32 v15, v0
	v_mov_b32_e32 v16, v0
	v_mov_b32_e32 v17, v0
	v_mov_b32_e32 v18, v0
	v_mov_b32_e32 v19, v0
	v_mov_b32_e32 v20, v0
	v_mov_b32_e32 v21, v0
	v_mov_b32_e32 v22, v0
	v_mov_b32_e32 v23, v0
	v_mov_b32_e32 v24, v0
	v_mov_b32_e32 v25, v0
	v_mov_b32_e32 v26, v0
	v_mov_b32_e32 v27, v0
	v_mov_b32_e32 v28, v0
	v_mov_b32_e32 v29, v0
	v_mov_b32_e32 v30, v0
	v_mov_b32_e32 v31, v0
	v_mov_b32_e32 v32, v0
	v_mov_b32_e32 v33, v0
	v_mov_b32_e32 v34, v0
	v_mov_b32_e32 v35, v0
	v_mov_b32_e32 v36, v0
	v_mov_b32_e32 v37, v0
	v_mov_b32_e32 v38, v0
	v_mov_b32_e32 v39, v0
	s_waitcnt vmcnt(40)
; __device__ __forceinline__ void gemm_mainloop256(const bh* __restrict__ A, long lda, const bh* __restrict__ B, long ldb, int K,
;                                                  char* lds, f32x4 (&acc)[8][4]) {
;     ...
; #pragma unroll
;   for (int i = 0; i < 4; ++i) { *reinterpret_cast<bf16x8*>(lds + swo + i * 8192) = ra[i]; *reinterpret_cast<bf16x8*>(lds + T_BYTES + swo + i * 8192) = rb[i]; }
;   __syncthreads();
;   const int a_row = (wr * 128 + fr) * 128, b_row = (wc * 64 + fr) * 128;
;   const int c0 = ((0 + fq) ^ (fr & 7)) << 4, c1 = ((4 + fq) ^ (fr & 7)) << 4;
; #pragma unroll 1
;   for (int kt = 0; kt < nk; ++kt) {
;     const bool more = kt + 1 < nk;
;     if (more) {
; #pragma unroll
;       for (int i = 0; i < 4; ++i) { ra[i] = *reinterpret_cast<const bf16x8*>(Ap + (long)(64 * i) * lda + (kt + 1) * 64); rb[i] = *reinterpret_cast<const bf16x8*>(Bp + (long)(64 * i) * ldb + (kt + 1) * 64); }
;     }
; template <int OMODE>
; __device__ __forceinline__ void gemm_phase256(const bh* __restrict__ A, long lda, const bh* __restrict__ Bt, long ldb, int M, int ncols, int K,
;                                               void* Cp, long ldc, char* lds) {
;     ...
; #pragma unroll
;     for (int m = 0; m < 8; ++m)
; #pragma unroll
;       for (int n = 0; n < 4; ++n) acc[m][n] = f32x4{0.f, 0.f, 0.f, 0.f};
	v_mov_b32_e32 v40, v0
	v_mov_b32_e32 v41, v0
	v_mov_b32_e32 v42, v0
	v_mov_b32_e32 v43, v0
	v_mov_b32_e32 v44, v0
	v_mov_b32_e32 v45, v0
	v_mov_b32_e32 v46, v0
	v_mov_b32_e32 v47, v0
	v_mov_b32_e32 v48, v0
	v_mov_b32_e32 v49, v0
	v_mov_b32_e32 v50, v0
	v_mov_b32_e32 v51, v0
	v_mov_b32_e32 v52, v0
	v_mov_b32_e32 v53, v0
	v_mov_b32_e32 v54, v0
	v_mov_b32_e32 v55, v0
	v_mov_b32_e32 v56, v0
	v_mov_b32_e32 v57, v0
	v_mov_b32_e32 v58, v0
	v_mov_b32_e32 v59, v0
	v_mov_b32_e32 v60, v0
	v_mov_b32_e32 v61, v0
	v_mov_b32_e32 v62, v0
	v_mov_b32_e32 v63, v0
	v_mov_b32_e32 v72, v0
	v_mov_b32_e32 v73, v0
	v_mov_b32_e32 v74, v0
	v_mov_b32_e32 v75, v0
	v_mov_b32_e32 v84, v0
	v_mov_b32_e32 v85, v0
	v_mov_b32_e32 v86, v0
	v_mov_b32_e32 v87, v0
	v_mov_b32_e32 v88, v0
	v_mov_b32_e32 v89, v0
	v_mov_b32_e32 v90, v0
	v_mov_b32_e32 v91, v0
	v_mov_b32_e32 v100, v0
	v_mov_b32_e32 v101, v0
	v_mov_b32_e32 v102, v0
	v_mov_b32_e32 v103, v0
	v_mov_b32_e32 v112, v0
	v_mov_b32_e32 v113, v0
	v_mov_b32_e32 v114, v0
	v_mov_b32_e32 v115, v0
	v_mov_b32_e32 v116, v0
	v_mov_b32_e32 v117, v0
	v_mov_b32_e32 v118, v0
	v_mov_b32_e32 v119, v0
	v_mov_b32_e32 v120, v0
	v_mov_b32_e32 v121, v0
	v_mov_b32_e32 v122, v0
	v_mov_b32_e32 v123, v0
	v_mov_b32_e32 v124, v0
	v_mov_b32_e32 v125, v0
	v_mov_b32_e32 v126, v0
	v_mov_b32_e32 v127, v0
	v_mov_b32_e32 v128, v0
	v_mov_b32_e32 v129, v0
	v_mov_b32_e32 v130, v0
	v_mov_b32_e32 v131, v0
	v_mov_b32_e32 v132, v0
	v_mov_b32_e32 v133, v0
	v_mov_b32_e32 v134, v0
	v_mov_b32_e32 v135, v0
	v_mov_b32_e32 v136, v0
	v_mov_b32_e32 v137, v0
	v_mov_b32_e32 v138, v0
	v_mov_b32_e32 v139, v0
	v_mov_b32_e32 v140, v0
	v_mov_b32_e32 v141, v0
	v_mov_b32_e32 v142, v0
	v_mov_b32_e32 v143, v0
	v_mov_b32_e32 v144, v0
	v_mov_b32_e32 v145, v0
	v_mov_b32_e32 v146, v0
	v_mov_b32_e32 v147, v0
	v_mov_b32_e32 v148, v0
	v_mov_b32_e32 v149, v0
	v_mov_b32_e32 v150, v0
	v_mov_b32_e32 v151, v0
	v_mov_b32_e32 v152, v0
	v_mov_b32_e32 v153, v0
	v_mov_b32_e32 v154, v0
	v_mov_b32_e32 v155, v0
	v_mov_b32_e32 v156, v0
	v_mov_b32_e32 v157, v0
	v_mov_b32_e32 v158, v0
	v_mov_b32_e32 v159, v0
	s_waitcnt vmcnt(7)
	ds_write_b128 v170, v[64:67]
	s_waitcnt vmcnt(5)
	ds_write_b128 v170, v[76:79] offset:8192
	s_waitcnt vmcnt(3)
	ds_write_b128 v170, v[92:95] offset:16384
	s_waitcnt vmcnt(1)
	ds_write_b128 v170, v[104:107] offset:24576
	ds_write_b128 v170, v[68:71] offset:32768
	ds_write_b128 v170, v[80:83] offset:40960
	ds_write_b128 v170, v[96:99] offset:49152
	s_waitcnt vmcnt(0)
	ds_write_b128 v170, v[108:111] offset:57344
	s_waitcnt lgkmcnt(0)
	s_waitcnt vmcnt(1)
	v_lshl_add_u64 v[104:105], v[160:161], 0, s[8:9]
	v_add_co_u32_e32 v64, vcc, 0x5770000, v104
	v_lshl_add_u64 v[106:107], v[162:163], 0, s[8:9]
	s_nop 0
	v_addc_co_u32_e32 v65, vcc, 0, v105, vcc
	v_add_co_u32_e32 v68, vcc, 0x1b38000, v106
	s_nop 1
	v_addc_co_u32_e32 v69, vcc, 0, v107, vcc
	v_add_co_u32_e32 v76, vcc, 0x5790000, v104
	global_load_dwordx4 v[64:67], v[64:65], off offset:128
	s_nop 0
	global_load_dwordx4 v[68:71], v[68:69], off offset:128
	v_addc_co_u32_e32 v77, vcc, 0, v105, vcc
	v_add_co_u32_e32 v80, vcc, 0x1b58000, v106
	s_nop 1
	v_addc_co_u32_e32 v81, vcc, 0, v107, vcc
	v_add_co_u32_e32 v92, vcc, 0x57b0000, v104
	global_load_dwordx4 v[76:79], v[76:77], off offset:128
	s_nop 0
	global_load_dwordx4 v[80:83], v[80:81], off offset:128
	v_addc_co_u32_e32 v93, vcc, 0, v105, vcc
	v_add_co_u32_e32 v96, vcc, 0x1b78000, v106
	s_nop 1
	v_addc_co_u32_e32 v97, vcc, 0, v107, vcc
	v_add_co_u32_e32 v104, vcc, 0x57d0000, v104
	global_load_dwordx4 v[92:95], v[92:93], off offset:128
	s_nop 0
	global_load_dwordx4 v[96:99], v[96:97], off offset:128
	v_addc_co_u32_e32 v105, vcc, 0, v105, vcc
	s_waitcnt vmcnt(6)
	v_add_co_u32_e32 v108, vcc, 0x1b98000, v106
	s_nop 1
	v_addc_co_u32_e32 v109, vcc, 0, v107, vcc
	global_load_dwordx4 v[104:107], v[104:105], off offset:128
	s_nop 0
	global_load_dwordx4 v[108:111], v[108:109], off offset:128
	s_barrier
	s_branch .LBB0_1121

; #define LDF_A(dst, mh, co) _Pragma("unroll") for (int m = 0; m < 4; ++m) dst[m] = *reinterpret_cast<const bf16x8*>(sa + ((mh) * 4 + m) * 2048 + (co))
; #define LDF_B(dst, co) _Pragma("unroll") for (int n = 0; n < 4; ++n) dst[n] = *reinterpret_cast<const bf16x8*>(sb + n * 2048 + (co))
; #define MMA16(av, bv, mh) do { __builtin_amdgcn_s_setprio(1); _Pragma("unroll") for (int m = 0; m < 4; ++m) _Pragma("unroll") for (int n = 0; n < 4; ++n) \
;       acc[(mh) * 4 + m][n] = mfma16(av[m], bv[n], acc[(mh) * 4 + m][n]); __builtin_amdgcn_s_setprio(0); } while (0)
; __device__ __forceinline__ void gemm_mainloop256(const bh* __restrict__ A, long lda, const bh* __restrict__ B, long ldb, int K,
;                                                  char* lds, f32x4 (&acc)[8][4]) {
;     ...
;   for (int kt = 0; kt < nk; ++kt) {
;     const bool more = kt + 1 < nk;
;     if (more) {
; #pragma unroll
;       for (int i = 0; i < 4; ++i) { ra[i] = *reinterpret_cast<const bf16x8*>(Ap + (long)(64 * i) * lda + (kt + 1) * 64); rb[i] = *reinterpret_cast<const bf16x8*>(Bp + (long)(64 * i) * ldb + (kt + 1) * 64); }
;     }
;     const char* sa = lds + (kt & 1) * STAGE + a_row;
;     const char* sb = lds + (kt & 1) * STAGE + T_BYTES + b_row;
;     bf16x8 b0[4], a0[4], a1[4];
;     ...
;     LDF_B(b0, c0); LDF_A(a0, 0, c0);
;     LDF_A(a1, 1, c0);
;     MMA16(a0, b0, 0);
;     LDF_A(a0, 0, c1);
;     MMA16(a1, b0, 1);
;     LDF_B(b0, c1); LDF_A(a1, 1, c1);
;     MMA16(a0, b0, 0);
;     MMA16(a1, b0, 1);
.LBB0_1121:
	s_cmp_gt_u32 s1, 14
	s_cselect_b64 s[10:11], -1, 0
	s_and_b32 s5, s3, 0x10000
	s_add_i32 s5, s5, 32
	v_add_u32_e32 v171, s5, v166
	v_add_u32_e32 v176, v171, v168
	ds_read_b128 v[172:175], v176 offset:32768
	ds_read_b128 v[182:185], v176 offset:34816
	ds_read_b128 v[198:201], v176 offset:36864
	ds_read_b128 v[206:209], v176 offset:38912
	v_add_u32_e32 v176, s5, v167
	v_add_u32_e32 v179, v176, v168
	ds_read_b128 v[210:213], v179
	ds_read_b128 v[214:217], v179 offset:2048
	ds_read_b128 v[218:221], v179 offset:4096
	ds_read_b128 v[222:225], v179 offset:6144
	ds_read_b128 v[226:229], v179 offset:8192
	ds_read_b128 v[230:233], v179 offset:10240
	ds_read_b128 v[234:237], v179 offset:12288
	ds_read_b128 v[238:241], v179 offset:14336
.LBB0_1123:
	s_setprio 1
	s_waitcnt lgkmcnt(7)
	v_mfma_f32_16x16x32_bf16 v[156:159], v[210:213], v[172:175], v[156:159]
	v_mfma_f32_16x16x32_bf16 v[152:155], v[210:213], v[182:185], v[152:155]
	v_mfma_f32_16x16x32_bf16 v[148:151], v[210:213], v[198:201], v[148:151]
	v_mfma_f32_16x16x32_bf16 v[144:147], v[210:213], v[206:209], v[144:147]
	s_waitcnt lgkmcnt(6)
	v_mfma_f32_16x16x32_bf16 v[140:143], v[214:217], v[172:175], v[140:143]
	v_mfma_f32_16x16x32_bf16 v[136:139], v[214:217], v[182:185], v[136:139]
	v_mfma_f32_16x16x32_bf16 v[132:135], v[214:217], v[198:201], v[132:135]
	v_mfma_f32_16x16x32_bf16 v[128:131], v[214:217], v[206:209], v[128:131]
	s_waitcnt lgkmcnt(5)
	v_mfma_f32_16x16x32_bf16 v[124:127], v[218:221], v[172:175], v[124:127]
	v_mfma_f32_16x16x32_bf16 v[120:123], v[218:221], v[182:185], v[120:123]
	v_mfma_f32_16x16x32_bf16 v[116:119], v[218:221], v[198:201], v[116:119]
	v_mfma_f32_16x16x32_bf16 v[112:115], v[218:221], v[206:209], v[112:115]
	s_waitcnt lgkmcnt(4)
	v_mfma_f32_16x16x32_bf16 v[100:103], v[222:225], v[172:175], v[100:103]
	v_mfma_f32_16x16x32_bf16 v[88:91], v[222:225], v[182:185], v[88:91]
	v_mfma_f32_16x16x32_bf16 v[84:87], v[222:225], v[198:201], v[84:87]
	v_mfma_f32_16x16x32_bf16 v[72:75], v[222:225], v[206:209], v[72:75]
	s_setprio 0
	v_add_u32_e32 v176, v176, v169
	ds_read_b128 v[210:213], v176
	ds_read_b128 v[214:217], v176 offset:2048
	ds_read_b128 v[218:221], v176 offset:4096
	ds_read_b128 v[222:225], v176 offset:6144
	s_setprio 1
	s_waitcnt lgkmcnt(7)
	v_mfma_f32_16x16x32_bf16 v[60:63], v[226:229], v[172:175], v[60:63]
	v_mfma_f32_16x16x32_bf16 v[56:59], v[226:229], v[182:185], v[56:59]
	v_mfma_f32_16x16x32_bf16 v[52:55], v[226:229], v[198:201], v[52:55]
	v_mfma_f32_16x16x32_bf16 v[48:51], v[226:229], v[206:209], v[48:51]
	s_waitcnt lgkmcnt(6)
	v_mfma_f32_16x16x32_bf16 v[44:47], v[230:233], v[172:175], v[44:47]
	v_mfma_f32_16x16x32_bf16 v[40:43], v[230:233], v[182:185], v[40:43]
	v_mfma_f32_16x16x32_bf16 v[36:39], v[230:233], v[198:201], v[36:39]
	v_mfma_f32_16x16x32_bf16 v[32:35], v[230:233], v[206:209], v[32:35]
	s_waitcnt lgkmcnt(5)
	v_mfma_f32_16x16x32_bf16 v[28:31], v[234:237], v[172:175], v[28:31]
	v_mfma_f32_16x16x32_bf16 v[24:27], v[234:237], v[182:185], v[24:27]
	v_mfma_f32_16x16x32_bf16 v[20:23], v[234:237], v[198:201], v[20:23]
	v_mfma_f32_16x16x32_bf16 v[16:19], v[234:237], v[206:209], v[16:19]
	s_waitcnt lgkmcnt(4)
	v_mfma_f32_16x16x32_bf16 v[12:15], v[238:241], v[172:175], v[12:15]
	v_mfma_f32_16x16x32_bf16 v[8:11], v[238:241], v[182:185], v[8:11]
	v_mfma_f32_16x16x32_bf16 v[4:7], v[238:241], v[198:201], v[4:7]
	v_mfma_f32_16x16x32_bf16 v[0:3], v[238:241], v[206:209], v[0:3]
	s_setprio 0
	v_add_u32_e32 v171, v171, v169
	ds_read_b128 v[172:175], v171 offset:32768
	ds_read_b128 v[182:185], v171 offset:34816
	ds_read_b128 v[198:201], v171 offset:36864
	ds_read_b128 v[206:209], v171 offset:38912
	ds_read_b128 v[226:229], v176 offset:8192
	ds_read_b128 v[230:233], v176 offset:10240
	ds_read_b128 v[234:237], v176 offset:12288
	ds_read_b128 v[238:241], v176 offset:14336
	s_and_b64 vcc, exec, s[10:11]
	s_cbranch_vccnz .Lmy_g256_last_2
; #define LDF_A(dst, mh, co) _Pragma("unroll") for (int m = 0; m < 4; ++m) dst[m] = *reinterpret_cast<const bf16x8*>(sa + ((mh) * 4 + m) * 2048 + (co))
; #define LDF_B(dst, co) _Pragma("unroll") for (int n = 0; n < 4; ++n) dst[n] = *reinterpret_cast<const bf16x8*>(sb + n * 2048 + (co))
; #define MMA16(av, bv, mh) do { __builtin_amdgcn_s_setprio(1); _Pragma("unroll") for (int m = 0; m < 4; ++m) _Pragma("unroll") for (int n = 0; n < 4; ++n) \
;       acc[(mh) * 4 + m][n] = mfma16(av[m], bv[n], acc[(mh) * 4 + m][n]); __builtin_amdgcn_s_setprio(0); } while (0)
; __device__ __forceinline__ void gemm_mainloop256(const bh* __restrict__ A, long lda, const bh* __restrict__ B, long ldb, int K,
;                                                  char* lds, f32x4 (&acc)[8][4]) {
;     ...
;     if (more) {
; #pragma unroll
;       for (int i = 0; i < 4; ++i) { ra[i] = *reinterpret_cast<const bf16x8*>(Ap + (long)(64 * i) * lda + (kt + 1) * 64); rb[i] = *reinterpret_cast<const bf16x8*>(Bp + (long)(64 * i) * ldb + (kt + 1) * 64); }
;     }
;     ...
;     MMA16(a1, b0, 1);
;     LDF_B(b0, c1); LDF_A(a1, 1, c1);
;     MMA16(a0, b0, 0);
;     MMA16(a1, b0, 1);
;     ...
;     if (more) {
;       char* wb = lds + ((kt + 1) & 1) * STAGE;
; #pragma unroll
;       for (int i = 0; i < 4; ++i) { *reinterpret_cast<bf16x8*>(wb + swo + i * 8192) = ra[i]; *reinterpret_cast<bf16x8*>(wb + T_BYTES + swo + i * 8192) = rb[i]; }
;     }
;     __syncthreads();
	s_add_i32 s5, s3, 0x10000
	s_and_b32 s3, s5, 0x10000
	v_add_u32_e32 v171, s3, v170
	s_setprio 1
	s_waitcnt lgkmcnt(7)
	v_mfma_f32_16x16x32_bf16 v[156:159], v[210:213], v[172:175], v[156:159]
	s_waitcnt lgkmcnt(6)
	v_mfma_f32_16x16x32_bf16 v[152:155], v[210:213], v[182:185], v[152:155]
	s_waitcnt lgkmcnt(5)
	v_mfma_f32_16x16x32_bf16 v[148:151], v[210:213], v[198:201], v[148:151]
	s_waitcnt lgkmcnt(4)
	v_mfma_f32_16x16x32_bf16 v[144:147], v[210:213], v[206:209], v[144:147]
	s_waitcnt vmcnt(7)
	ds_write_b128 v171, v[64:67]
	v_mfma_f32_16x16x32_bf16 v[140:143], v[214:217], v[172:175], v[140:143]
	v_mfma_f32_16x16x32_bf16 v[136:139], v[214:217], v[182:185], v[136:139]
	v_mfma_f32_16x16x32_bf16 v[132:135], v[214:217], v[198:201], v[132:135]
	v_mfma_f32_16x16x32_bf16 v[128:131], v[214:217], v[206:209], v[128:131]
	s_waitcnt vmcnt(6)
	ds_write_b128 v171, v[68:71] offset:32768
	v_mfma_f32_16x16x32_bf16 v[124:127], v[218:221], v[172:175], v[124:127]
	v_mfma_f32_16x16x32_bf16 v[120:123], v[218:221], v[182:185], v[120:123]
	v_mfma_f32_16x16x32_bf16 v[116:119], v[218:221], v[198:201], v[116:119]
	v_mfma_f32_16x16x32_bf16 v[112:115], v[218:221], v[206:209], v[112:115]
	s_waitcnt vmcnt(5)
	ds_write_b128 v171, v[76:79] offset:8192
	v_mfma_f32_16x16x32_bf16 v[100:103], v[222:225], v[172:175], v[100:103]
	v_mfma_f32_16x16x32_bf16 v[88:91], v[222:225], v[182:185], v[88:91]
	v_mfma_f32_16x16x32_bf16 v[84:87], v[222:225], v[198:201], v[84:87]
	v_mfma_f32_16x16x32_bf16 v[72:75], v[222:225], v[206:209], v[72:75]
	s_waitcnt vmcnt(4)
	ds_write_b128 v171, v[80:83] offset:40960
	s_waitcnt lgkmcnt(7)
	v_mfma_f32_16x16x32_bf16 v[60:63], v[226:229], v[172:175], v[60:63]
	v_mfma_f32_16x16x32_bf16 v[56:59], v[226:229], v[182:185], v[56:59]
	v_mfma_f32_16x16x32_bf16 v[52:55], v[226:229], v[198:201], v[52:55]
	v_mfma_f32_16x16x32_bf16 v[48:51], v[226:229], v[206:209], v[48:51]
	s_waitcnt vmcnt(3)
	ds_write_b128 v171, v[92:95] offset:16384
	s_waitcnt lgkmcnt(7)
	v_mfma_f32_16x16x32_bf16 v[44:47], v[230:233], v[172:175], v[44:47]
	v_mfma_f32_16x16x32_bf16 v[40:43], v[230:233], v[182:185], v[40:43]
	v_mfma_f32_16x16x32_bf16 v[36:39], v[230:233], v[198:201], v[36:39]
	v_mfma_f32_16x16x32_bf16 v[32:35], v[230:233], v[206:209], v[32:35]
	s_waitcnt vmcnt(2)
	ds_write_b128 v171, v[96:99] offset:49152
	s_waitcnt lgkmcnt(7)
	v_mfma_f32_16x16x32_bf16 v[28:31], v[234:237], v[172:175], v[28:31]
	v_mfma_f32_16x16x32_bf16 v[24:27], v[234:237], v[182:185], v[24:27]
	v_mfma_f32_16x16x32_bf16 v[20:23], v[234:237], v[198:201], v[20:23]
	v_mfma_f32_16x16x32_bf16 v[16:19], v[234:237], v[206:209], v[16:19]
	s_waitcnt vmcnt(1)
	ds_write_b128 v171, v[104:107] offset:24576
	s_waitcnt lgkmcnt(7)
	v_mfma_f32_16x16x32_bf16 v[12:15], v[238:241], v[172:175], v[12:15]
	v_mfma_f32_16x16x32_bf16 v[8:11], v[238:241], v[182:185], v[8:11]
	v_mfma_f32_16x16x32_bf16 v[4:7], v[238:241], v[198:201], v[4:7]
	v_mfma_f32_16x16x32_bf16 v[0:3], v[238:241], v[206:209], v[0:3]
	s_waitcnt vmcnt(0)
	ds_write_b128 v171, v[108:111] offset:57344
	s_setprio 0
	s_cmp_gt_u32 s1, 13
	s_cbranch_scc1 .Lmy_t14_skip_5
	s_waitcnt vmcnt(1)
	v_lshl_add_u64 v[104:105], v[160:161], 0, s[8:9]
	v_add_co_u32_e32 v64, vcc, 0x5770000, v104
	v_lshl_add_u64 v[106:107], v[162:163], 0, s[8:9]
	s_nop 0
	v_addc_co_u32_e32 v65, vcc, 0, v105, vcc
	v_add_co_u32_e32 v68, vcc, 0x1b38000, v106
	s_nop 1
	v_addc_co_u32_e32 v69, vcc, 0, v107, vcc
	v_add_co_u32_e32 v76, vcc, 0x5790000, v104
	global_load_dwordx4 v[64:67], v[64:65], off offset:256
	s_nop 0
	global_load_dwordx4 v[68:71], v[68:69], off offset:256
	v_addc_co_u32_e32 v77, vcc, 0, v105, vcc
	v_add_co_u32_e32 v80, vcc, 0x1b58000, v106
	s_nop 1
	v_addc_co_u32_e32 v81, vcc, 0, v107, vcc
	v_add_co_u32_e32 v92, vcc, 0x57b0000, v104
	global_load_dwordx4 v[76:79], v[76:77], off offset:256
	s_nop 0
	global_load_dwordx4 v[80:83], v[80:81], off offset:256
	v_addc_co_u32_e32 v93, vcc, 0, v105, vcc
	v_add_co_u32_e32 v96, vcc, 0x1b78000, v106
	s_nop 1
	v_addc_co_u32_e32 v97, vcc, 0, v107, vcc
	v_add_co_u32_e32 v104, vcc, 0x57d0000, v104
	global_load_dwordx4 v[92:95], v[92:93], off offset:256
	s_nop 0
	global_load_dwordx4 v[96:99], v[96:97], off offset:256
	v_addc_co_u32_e32 v105, vcc, 0, v105, vcc
	s_waitcnt vmcnt(6)
	v_add_co_u32_e32 v108, vcc, 0x1b98000, v106
	s_nop 1
	v_addc_co_u32_e32 v109, vcc, 0, v107, vcc
	global_load_dwordx4 v[104:107], v[104:105], off offset:256
	s_nop 0
	global_load_dwordx4 v[108:111], v[108:109], off offset:256

; __device__ __forceinline__ int tidx() { int t = threadIdx.x; asm volatile("" : "+v"(t)); return t; }
; __device__ __forceinline__ void gemm_mainloop256(const bh* __restrict__ A, long lda, const bh* __restrict__ B, long ldb, int K,
;                                                  char* lds, f32x4 (&acc)[8][4]) {
;     ...
;   const int tid = tidx(), lane = tid & 63, wid = tid >> 6, wr = wid >> 2, wc = wid & 3, fr = lane & 15, fq = lane >> 4;
;   const int srow = tid >> 3, sch = tid & 7;
;   const bh* Ap = A + (long)srow * lda + sch * 8;
;   const bh* Bp = B + (long)srow * ldb + sch * 8;
;   const int swo = srow * 128 + ((sch ^ (srow & 7)) << 4);
;   bf16x8 ra[4], rb[4];
;   const int nk = K >> 6;
; #pragma unroll
;   for (int i = 0; i < 4; ++i) { ra[i] = *reinterpret_cast<const bf16x8*>(Ap + (long)(64 * i) * lda); rb[i] = *reinterpret_cast<const bf16x8*>(Bp + (long)(64 * i) * ldb); }
; #pragma unroll
;   for (int i = 0; i < 4; ++i) { *reinterpret_cast<bf16x8*>(lds + swo + i * 8192) = ra[i]; *reinterpret_cast<bf16x8*>(lds + T_BYTES + swo + i * 8192) = rb[i]; }
;   __syncthreads();
; template <int OMODE>
; __device__ __forceinline__ void gemm_phase256(const bh* __restrict__ A, long lda, const bh* __restrict__ Bt, long ldb, int M, int ncols, int K,
;                                               void* Cp, long ldc, char* lds) {
;     ...
;   for (int tile = blockIdx.x; tile < tm_n * tn_n; tile += gridDim.x) {
;     const int tn = tile / tm_n, tm = tile - tn * tm_n;
;     f32x4 acc[8][4];
; #pragma unroll
;     for (int m = 0; m < 8; ++m)
; #pragma unroll
;       for (int n = 0; n < 4; ++n) acc[m][n] = f32x4{0.f, 0.f, 0.f, 0.f};
;     gemm_mainloop256(A + (long)tm * 256 * lda, lda, Bt + (long)tn * 256 * ldb, ldb, K, lds, acc);
.LBB0_1216:
	s_ashr_i32 s0, s8, 31
	s_lshr_b32 s0, s0, 26
	s_add_i32 s0, s8, s0
	s_and_b32 s11, s0, 0xffffffc0
	s_sub_i32 s10, s8, s11
	s_ashr_i32 s9, s0, 6
	s_mul_i32 s0, s10, 0x160000
	s_mul_hi_i32 s1, s10, 0x160000
	s_add_u32 s0, s70, s0
	s_addc_u32 s1, s71, s1
	s_mul_i32 s2, s9, 0x160000
	s_mul_hi_i32 s3, s9, 0x160000
	s_add_u32 s2, s4, s2
	v_mov_b32_e32 v8, v188
	s_addc_u32 s3, s5, s3
	v_mov_b64_e32 v[0:1], s[0:1]
	v_lshlrev_b32_e32 v2, 4, v8
	v_ashrrev_i32_e32 v9, 3, v8
	s_movk_i32 s13, 0x1600
	v_and_b32_e32 v176, 0x70, v2
	v_mov_b64_e32 v[2:3], s[2:3]
	v_mad_i64_i32 v[0:1], s[0:1], v9, s13, v[0:1]
	v_mad_i64_i32 v[2:3], s[0:1], v9, s13, v[2:3]
	v_lshl_add_u64 v[0:1], v[0:1], 0, v[176:177]
	s_mov_b32 s0, 0x58000
	v_add_co_u32_e32 v4, vcc, s0, v0
	v_lshl_add_u64 v[2:3], v[2:3], 0, v[176:177]
	s_nop 0
	v_addc_co_u32_e32 v5, vcc, 0, v1, vcc
	v_add_co_u32_e32 v6, vcc, s0, v2
	s_mov_b32 s0, 0xb0000
	s_nop 0
	v_addc_co_u32_e32 v7, vcc, 0, v3, vcc
	global_load_dwordx4 v[76:79], v[0:1], off
	global_load_dwordx4 v[80:83], v[2:3], off
	global_load_dwordx4 v[88:91], v[4:5], off
	global_load_dwordx4 v[92:95], v[6:7], off
	v_add_co_u32_e32 v4, vcc, s0, v0
	s_mov_b32 s12, 0
	s_nop 0
	v_addc_co_u32_e32 v5, vcc, 0, v1, vcc
	v_add_co_u32_e32 v6, vcc, s0, v2
	s_mov_b32 s0, 0x108000
	s_nop 0
	v_addc_co_u32_e32 v7, vcc, 0, v3, vcc
	v_add_co_u32_e32 v0, vcc, s0, v0
	global_load_dwordx4 v[100:103], v[4:5], off
	global_load_dwordx4 v[104:107], v[6:7], off
	v_addc_co_u32_e32 v1, vcc, 0, v1, vcc
	global_load_dwordx4 v[112:115], v[0:1], off
	v_add_co_u32_e32 v0, vcc, s0, v2
	v_bfe_u32 v2, v8, 4, 2
	s_nop 0
	v_addc_co_u32_e32 v1, vcc, 0, v3, vcc
	global_load_dwordx4 v[120:123], v[0:1], off
	v_lshrrev_b32_e32 v0, 4, v8
	v_and_b32_e32 v1, 15, v8
	v_lshrrev_b32_e32 v3, 1, v8
	v_lshlrev_b32_e32 v4, 7, v8
	v_and_b32_e32 v5, 7, v8
	s_mov_b32 s0, 0x1ffff80
	v_and_or_b32 v3, v3, s0, v1
	v_and_b32_e32 v166, 0x6780, v4
	v_bitop3_b32 v4, v0, v5, 3 bitop3:0x6c
	v_bitop3_b32 v2, v2, v5, 4 bitop3:0x36
	v_mad_i64_i32 v[0:1], s[0:1], v9, s13, 0
	v_xor_b32_e32 v6, v9, v8
	v_lshlrev_b32_e32 v167, 7, v3
	v_lshlrev_b32_e32 v169, 4, v2
	v_mad_i64_i32 v[2:3], s[0:1], s8, v202, v[0:1]
	v_lshlrev_b32_e32 v7, 7, v9
	v_lshlrev_b32_e32 v6, 4, v6
	s_movk_i32 s0, 0x70
	v_lshlrev_b32_e32 v168, 4, v4
	v_and_or_b32 v4, v6, s0, v7
	s_mul_hi_i32 s0, s11, 0x160000
	v_lshlrev_b32_e32 v5, 4, v5
	v_add_u32_e32 v170, 32, v4
	v_mov_b32_e32 v4, s0
	v_mad_i64_i32 v[0:1], s[0:1], s9, v202, v[0:1]
	v_or_b32_e32 v2, v2, v5
	s_mul_i32 s11, s11, 0x160000
	v_readlane_b32 s0, v253, 55
	v_subrev_co_u32_e32 v2, vcc, s11, v2
	v_or_b32_e32 v0, v0, v5
	v_readlane_b32 s1, v253, 56
	v_subb_co_u32_e32 v3, vcc, v3, v4, vcc
	s_nop 0
	v_lshl_add_u64 v[162:163], s[0:1], 0, v[0:1]
	v_mov_b32_e32 v0, 0
	v_lshl_add_u64 v[160:161], s[28:29], 0, v[2:3]
	s_mov_b64 s[0:1], 0
	s_mov_b32 s11, 0
	v_mov_b32_e32 v1, v0
	v_mov_b32_e32 v2, v0
	v_mov_b32_e32 v3, v0
	v_mov_b32_e32 v4, v0
	v_mov_b32_e32 v5, v0
	v_mov_b32_e32 v6, v0
	v_mov_b32_e32 v7, v0
	v_mov_b32_e32 v8, v0
	v_mov_b32_e32 v9, v0
	v_mov_b32_e32 v10, v0
	v_mov_b32_e32 v11, v0
	v_mov_b32_e32 v12, v0
	v_mov_b32_e32 v13, v0
	v_mov_b32_e32 v14, v0
	v_mov_b32_e32 v15, v0
	s_waitcnt vmcnt(18)
	v_mov_b32_e32 v16, v0
	v_mov_b32_e32 v17, v0
	v_mov_b32_e32 v18, v0
	v_mov_b32_e32 v19, v0
	v_mov_b32_e32 v20, v0
	v_mov_b32_e32 v21, v0
	v_mov_b32_e32 v22, v0
	v_mov_b32_e32 v23, v0
	s_waitcnt vmcnt(17)
	v_mov_b32_e32 v24, v0
	v_mov_b32_e32 v25, v0
	v_mov_b32_e32 v26, v0
	v_mov_b32_e32 v27, v0
	v_mov_b32_e32 v28, v0
	v_mov_b32_e32 v29, v0
	v_mov_b32_e32 v30, v0
	v_mov_b32_e32 v31, v0
	s_waitcnt vmcnt(16)
; __device__ __forceinline__ void gemm_mainloop256(const bh* __restrict__ A, long lda, const bh* __restrict__ B, long ldb, int K,
;                                                  char* lds, f32x4 (&acc)[8][4]) {
;     ...
; #pragma unroll
;   for (int i = 0; i < 4; ++i) { *reinterpret_cast<bf16x8*>(lds + swo + i * 8192) = ra[i]; *reinterpret_cast<bf16x8*>(lds + T_BYTES + swo + i * 8192) = rb[i]; }
;   __syncthreads();
;   const int a_row = (wr * 128 + fr) * 128, b_row = (wc * 64 + fr) * 128;
;   const int c0 = ((0 + fq) ^ (fr & 7)) << 4, c1 = ((4 + fq) ^ (fr & 7)) << 4;
; #pragma unroll 1
;   for (int kt = 0; kt < nk; ++kt) {
;     const bool more = kt + 1 < nk;
;     if (more) {
; #pragma unroll
;       for (int i = 0; i < 4; ++i) { ra[i] = *reinterpret_cast<const bf16x8*>(Ap + (long)(64 * i) * lda + (kt + 1) * 64); rb[i] = *reinterpret_cast<const bf16x8*>(Bp + (long)(64 * i) * ldb + (kt + 1) * 64); }
;     }
; template <int OMODE>
; __device__ __forceinline__ void gemm_phase256(const bh* __restrict__ A, long lda, const bh* __restrict__ Bt, long ldb, int M, int ncols, int K,
;                                               void* Cp, long ldc, char* lds) {
;     ...
; #pragma unroll
;     for (int m = 0; m < 8; ++m)
; #pragma unroll
;       for (int n = 0; n < 4; ++n) acc[m][n] = f32x4{0.f, 0.f, 0.f, 0.f};
	v_mov_b32_e32 v32, v0
	v_mov_b32_e32 v33, v0
	v_mov_b32_e32 v34, v0
	v_mov_b32_e32 v35, v0
	v_mov_b32_e32 v36, v0
	v_mov_b32_e32 v37, v0
	v_mov_b32_e32 v38, v0
	v_mov_b32_e32 v39, v0
	v_mov_b32_e32 v40, v0
	v_mov_b32_e32 v41, v0
	v_mov_b32_e32 v42, v0
	v_mov_b32_e32 v43, v0
	v_mov_b32_e32 v44, v0
	v_mov_b32_e32 v45, v0
	v_mov_b32_e32 v46, v0
	v_mov_b32_e32 v47, v0
	v_mov_b32_e32 v48, v0
	v_mov_b32_e32 v49, v0
	v_mov_b32_e32 v50, v0
	v_mov_b32_e32 v51, v0
	v_mov_b32_e32 v52, v0
	v_mov_b32_e32 v53, v0
	v_mov_b32_e32 v54, v0
	v_mov_b32_e32 v55, v0
	v_mov_b32_e32 v56, v0
	v_mov_b32_e32 v57, v0
	v_mov_b32_e32 v58, v0
	v_mov_b32_e32 v59, v0
	v_mov_b32_e32 v60, v0
	v_mov_b32_e32 v61, v0
	v_mov_b32_e32 v62, v0
	v_mov_b32_e32 v63, v0
	v_mov_b32_e32 v64, v0
	v_mov_b32_e32 v65, v0
	v_mov_b32_e32 v66, v0
	v_mov_b32_e32 v67, v0
	v_mov_b32_e32 v68, v0
	v_mov_b32_e32 v69, v0
	v_mov_b32_e32 v70, v0
	v_mov_b32_e32 v71, v0
	v_mov_b32_e32 v72, v0
	v_mov_b32_e32 v73, v0
	v_mov_b32_e32 v74, v0
	v_mov_b32_e32 v75, v0
	v_mov_b32_e32 v84, v0
	v_mov_b32_e32 v85, v0
	v_mov_b32_e32 v86, v0
	v_mov_b32_e32 v87, v0
	v_mov_b32_e32 v96, v0
	v_mov_b32_e32 v97, v0
	v_mov_b32_e32 v98, v0
	v_mov_b32_e32 v99, v0
	v_mov_b32_e32 v108, v0
	v_mov_b32_e32 v109, v0
	v_mov_b32_e32 v110, v0
	v_mov_b32_e32 v111, v0
	v_mov_b32_e32 v116, v0
	v_mov_b32_e32 v117, v0
	v_mov_b32_e32 v118, v0
	v_mov_b32_e32 v119, v0
	v_mov_b32_e32 v124, v0
	v_mov_b32_e32 v125, v0
	v_mov_b32_e32 v126, v0
	v_mov_b32_e32 v127, v0
	v_mov_b32_e32 v128, v0
	v_mov_b32_e32 v129, v0
	v_mov_b32_e32 v130, v0
	v_mov_b32_e32 v131, v0
	v_mov_b32_e32 v132, v0
	v_mov_b32_e32 v133, v0
	v_mov_b32_e32 v134, v0
	v_mov_b32_e32 v135, v0
	v_mov_b32_e32 v136, v0
	v_mov_b32_e32 v137, v0
	v_mov_b32_e32 v138, v0
	v_mov_b32_e32 v139, v0
	v_mov_b32_e32 v140, v0
	v_mov_b32_e32 v141, v0
	v_mov_b32_e32 v142, v0
	v_mov_b32_e32 v143, v0
	v_mov_b32_e32 v144, v0
	v_mov_b32_e32 v145, v0
	v_mov_b32_e32 v146, v0
	v_mov_b32_e32 v147, v0
	v_mov_b32_e32 v148, v0
	v_mov_b32_e32 v149, v0
	v_mov_b32_e32 v150, v0
	v_mov_b32_e32 v151, v0
	v_mov_b32_e32 v152, v0
	v_mov_b32_e32 v153, v0
	v_mov_b32_e32 v154, v0
	v_mov_b32_e32 v155, v0
	v_mov_b32_e32 v156, v0
	v_mov_b32_e32 v157, v0
	v_mov_b32_e32 v158, v0
	v_mov_b32_e32 v159, v0
	s_waitcnt vmcnt(7)
	ds_write_b128 v170, v[76:79]
	s_waitcnt vmcnt(5)
	ds_write_b128 v170, v[88:91] offset:8192
	s_waitcnt vmcnt(3)
	ds_write_b128 v170, v[100:103] offset:16384
	s_waitcnt vmcnt(1)
	ds_write_b128 v170, v[112:115] offset:24576
	ds_write_b128 v170, v[80:83] offset:32768
	ds_write_b128 v170, v[92:95] offset:40960
	ds_write_b128 v170, v[104:107] offset:49152
	s_waitcnt vmcnt(0)
	ds_write_b128 v170, v[120:123] offset:57344
	s_waitcnt lgkmcnt(0)
	s_waitcnt vmcnt(1)
	v_lshl_add_u64 v[112:113], v[160:161], 0, s[0:1]
	v_add_co_u32_e32 v76, vcc, 0x12770000, v112
	v_lshl_add_u64 v[114:115], v[162:163], 0, s[0:1]
	s_nop 0
	v_addc_co_u32_e32 v77, vcc, 0, v113, vcc
	v_add_co_u32_e32 v80, vcc, 0x2638000, v114
	s_nop 1
	v_addc_co_u32_e32 v81, vcc, 0, v115, vcc
	v_add_co_u32_e32 v88, vcc, 0x127c8000, v112
	global_load_dwordx4 v[76:79], v[76:77], off offset:128
	s_nop 0
	global_load_dwordx4 v[80:83], v[80:81], off offset:128
	v_addc_co_u32_e32 v89, vcc, 0, v113, vcc
	v_add_co_u32_e32 v92, vcc, 0x2690000, v114
	s_nop 1
	v_addc_co_u32_e32 v93, vcc, 0, v115, vcc
	v_add_co_u32_e32 v100, vcc, 0x12820000, v112
	global_load_dwordx4 v[88:91], v[88:89], off offset:128
	s_nop 0
	global_load_dwordx4 v[92:95], v[92:93], off offset:128
	v_addc_co_u32_e32 v101, vcc, 0, v113, vcc
	v_add_co_u32_e32 v104, vcc, 0x26e8000, v114
	s_nop 1
	v_addc_co_u32_e32 v105, vcc, 0, v115, vcc
	v_add_co_u32_e32 v112, vcc, 0x12878000, v112
	global_load_dwordx4 v[100:103], v[100:101], off offset:128
	s_nop 0
	global_load_dwordx4 v[104:107], v[104:105], off offset:128
	v_addc_co_u32_e32 v113, vcc, 0, v113, vcc
	s_waitcnt vmcnt(6)
	v_add_co_u32_e32 v120, vcc, 0x2740000, v114
	s_nop 1
	v_addc_co_u32_e32 v121, vcc, 0, v115, vcc
	global_load_dwordx4 v[112:115], v[112:113], off offset:128
	s_nop 0
	global_load_dwordx4 v[120:123], v[120:121], off offset:128
	s_barrier
	s_branch .LBB0_1218

; #define LDF_A(dst, mh, co) _Pragma("unroll") for (int m = 0; m < 4; ++m) dst[m] = *reinterpret_cast<const bf16x8*>(sa + ((mh) * 4 + m) * 2048 + (co))
; #define LDF_B(dst, co) _Pragma("unroll") for (int n = 0; n < 4; ++n) dst[n] = *reinterpret_cast<const bf16x8*>(sb + n * 2048 + (co))
; #define MMA16(av, bv, mh) do { __builtin_amdgcn_s_setprio(1); _Pragma("unroll") for (int m = 0; m < 4; ++m) _Pragma("unroll") for (int n = 0; n < 4; ++n) \
;       acc[(mh) * 4 + m][n] = mfma16(av[m], bv[n], acc[(mh) * 4 + m][n]); __builtin_amdgcn_s_setprio(0); } while (0)
; __device__ __forceinline__ void gemm_mainloop256(const bh* __restrict__ A, long lda, const bh* __restrict__ B, long ldb, int K,
;                                                  char* lds, f32x4 (&acc)[8][4]) {
;     ...
;   for (int kt = 0; kt < nk; ++kt) {
;     const bool more = kt + 1 < nk;
;     if (more) {
; #pragma unroll
;       for (int i = 0; i < 4; ++i) { ra[i] = *reinterpret_cast<const bf16x8*>(Ap + (long)(64 * i) * lda + (kt + 1) * 64); rb[i] = *reinterpret_cast<const bf16x8*>(Bp + (long)(64 * i) * ldb + (kt + 1) * 64); }
;     }
;     const char* sa = lds + (kt & 1) * STAGE + a_row;
;     const char* sb = lds + (kt & 1) * STAGE + T_BYTES + b_row;
;     bf16x8 b0[4], a0[4], a1[4];
;     ...
;     LDF_B(b0, c0); LDF_A(a0, 0, c0);
;     LDF_A(a1, 1, c0);
;     MMA16(a0, b0, 0);
;     LDF_A(a0, 0, c1);
;     MMA16(a1, b0, 1);
;     LDF_B(b0, c1); LDF_A(a1, 1, c1);
;     MMA16(a0, b0, 0);
;     MMA16(a1, b0, 1);
.LBB0_1218:
	s_cmp_gt_u32 s11, 42
	s_cselect_b64 s[2:3], -1, 0
	s_and_b32 s13, s12, 0x10000
	s_add_i32 s13, s13, 32
	v_add_u32_e32 v171, s13, v166
	v_add_u32_e32 v176, v171, v168
	ds_read_b128 v[172:175], v176 offset:32768
	ds_read_b128 v[182:185], v176 offset:34816
	ds_read_b128 v[198:201], v176 offset:36864
	ds_read_b128 v[206:209], v176 offset:38912
	v_add_u32_e32 v176, s13, v167
	v_add_u32_e32 v179, v176, v168
	ds_read_b128 v[210:213], v179
	ds_read_b128 v[214:217], v179 offset:2048
	ds_read_b128 v[218:221], v179 offset:4096
	ds_read_b128 v[222:225], v179 offset:6144
	ds_read_b128 v[226:229], v179 offset:8192
	ds_read_b128 v[230:233], v179 offset:10240
	ds_read_b128 v[234:237], v179 offset:12288
	ds_read_b128 v[238:241], v179 offset:14336
.LBB0_1220:
	s_setprio 1
	s_waitcnt lgkmcnt(7)
	v_mfma_f32_16x16x32_bf16 v[156:159], v[210:213], v[172:175], v[156:159]
	v_mfma_f32_16x16x32_bf16 v[152:155], v[210:213], v[182:185], v[152:155]
	v_mfma_f32_16x16x32_bf16 v[148:151], v[210:213], v[198:201], v[148:151]
	v_mfma_f32_16x16x32_bf16 v[144:147], v[210:213], v[206:209], v[144:147]
	s_waitcnt lgkmcnt(6)
	v_mfma_f32_16x16x32_bf16 v[140:143], v[214:217], v[172:175], v[140:143]
	v_mfma_f32_16x16x32_bf16 v[136:139], v[214:217], v[182:185], v[136:139]
	v_mfma_f32_16x16x32_bf16 v[132:135], v[214:217], v[198:201], v[132:135]
	v_mfma_f32_16x16x32_bf16 v[128:131], v[214:217], v[206:209], v[128:131]
	s_waitcnt lgkmcnt(5)
	v_mfma_f32_16x16x32_bf16 v[124:127], v[218:221], v[172:175], v[124:127]
	v_mfma_f32_16x16x32_bf16 v[116:119], v[218:221], v[182:185], v[116:119]
	v_mfma_f32_16x16x32_bf16 v[108:111], v[218:221], v[198:201], v[108:111]
	v_mfma_f32_16x16x32_bf16 v[96:99], v[218:221], v[206:209], v[96:99]
	s_waitcnt lgkmcnt(4)
	v_mfma_f32_16x16x32_bf16 v[84:87], v[222:225], v[172:175], v[84:87]
	v_mfma_f32_16x16x32_bf16 v[72:75], v[222:225], v[182:185], v[72:75]
	v_mfma_f32_16x16x32_bf16 v[68:71], v[222:225], v[198:201], v[68:71]
	v_mfma_f32_16x16x32_bf16 v[64:67], v[222:225], v[206:209], v[64:67]
	s_setprio 0
	v_add_u32_e32 v176, v176, v169
	ds_read_b128 v[210:213], v176
	ds_read_b128 v[214:217], v176 offset:2048
	ds_read_b128 v[218:221], v176 offset:4096
	ds_read_b128 v[222:225], v176 offset:6144
	s_setprio 1
	s_waitcnt lgkmcnt(7)
	v_mfma_f32_16x16x32_bf16 v[60:63], v[226:229], v[172:175], v[60:63]
	v_mfma_f32_16x16x32_bf16 v[56:59], v[226:229], v[182:185], v[56:59]
	v_mfma_f32_16x16x32_bf16 v[52:55], v[226:229], v[198:201], v[52:55]
	v_mfma_f32_16x16x32_bf16 v[48:51], v[226:229], v[206:209], v[48:51]
	s_waitcnt lgkmcnt(6)
	v_mfma_f32_16x16x32_bf16 v[44:47], v[230:233], v[172:175], v[44:47]
	v_mfma_f32_16x16x32_bf16 v[40:43], v[230:233], v[182:185], v[40:43]
	v_mfma_f32_16x16x32_bf16 v[36:39], v[230:233], v[198:201], v[36:39]
	v_mfma_f32_16x16x32_bf16 v[32:35], v[230:233], v[206:209], v[32:35]
	s_waitcnt lgkmcnt(5)
	v_mfma_f32_16x16x32_bf16 v[28:31], v[234:237], v[172:175], v[28:31]
	v_mfma_f32_16x16x32_bf16 v[24:27], v[234:237], v[182:185], v[24:27]
	v_mfma_f32_16x16x32_bf16 v[20:23], v[234:237], v[198:201], v[20:23]
	v_mfma_f32_16x16x32_bf16 v[16:19], v[234:237], v[206:209], v[16:19]
	s_waitcnt lgkmcnt(4)
	v_mfma_f32_16x16x32_bf16 v[12:15], v[238:241], v[172:175], v[12:15]
	v_mfma_f32_16x16x32_bf16 v[8:11], v[238:241], v[182:185], v[8:11]
	v_mfma_f32_16x16x32_bf16 v[4:7], v[238:241], v[198:201], v[4:7]
	v_mfma_f32_16x16x32_bf16 v[0:3], v[238:241], v[206:209], v[0:3]
	s_setprio 0
	v_add_u32_e32 v171, v171, v169
	ds_read_b128 v[172:175], v171 offset:32768
	ds_read_b128 v[182:185], v171 offset:34816
	ds_read_b128 v[198:201], v171 offset:36864
	ds_read_b128 v[206:209], v171 offset:38912
	ds_read_b128 v[226:229], v176 offset:8192
	ds_read_b128 v[230:233], v176 offset:10240
	ds_read_b128 v[234:237], v176 offset:12288
	ds_read_b128 v[238:241], v176 offset:14336
	s_and_b64 vcc, exec, s[2:3]
	s_cbranch_vccnz .Lmy_g256_last_1
; #define LDF_A(dst, mh, co) _Pragma("unroll") for (int m = 0; m < 4; ++m) dst[m] = *reinterpret_cast<const bf16x8*>(sa + ((mh) * 4 + m) * 2048 + (co))
; #define LDF_B(dst, co) _Pragma("unroll") for (int n = 0; n < 4; ++n) dst[n] = *reinterpret_cast<const bf16x8*>(sb + n * 2048 + (co))
; #define MMA16(av, bv, mh) do { __builtin_amdgcn_s_setprio(1); _Pragma("unroll") for (int m = 0; m < 4; ++m) _Pragma("unroll") for (int n = 0; n < 4; ++n) \
;       acc[(mh) * 4 + m][n] = mfma16(av[m], bv[n], acc[(mh) * 4 + m][n]); __builtin_amdgcn_s_setprio(0); } while (0)
; __device__ __forceinline__ void gemm_mainloop256(const bh* __restrict__ A, long lda, const bh* __restrict__ B, long ldb, int K,
;                                                  char* lds, f32x4 (&acc)[8][4]) {
;     ...
;     if (more) {
; #pragma unroll
;       for (int i = 0; i < 4; ++i) { ra[i] = *reinterpret_cast<const bf16x8*>(Ap + (long)(64 * i) * lda + (kt + 1) * 64); rb[i] = *reinterpret_cast<const bf16x8*>(Bp + (long)(64 * i) * ldb + (kt + 1) * 64); }
;     }
;     ...
;     MMA16(a1, b0, 1);
;     LDF_B(b0, c1); LDF_A(a1, 1, c1);
;     MMA16(a0, b0, 0);
;     MMA16(a1, b0, 1);
;     ...
;     if (more) {
;       char* wb = lds + ((kt + 1) & 1) * STAGE;
; #pragma unroll
;       for (int i = 0; i < 4; ++i) { *reinterpret_cast<bf16x8*>(wb + swo + i * 8192) = ra[i]; *reinterpret_cast<bf16x8*>(wb + T_BYTES + swo + i * 8192) = rb[i]; }
;     }
;     __syncthreads();
	s_add_i32 s13, s12, 0x10000
	s_and_b32 s2, s13, 0x10000
	v_add_u32_e32 v171, s2, v170
	s_setprio 1
	s_waitcnt lgkmcnt(7)
	v_mfma_f32_16x16x32_bf16 v[156:159], v[210:213], v[172:175], v[156:159]
	s_waitcnt lgkmcnt(6)
	v_mfma_f32_16x16x32_bf16 v[152:155], v[210:213], v[182:185], v[152:155]
	s_waitcnt lgkmcnt(5)
	v_mfma_f32_16x16x32_bf16 v[148:151], v[210:213], v[198:201], v[148:151]
	s_waitcnt lgkmcnt(4)
	v_mfma_f32_16x16x32_bf16 v[144:147], v[210:213], v[206:209], v[144:147]
	s_waitcnt vmcnt(7)
	ds_write_b128 v171, v[76:79]
	v_mfma_f32_16x16x32_bf16 v[140:143], v[214:217], v[172:175], v[140:143]
	v_mfma_f32_16x16x32_bf16 v[136:139], v[214:217], v[182:185], v[136:139]
	v_mfma_f32_16x16x32_bf16 v[132:135], v[214:217], v[198:201], v[132:135]
	v_mfma_f32_16x16x32_bf16 v[128:131], v[214:217], v[206:209], v[128:131]
	s_waitcnt vmcnt(6)
	ds_write_b128 v171, v[80:83] offset:32768
	v_mfma_f32_16x16x32_bf16 v[124:127], v[218:221], v[172:175], v[124:127]
	v_mfma_f32_16x16x32_bf16 v[116:119], v[218:221], v[182:185], v[116:119]
	v_mfma_f32_16x16x32_bf16 v[108:111], v[218:221], v[198:201], v[108:111]
	v_mfma_f32_16x16x32_bf16 v[96:99], v[218:221], v[206:209], v[96:99]
	s_waitcnt vmcnt(5)
	ds_write_b128 v171, v[88:91] offset:8192
	v_mfma_f32_16x16x32_bf16 v[84:87], v[222:225], v[172:175], v[84:87]
	v_mfma_f32_16x16x32_bf16 v[72:75], v[222:225], v[182:185], v[72:75]
	v_mfma_f32_16x16x32_bf16 v[68:71], v[222:225], v[198:201], v[68:71]
	v_mfma_f32_16x16x32_bf16 v[64:67], v[222:225], v[206:209], v[64:67]
	s_waitcnt vmcnt(4)
	ds_write_b128 v171, v[92:95] offset:40960
	s_waitcnt lgkmcnt(7)
	v_mfma_f32_16x16x32_bf16 v[60:63], v[226:229], v[172:175], v[60:63]
	v_mfma_f32_16x16x32_bf16 v[56:59], v[226:229], v[182:185], v[56:59]
	v_mfma_f32_16x16x32_bf16 v[52:55], v[226:229], v[198:201], v[52:55]
	v_mfma_f32_16x16x32_bf16 v[48:51], v[226:229], v[206:209], v[48:51]
	s_waitcnt vmcnt(3)
	ds_write_b128 v171, v[100:103] offset:16384
	s_waitcnt lgkmcnt(7)
	v_mfma_f32_16x16x32_bf16 v[44:47], v[230:233], v[172:175], v[44:47]
	v_mfma_f32_16x16x32_bf16 v[40:43], v[230:233], v[182:185], v[40:43]
	v_mfma_f32_16x16x32_bf16 v[36:39], v[230:233], v[198:201], v[36:39]
	v_mfma_f32_16x16x32_bf16 v[32:35], v[230:233], v[206:209], v[32:35]
	s_waitcnt vmcnt(2)
	ds_write_b128 v171, v[104:107] offset:49152
	s_waitcnt lgkmcnt(7)
	v_mfma_f32_16x16x32_bf16 v[28:31], v[234:237], v[172:175], v[28:31]
	v_mfma_f32_16x16x32_bf16 v[24:27], v[234:237], v[182:185], v[24:27]
	v_mfma_f32_16x16x32_bf16 v[20:23], v[234:237], v[198:201], v[20:23]
	v_mfma_f32_16x16x32_bf16 v[16:19], v[234:237], v[206:209], v[16:19]
	s_waitcnt vmcnt(1)
	ds_write_b128 v171, v[112:115] offset:24576
	s_waitcnt lgkmcnt(7)
	v_mfma_f32_16x16x32_bf16 v[12:15], v[238:241], v[172:175], v[12:15]
	v_mfma_f32_16x16x32_bf16 v[8:11], v[238:241], v[182:185], v[8:11]
	v_mfma_f32_16x16x32_bf16 v[4:7], v[238:241], v[198:201], v[4:7]
	v_mfma_f32_16x16x32_bf16 v[0:3], v[238:241], v[206:209], v[0:3]
	s_waitcnt vmcnt(0)
	ds_write_b128 v171, v[120:123] offset:57344
	s_setprio 0
	s_cmp_gt_u32 s11, 41
	s_cbranch_scc1 .Lmy_t14_skip_6
	s_waitcnt vmcnt(1)
	v_lshl_add_u64 v[112:113], v[160:161], 0, s[0:1]
	v_add_co_u32_e32 v76, vcc, 0x12770000, v112
	v_lshl_add_u64 v[114:115], v[162:163], 0, s[0:1]
	s_nop 0
	v_addc_co_u32_e32 v77, vcc, 0, v113, vcc
	v_add_co_u32_e32 v80, vcc, 0x2638000, v114
	s_nop 1
	v_addc_co_u32_e32 v81, vcc, 0, v115, vcc
	v_add_co_u32_e32 v88, vcc, 0x127c8000, v112
	global_load_dwordx4 v[76:79], v[76:77], off offset:256
	s_nop 0
	global_load_dwordx4 v[80:83], v[80:81], off offset:256
	v_addc_co_u32_e32 v89, vcc, 0, v113, vcc
	v_add_co_u32_e32 v92, vcc, 0x2690000, v114
	s_nop 1
	v_addc_co_u32_e32 v93, vcc, 0, v115, vcc
	v_add_co_u32_e32 v100, vcc, 0x12820000, v112
	global_load_dwordx4 v[88:91], v[88:89], off offset:256
	s_nop 0
	global_load_dwordx4 v[92:95], v[92:93], off offset:256
	v_addc_co_u32_e32 v101, vcc, 0, v113, vcc
	v_add_co_u32_e32 v104, vcc, 0x26e8000, v114
	s_nop 1
	v_addc_co_u32_e32 v105, vcc, 0, v115, vcc
	v_add_co_u32_e32 v112, vcc, 0x12878000, v112
	global_load_dwordx4 v[100:103], v[100:101], off offset:256
	s_nop 0
	global_load_dwordx4 v[104:107], v[104:105], off offset:256
	v_addc_co_u32_e32 v113, vcc, 0, v113, vcc
	s_waitcnt vmcnt(6)
	v_add_co_u32_e32 v120, vcc, 0x2740000, v114
	s_nop 1
	v_addc_co_u32_e32 v121, vcc, 0, v115, vcc
	global_load_dwordx4 v[112:115], v[112:113], off offset:256
	s_nop 0
	global_load_dwordx4 v[120:123], v[120:121], off offset:256
